# baseline (speedup 1.0000x reference)
.LBB0_110:
	ds_read_b128 v[140:143], v138
	ds_read_b128 v[144:147], v138 offset:1024
	ds_read_b128 v[148:151], v138 offset:2048
	ds_read_b128 v[152:155], v138 offset:3072
	ds_read_b128 v[156:159], v192
	ds_read_b128 v[160:163], v192 offset:1024
	ds_read_b128 v[194:197], v191
	ds_read_b128 v[198:201], v191 offset:1024
	ds_read_b128 v[202:205], v190
	ds_read_b128 v[206:209], v190 offset:1024
	ds_read_b128 v[210:213], v189
	ds_read_b128 v[214:217], v189 offset:1024
	s_waitcnt lgkmcnt(8)
	s_waitcnt vmcnt(10)
	s_barrier
	s_waitcnt lgkmcnt(0)
	s_waitcnt lgkmcnt(0)
	v_mfma_f32_16x16x32_bf16 v[124:127], v[140:143], v[156:159], v[124:127]
	v_mfma_f32_16x16x32_bf16 v[120:123], v[148:151], v[156:159], v[120:123]
	v_mfma_f32_16x16x32_bf16 v[116:119], v[140:143], v[194:197], v[116:119]
	v_mfma_f32_16x16x32_bf16 v[112:115], v[148:151], v[194:197], v[112:115]
	v_mfma_f32_16x16x32_bf16 v[108:111], v[140:143], v[202:205], v[108:111]
	v_mfma_f32_16x16x32_bf16 v[104:107], v[148:151], v[202:205], v[104:107]
	v_mfma_f32_16x16x32_bf16 v[100:103], v[140:143], v[210:213], v[100:103]
	v_mfma_f32_16x16x32_bf16 v[96:99], v[148:151], v[210:213], v[96:99]
	v_mfma_f32_16x16x32_bf16 v[124:127], v[144:147], v[160:163], v[124:127]
	v_mfma_f32_16x16x32_bf16 v[120:123], v[152:155], v[160:163], v[120:123]
	v_mfma_f32_16x16x32_bf16 v[116:119], v[144:147], v[198:201], v[116:119]
	v_mfma_f32_16x16x32_bf16 v[112:115], v[152:155], v[198:201], v[112:115]
	v_mfma_f32_16x16x32_bf16 v[108:111], v[144:147], v[206:209], v[108:111]
	v_mfma_f32_16x16x32_bf16 v[104:107], v[152:155], v[206:209], v[104:107]
	v_mfma_f32_16x16x32_bf16 v[100:103], v[144:147], v[214:217], v[100:103]
	v_mfma_f32_16x16x32_bf16 v[96:99], v[152:155], v[214:217], v[96:99]
	s_barrier
	s_add_i32 s63, s98, 0x10000
	v_lshl_add_u64 v[234:235], s[66:67], 0, v[164:165]
	s_mov_b32 m0, s63
	s_add_i32 s63, s98, 0x12000
	ds_read_b128 v[218:221], v135
	ds_read_b128 v[222:225], v135 offset:1024
	ds_read_b128 v[226:229], v135 offset:2048
	ds_read_b128 v[230:233], v135 offset:3072
	global_load_lds_dwordx4 v[234:235], off
	v_lshl_add_u64 v[236:237], v[234:235], 0, s[10:11]
	s_mov_b32 m0, s63
	s_nop 0
	global_load_lds_dwordx4 v[236:237], off
	s_mov_b32 s63, s98
	v_lshl_add_u64 v[236:237], v[128:129], 0, s[26:27]
	s_mov_b32 m0, s63
	s_add_i32 s63, s98, 0x2000
	global_load_lds_dwordx4 v[236:237], off
	v_lshl_add_u64 v[236:237], v[128:129], 0, s[28:29]
	s_mov_b32 m0, s63
	s_nop 0
	global_load_lds_dwordx4 v[236:237], off
	s_waitcnt vmcnt(12)
	s_barrier
	s_waitcnt lgkmcnt(0)
	s_waitcnt lgkmcnt(0)
	v_mfma_f32_16x16x32_bf16 v[92:95], v[218:221], v[156:159], v[92:95]
	v_mfma_f32_16x16x32_bf16 v[88:91], v[226:229], v[156:159], v[88:91]
	v_mfma_f32_16x16x32_bf16 v[84:87], v[218:221], v[194:197], v[84:87]
	v_mfma_f32_16x16x32_bf16 v[80:83], v[226:229], v[194:197], v[80:83]
	v_mfma_f32_16x16x32_bf16 v[76:79], v[218:221], v[202:205], v[76:79]
	v_mfma_f32_16x16x32_bf16 v[72:75], v[226:229], v[202:205], v[72:75]
	v_mfma_f32_16x16x32_bf16 v[68:71], v[218:221], v[210:213], v[68:71]
	v_mfma_f32_16x16x32_bf16 v[64:67], v[226:229], v[210:213], v[64:67]
	v_mfma_f32_16x16x32_bf16 v[92:95], v[222:225], v[160:163], v[92:95]
	v_mfma_f32_16x16x32_bf16 v[88:91], v[230:233], v[160:163], v[88:91]
	v_mfma_f32_16x16x32_bf16 v[84:87], v[222:225], v[198:201], v[84:87]
	v_mfma_f32_16x16x32_bf16 v[80:83], v[230:233], v[198:201], v[80:83]
	v_mfma_f32_16x16x32_bf16 v[76:79], v[222:225], v[206:209], v[76:79]
	v_mfma_f32_16x16x32_bf16 v[72:75], v[230:233], v[206:209], v[72:75]
	v_mfma_f32_16x16x32_bf16 v[68:71], v[222:225], v[214:217], v[68:71]
	v_mfma_f32_16x16x32_bf16 v[64:67], v[230:233], v[214:217], v[64:67]
	s_barrier
	ds_read_b128 v[156:159], v192 offset:16384
	ds_read_b128 v[160:163], v192 offset:17408
	ds_read_b128 v[194:197], v191 offset:16384
	ds_read_b128 v[198:201], v191 offset:17408
	ds_read_b128 v[202:205], v190 offset:16384
	ds_read_b128 v[206:209], v190 offset:17408
	ds_read_b128 v[210:213], v189 offset:16384
	ds_read_b128 v[214:217], v189 offset:17408
	s_add_i32 s63, s98, 0x14000
	v_lshl_add_u64 v[236:237], v[234:235], 0, s[30:31]
	s_mov_b32 m0, s63
	s_add_i32 s63, s98, 0x16000
	global_load_lds_dwordx4 v[236:237], off
	v_lshl_add_u64 v[236:237], v[234:235], 0, s[34:35]
	s_mov_b32 m0, s63
	s_nop 0
	global_load_lds_dwordx4 v[236:237], off
	s_barrier
	s_waitcnt lgkmcnt(0)
	s_waitcnt lgkmcnt(0)
	v_mfma_f32_16x16x32_bf16 v[60:63], v[140:143], v[156:159], v[60:63]
	v_mfma_f32_16x16x32_bf16 v[56:59], v[148:151], v[156:159], v[56:59]
	v_mfma_f32_16x16x32_bf16 v[52:55], v[140:143], v[194:197], v[52:55]
	v_mfma_f32_16x16x32_bf16 v[48:51], v[148:151], v[194:197], v[48:51]
	v_mfma_f32_16x16x32_bf16 v[44:47], v[140:143], v[202:205], v[44:47]
	v_mfma_f32_16x16x32_bf16 v[40:43], v[148:151], v[202:205], v[40:43]
	v_mfma_f32_16x16x32_bf16 v[36:39], v[140:143], v[210:213], v[36:39]
	v_mfma_f32_16x16x32_bf16 v[32:35], v[148:151], v[210:213], v[32:35]
	v_mfma_f32_16x16x32_bf16 v[60:63], v[144:147], v[160:163], v[60:63]
	v_mfma_f32_16x16x32_bf16 v[56:59], v[152:155], v[160:163], v[56:59]
	v_mfma_f32_16x16x32_bf16 v[52:55], v[144:147], v[198:201], v[52:55]
	v_mfma_f32_16x16x32_bf16 v[48:51], v[152:155], v[198:201], v[48:51]
	v_mfma_f32_16x16x32_bf16 v[44:47], v[144:147], v[206:209], v[44:47]
	v_mfma_f32_16x16x32_bf16 v[40:43], v[152:155], v[206:209], v[40:43]
	v_mfma_f32_16x16x32_bf16 v[36:39], v[144:147], v[214:217], v[36:39]
	v_mfma_f32_16x16x32_bf16 v[32:35], v[152:155], v[214:217], v[32:35]
	s_barrier
	s_add_i32 s63, s98, 0x4000
	v_lshl_add_u64 v[142:143], v[128:129], 0, s[40:41]
	s_mov_b32 m0, s63
	s_add_i32 s63, s98, 0x6000
	global_load_lds_dwordx4 v[142:143], off
	s_mov_b32 m0, s63
	s_nop 0
	global_load_lds_dwordx4 v[128:129], off
	s_waitcnt vmcnt(12)
	s_barrier
	v_mfma_f32_16x16x32_bf16 v[28:31], v[218:221], v[156:159], v[28:31]
	v_mfma_f32_16x16x32_bf16 v[24:27], v[226:229], v[156:159], v[24:27]
	v_mfma_f32_16x16x32_bf16 v[20:23], v[218:221], v[194:197], v[20:23]
	v_mfma_f32_16x16x32_bf16 v[16:19], v[226:229], v[194:197], v[16:19]
	v_mfma_f32_16x16x32_bf16 v[12:15], v[218:221], v[202:205], v[12:15]
	v_mfma_f32_16x16x32_bf16 v[8:11], v[226:229], v[202:205], v[8:11]
	v_mfma_f32_16x16x32_bf16 v[4:7], v[218:221], v[210:213], v[4:7]
	v_mfma_f32_16x16x32_bf16 v[0:3], v[226:229], v[210:213], v[0:3]
	v_mfma_f32_16x16x32_bf16 v[28:31], v[222:225], v[160:163], v[28:31]
	v_mfma_f32_16x16x32_bf16 v[24:27], v[230:233], v[160:163], v[24:27]
	v_mfma_f32_16x16x32_bf16 v[20:23], v[222:225], v[198:201], v[20:23]
	v_mfma_f32_16x16x32_bf16 v[16:19], v[230:233], v[198:201], v[16:19]
	v_mfma_f32_16x16x32_bf16 v[12:15], v[222:225], v[206:209], v[12:15]
	v_mfma_f32_16x16x32_bf16 v[8:11], v[230:233], v[206:209], v[8:11]
	v_mfma_f32_16x16x32_bf16 v[4:7], v[222:225], v[214:217], v[4:7]
	v_mfma_f32_16x16x32_bf16 v[0:3], v[230:233], v[214:217], v[0:3]
	s_barrier
	ds_read_b128 v[140:143], v130
	ds_read_b128 v[144:147], v130 offset:1024
	ds_read_b128 v[148:151], v130 offset:2048
	ds_read_b128 v[152:155], v130 offset:3072
	ds_read_b128 v[156:159], v192 offset:32768
	ds_read_b128 v[160:163], v192 offset:33792
	ds_read_b128 v[194:197], v191 offset:32768
	ds_read_b128 v[198:201], v191 offset:33792
	ds_read_b128 v[202:205], v190 offset:32768
	ds_read_b128 v[206:209], v190 offset:33792
	ds_read_b128 v[210:213], v189 offset:32768
	ds_read_b128 v[214:217], v189 offset:33792
	s_waitcnt lgkmcnt(8)
	s_waitcnt vmcnt(10)
	s_barrier
	s_waitcnt lgkmcnt(0)
	s_waitcnt lgkmcnt(0)
	v_mfma_f32_16x16x32_bf16 v[124:127], v[140:143], v[156:159], v[124:127]
	v_mfma_f32_16x16x32_bf16 v[120:123], v[148:151], v[156:159], v[120:123]
	v_mfma_f32_16x16x32_bf16 v[116:119], v[140:143], v[194:197], v[116:119]
	v_mfma_f32_16x16x32_bf16 v[112:115], v[148:151], v[194:197], v[112:115]
	v_mfma_f32_16x16x32_bf16 v[108:111], v[140:143], v[202:205], v[108:111]
	v_mfma_f32_16x16x32_bf16 v[104:107], v[148:151], v[202:205], v[104:107]
	v_mfma_f32_16x16x32_bf16 v[100:103], v[140:143], v[210:213], v[100:103]
	v_mfma_f32_16x16x32_bf16 v[96:99], v[148:151], v[210:213], v[96:99]
	v_mfma_f32_16x16x32_bf16 v[124:127], v[144:147], v[160:163], v[124:127]
	v_mfma_f32_16x16x32_bf16 v[120:123], v[152:155], v[160:163], v[120:123]
	v_mfma_f32_16x16x32_bf16 v[116:119], v[144:147], v[198:201], v[116:119]
	v_mfma_f32_16x16x32_bf16 v[112:115], v[152:155], v[198:201], v[112:115]
	v_mfma_f32_16x16x32_bf16 v[108:111], v[144:147], v[206:209], v[108:111]
	v_mfma_f32_16x16x32_bf16 v[104:107], v[152:155], v[206:209], v[104:107]
	v_mfma_f32_16x16x32_bf16 v[100:103], v[144:147], v[214:217], v[100:103]
	v_mfma_f32_16x16x32_bf16 v[96:99], v[152:155], v[214:217], v[96:99]
	s_barrier
	s_add_i32 s63, s98, 0x18000
	v_lshl_add_u64 v[234:235], s[64:65], 0, v[164:165]
	s_mov_b32 m0, s63
	s_add_i32 s63, s98, 0x1a000
	ds_read_b128 v[218:221], v132
	ds_read_b128 v[222:225], v132 offset:1024
	ds_read_b128 v[226:229], v132 offset:2048
	ds_read_b128 v[230:233], v132 offset:3072
	global_load_lds_dwordx4 v[234:235], off
	v_lshl_add_u64 v[236:237], v[234:235], 0, s[10:11]
	s_mov_b32 m0, s63
	s_nop 0
	global_load_lds_dwordx4 v[236:237], off
	s_add_i32 s63, s98, 0x8000
	v_lshl_add_u64 v[236:237], v[128:129], 0, s[44:45]
	s_mov_b32 m0, s63
	s_add_i32 s63, s98, 0xa000
	global_load_lds_dwordx4 v[236:237], off
	v_lshl_add_u64 v[236:237], v[128:129], 0, s[46:47]
	s_mov_b32 m0, s63
	s_nop 0
	global_load_lds_dwordx4 v[236:237], off
	s_waitcnt vmcnt(12)
	s_barrier
	s_waitcnt lgkmcnt(0)
	s_waitcnt lgkmcnt(0)
	v_mfma_f32_16x16x32_bf16 v[92:95], v[218:221], v[156:159], v[92:95]
	v_mfma_f32_16x16x32_bf16 v[88:91], v[226:229], v[156:159], v[88:91]
	v_mfma_f32_16x16x32_bf16 v[84:87], v[218:221], v[194:197], v[84:87]
	v_mfma_f32_16x16x32_bf16 v[80:83], v[226:229], v[194:197], v[80:83]
	v_mfma_f32_16x16x32_bf16 v[76:79], v[218:221], v[202:205], v[76:79]
	v_mfma_f32_16x16x32_bf16 v[72:75], v[226:229], v[202:205], v[72:75]
	v_mfma_f32_16x16x32_bf16 v[68:71], v[218:221], v[210:213], v[68:71]
	v_mfma_f32_16x16x32_bf16 v[64:67], v[226:229], v[210:213], v[64:67]
	v_mfma_f32_16x16x32_bf16 v[92:95], v[222:225], v[160:163], v[92:95]
	v_mfma_f32_16x16x32_bf16 v[88:91], v[230:233], v[160:163], v[88:91]
	v_mfma_f32_16x16x32_bf16 v[84:87], v[222:225], v[198:201], v[84:87]
	v_mfma_f32_16x16x32_bf16 v[80:83], v[230:233], v[198:201], v[80:83]
	v_mfma_f32_16x16x32_bf16 v[76:79], v[222:225], v[206:209], v[76:79]
	v_mfma_f32_16x16x32_bf16 v[72:75], v[230:233], v[206:209], v[72:75]
	v_mfma_f32_16x16x32_bf16 v[68:71], v[222:225], v[214:217], v[68:71]
	v_mfma_f32_16x16x32_bf16 v[64:67], v[230:233], v[214:217], v[64:67]
	s_barrier
	ds_read_b128 v[156:159], v192 offset:49152
	ds_read_b128 v[160:163], v192 offset:50176
	ds_read_b128 v[194:197], v191 offset:49152
	ds_read_b128 v[198:201], v191 offset:50176
	ds_read_b128 v[202:205], v190 offset:49152
	ds_read_b128 v[206:209], v190 offset:50176
	ds_read_b128 v[210:213], v189 offset:49152
	ds_read_b128 v[214:217], v189 offset:50176
	s_add_i32 s63, s98, 0x1c000
	v_lshl_add_u64 v[236:237], v[234:235], 0, s[30:31]
	s_mov_b32 m0, s63
	s_add_i32 s63, s98, 0x1e000
	global_load_lds_dwordx4 v[236:237], off
	v_lshl_add_u64 v[236:237], v[234:235], 0, s[34:35]
	s_mov_b32 m0, s63
	s_nop 0
	global_load_lds_dwordx4 v[236:237], off
	s_barrier
	s_waitcnt lgkmcnt(0)
	s_waitcnt lgkmcnt(0)
	v_mfma_f32_16x16x32_bf16 v[60:63], v[140:143], v[156:159], v[60:63]
	v_mfma_f32_16x16x32_bf16 v[56:59], v[148:151], v[156:159], v[56:59]
	v_mfma_f32_16x16x32_bf16 v[52:55], v[140:143], v[194:197], v[52:55]
	v_mfma_f32_16x16x32_bf16 v[48:51], v[148:151], v[194:197], v[48:51]
	v_mfma_f32_16x16x32_bf16 v[44:47], v[140:143], v[202:205], v[44:47]
	v_mfma_f32_16x16x32_bf16 v[40:43], v[148:151], v[202:205], v[40:43]
	v_mfma_f32_16x16x32_bf16 v[36:39], v[140:143], v[210:213], v[36:39]
	v_mfma_f32_16x16x32_bf16 v[32:35], v[148:151], v[210:213], v[32:35]
	v_mfma_f32_16x16x32_bf16 v[60:63], v[144:147], v[160:163], v[60:63]
	v_mfma_f32_16x16x32_bf16 v[56:59], v[152:155], v[160:163], v[56:59]
	v_mfma_f32_16x16x32_bf16 v[52:55], v[144:147], v[198:201], v[52:55]
	v_mfma_f32_16x16x32_bf16 v[48:51], v[152:155], v[198:201], v[48:51]
	v_mfma_f32_16x16x32_bf16 v[44:47], v[144:147], v[206:209], v[44:47]
	v_mfma_f32_16x16x32_bf16 v[40:43], v[152:155], v[206:209], v[40:43]
	v_mfma_f32_16x16x32_bf16 v[36:39], v[144:147], v[214:217], v[36:39]
	v_mfma_f32_16x16x32_bf16 v[32:35], v[152:155], v[214:217], v[32:35]
	s_barrier
	v_lshl_add_u64 v[128:129], v[128:129], 0, s[56:57]
	s_add_i32 s63, s98, 0xc000
	v_lshl_add_u64 v[142:143], v[128:129], 0, s[22:23]
	s_mov_b32 m0, s63
	s_add_i32 s63, s98, 0xe000
	global_load_lds_dwordx4 v[142:143], off
	v_lshl_add_u64 v[142:143], v[128:129], 0, s[24:25]
	s_mov_b32 m0, s63
	s_nop 0
	global_load_lds_dwordx4 v[142:143], off
	s_waitcnt vmcnt(12)
	s_barrier
	v_mfma_f32_16x16x32_bf16 v[28:31], v[218:221], v[156:159], v[28:31]
	v_mfma_f32_16x16x32_bf16 v[24:27], v[226:229], v[156:159], v[24:27]
	v_mfma_f32_16x16x32_bf16 v[20:23], v[218:221], v[194:197], v[20:23]
	v_mfma_f32_16x16x32_bf16 v[16:19], v[226:229], v[194:197], v[16:19]
	v_mfma_f32_16x16x32_bf16 v[12:15], v[218:221], v[202:205], v[12:15]
	v_mfma_f32_16x16x32_bf16 v[8:11], v[226:229], v[202:205], v[8:11]
	v_mfma_f32_16x16x32_bf16 v[4:7], v[218:221], v[210:213], v[4:7]
	v_mfma_f32_16x16x32_bf16 v[0:3], v[226:229], v[210:213], v[0:3]
	v_mfma_f32_16x16x32_bf16 v[28:31], v[222:225], v[160:163], v[28:31]
	v_mfma_f32_16x16x32_bf16 v[24:27], v[230:233], v[160:163], v[24:27]
	v_mfma_f32_16x16x32_bf16 v[20:23], v[222:225], v[198:201], v[20:23]
	v_mfma_f32_16x16x32_bf16 v[16:19], v[230:233], v[198:201], v[16:19]
	v_mfma_f32_16x16x32_bf16 v[12:15], v[222:225], v[206:209], v[12:15]
	v_mfma_f32_16x16x32_bf16 v[8:11], v[230:233], v[206:209], v[8:11]
	v_mfma_f32_16x16x32_bf16 v[4:7], v[222:225], v[214:217], v[4:7]
	v_mfma_f32_16x16x32_bf16 v[0:3], v[230:233], v[214:217], v[0:3]
	s_add_i32 s4, s4, 2
	s_add_u32 s64, s64, s68
	s_addc_u32 s65, s65, s69
	s_add_u32 s66, s66, s68
	s_addc_u32 s67, s67, s69
	s_cmp_lt_u32 s4, 28
	s_barrier
	s_cbranch_scc1 .LBB0_110
	s_lshl_b32 s4, s70, 11
	s_or_b32 s64, s71, s4
	s_or_b32 s66, s64, 0x80
	v_lshlrev_b32_e32 v128, 3, v131
	v_lshlrev_b32_e32 v129, 5, v131
	s_ashr_i32 s67, s66, 31
	v_and_b32_e32 v128, 0xffff0, v128
	v_and_b32_e32 v129, 32, v129
	s_lshl_b64 s[66:67], s[66:67], 12
	v_add_u32_e32 v129, v129, v134
	v_add_lshl_u32 v128, v133, v128, 12
	s_add_u32 s66, s54, s66
	v_lshl_add_u32 v164, v129, 1, v128
	s_addc_u32 s67, s55, s67
	v_lshl_add_u64 v[128:129], s[66:67], 0, v[164:165]
	v_readfirstlane_b32 s4, v137
	ds_read_b128 v[140:143], v138
	ds_read_b128 v[144:147], v138 offset:1024
	ds_read_b128 v[148:151], v138 offset:2048
	ds_read_b128 v[152:155], v138 offset:3072
	ds_read_b128 v[156:159], v192
	ds_read_b128 v[160:163], v192 offset:1024
	ds_read_b128 v[194:197], v191
	ds_read_b128 v[198:201], v191 offset:1024
	ds_read_b128 v[202:205], v190
	ds_read_b128 v[206:209], v190 offset:1024
	ds_read_b128 v[210:213], v189
	ds_read_b128 v[214:217], v189 offset:1024
	v_lshl_add_u64 v[138:139], v[128:129], 0, s[58:59]
	s_mov_b32 m0, s4
	v_readfirstlane_b32 s4, v136
	v_lshl_add_u64 v[128:129], v[128:129], 0, s[60:61]
	s_mov_b32 m0, s4
	s_ashr_i32 s65, s64, 31
	s_waitcnt vmcnt(8)
	s_barrier
	s_waitcnt lgkmcnt(0)
	s_setprio 1
	s_waitcnt lgkmcnt(0)
	v_mfma_f32_16x16x32_bf16 v[124:127], v[140:143], v[156:159], v[124:127]
	v_mfma_f32_16x16x32_bf16 v[120:123], v[148:151], v[156:159], v[120:123]
	v_mfma_f32_16x16x32_bf16 v[116:119], v[140:143], v[194:197], v[116:119]
	v_mfma_f32_16x16x32_bf16 v[112:115], v[148:151], v[194:197], v[112:115]
	v_mfma_f32_16x16x32_bf16 v[108:111], v[140:143], v[202:205], v[108:111]
	v_mfma_f32_16x16x32_bf16 v[104:107], v[148:151], v[202:205], v[104:107]
	v_mfma_f32_16x16x32_bf16 v[100:103], v[140:143], v[210:213], v[100:103]
	v_mfma_f32_16x16x32_bf16 v[96:99], v[148:151], v[210:213], v[96:99]
	v_mfma_f32_16x16x32_bf16 v[124:127], v[144:147], v[160:163], v[124:127]
	v_mfma_f32_16x16x32_bf16 v[120:123], v[152:155], v[160:163], v[120:123]
	v_mfma_f32_16x16x32_bf16 v[116:119], v[144:147], v[198:201], v[116:119]
	v_mfma_f32_16x16x32_bf16 v[112:115], v[152:155], v[198:201], v[112:115]
	v_mfma_f32_16x16x32_bf16 v[108:111], v[144:147], v[206:209], v[108:111]
	v_mfma_f32_16x16x32_bf16 v[104:107], v[152:155], v[206:209], v[104:107]
	v_mfma_f32_16x16x32_bf16 v[100:103], v[144:147], v[214:217], v[100:103]
	v_mfma_f32_16x16x32_bf16 v[96:99], v[152:155], v[214:217], v[96:99]
	s_setprio 0
	s_barrier
	ds_read_b128 v[136:139], v135
	ds_read_b128 v[218:221], v135 offset:1024
	ds_read_b128 v[222:225], v135 offset:2048
	ds_read_b128 v[226:229], v135 offset:3072
	s_barrier
	s_waitcnt lgkmcnt(0)
	s_setprio 1
	s_waitcnt lgkmcnt(0)
	v_mfma_f32_16x16x32_bf16 v[92:95], v[136:139], v[156:159], v[92:95]
	v_mfma_f32_16x16x32_bf16 v[88:91], v[222:225], v[156:159], v[88:91]
	v_mfma_f32_16x16x32_bf16 v[84:87], v[136:139], v[194:197], v[84:87]
	v_mfma_f32_16x16x32_bf16 v[80:83], v[222:225], v[194:197], v[80:83]
	v_mfma_f32_16x16x32_bf16 v[76:79], v[136:139], v[202:205], v[76:79]
	v_mfma_f32_16x16x32_bf16 v[72:75], v[222:225], v[202:205], v[72:75]
	v_mfma_f32_16x16x32_bf16 v[68:71], v[136:139], v[210:213], v[68:71]
	v_mfma_f32_16x16x32_bf16 v[64:67], v[222:225], v[210:213], v[64:67]
	v_mfma_f32_16x16x32_bf16 v[156:159], v[218:221], v[160:163], v[92:95]
	v_mfma_f32_16x16x32_bf16 v[160:163], v[226:229], v[160:163], v[88:91]
	v_mfma_f32_16x16x32_bf16 v[194:197], v[218:221], v[198:201], v[84:87]
	v_mfma_f32_16x16x32_bf16 v[198:201], v[226:229], v[198:201], v[80:83]
	v_mfma_f32_16x16x32_bf16 v[202:205], v[218:221], v[206:209], v[76:79]
	v_mfma_f32_16x16x32_bf16 v[206:209], v[226:229], v[206:209], v[72:75]
	v_mfma_f32_16x16x32_bf16 v[210:213], v[218:221], v[214:217], v[68:71]
	v_mfma_f32_16x16x32_bf16 v[214:217], v[226:229], v[214:217], v[64:67]
	s_setprio 0
	s_barrier
	s_nop 0
	ds_read_b128 v[64:67], v192 offset:16384
	ds_read_b128 v[68:71], v192 offset:17408
	ds_read_b128 v[72:75], v191 offset:16384
	ds_read_b128 v[76:79], v191 offset:17408
	ds_read_b128 v[80:83], v190 offset:16384
	ds_read_b128 v[84:87], v190 offset:17408
	ds_read_b128 v[88:91], v189 offset:16384
	ds_read_b128 v[92:95], v189 offset:17408
	s_waitcnt vmcnt(4)
	s_barrier
	s_waitcnt lgkmcnt(0)
	s_setprio 1
	s_waitcnt lgkmcnt(0)
	v_mfma_f32_16x16x32_bf16 v[60:63], v[140:143], v[64:67], v[60:63]
	v_mfma_f32_16x16x32_bf16 v[56:59], v[148:151], v[64:67], v[56:59]
	v_mfma_f32_16x16x32_bf16 v[52:55], v[140:143], v[72:75], v[52:55]
	v_mfma_f32_16x16x32_bf16 v[48:51], v[148:151], v[72:75], v[48:51]
	v_mfma_f32_16x16x32_bf16 v[230:233], v[140:143], v[80:83], v[44:47]
	v_mfma_f32_16x16x32_bf16 v[234:237], v[148:151], v[80:83], v[40:43]
	v_mfma_f32_16x16x32_bf16 v[140:143], v[140:143], v[88:91], v[36:39]
	v_mfma_f32_16x16x32_bf16 v[148:151], v[148:151], v[88:91], v[32:35]
	v_mfma_f32_16x16x32_bf16 v[32:35], v[144:147], v[68:71], v[60:63]
	v_mfma_f32_16x16x32_bf16 v[36:39], v[152:155], v[68:71], v[56:59]
	v_mfma_f32_16x16x32_bf16 v[40:43], v[144:147], v[76:79], v[52:55]
	v_mfma_f32_16x16x32_bf16 v[44:47], v[152:155], v[76:79], v[48:51]
	v_mfma_f32_16x16x32_bf16 v[48:51], v[144:147], v[84:87], v[230:233]
	v_mfma_f32_16x16x32_bf16 v[52:55], v[152:155], v[84:87], v[234:237]
	v_mfma_f32_16x16x32_bf16 v[56:59], v[144:147], v[92:95], v[140:143]
	v_mfma_f32_16x16x32_bf16 v[60:63], v[152:155], v[92:95], v[148:151]
	s_setprio 0
	s_setprio 1
	v_mfma_f32_16x16x32_bf16 v[28:31], v[136:139], v[64:67], v[28:31]
	v_mfma_f32_16x16x32_bf16 v[24:27], v[222:225], v[64:67], v[24:27]
	v_mfma_f32_16x16x32_bf16 v[20:23], v[136:139], v[72:75], v[20:23]
	v_mfma_f32_16x16x32_bf16 v[64:67], v[222:225], v[72:75], v[16:19]
	v_mfma_f32_16x16x32_bf16 v[12:15], v[136:139], v[80:83], v[12:15]
	v_mfma_f32_16x16x32_bf16 v[8:11], v[222:225], v[80:83], v[8:11]
	v_mfma_f32_16x16x32_bf16 v[72:75], v[136:139], v[88:91], v[4:7]
	v_mfma_f32_16x16x32_bf16 v[80:83], v[222:225], v[88:91], v[0:3]
	v_mfma_f32_16x16x32_bf16 v[0:3], v[218:221], v[68:71], v[28:31]
	v_mfma_f32_16x16x32_bf16 v[4:7], v[226:229], v[68:71], v[24:27]
	v_mfma_f32_16x16x32_bf16 v[16:19], v[218:221], v[76:79], v[20:23]
	v_mfma_f32_16x16x32_bf16 v[20:23], v[226:229], v[76:79], v[64:67]
	v_mfma_f32_16x16x32_bf16 v[64:67], v[218:221], v[84:87], v[12:15]
	v_mfma_f32_16x16x32_bf16 v[68:71], v[226:229], v[84:87], v[8:11]
	v_mfma_f32_16x16x32_bf16 v[72:75], v[218:221], v[92:95], v[72:75]
	v_mfma_f32_16x16x32_bf16 v[76:79], v[226:229], v[92:95], v[80:83]
	s_setprio 0
	s_barrier
	ds_read_b128 v[12:15], v130
	ds_read_b128 v[8:11], v130 offset:1024
	ds_read_b128 v[24:27], v130 offset:2048
	ds_read_b128 v[80:83], v130 offset:3072
	ds_read_b128 v[140:143], v192 offset:32768
	ds_read_b128 v[148:151], v192 offset:33792
	ds_read_b128 v[218:221], v191 offset:32768
	ds_read_b128 v[222:225], v191 offset:33792
	ds_read_b128 v[226:229], v190 offset:32768
	ds_read_b128 v[230:233], v190 offset:33792
	ds_read_b128 v[234:237], v189 offset:32768
	ds_read_b128 v[238:241], v189 offset:33792
	s_waitcnt vmcnt(2)
	s_barrier
	s_waitcnt lgkmcnt(0)
	s_setprio 1
	s_waitcnt lgkmcnt(0)
	v_mfma_f32_16x16x32_bf16 v[28:31], v[12:15], v[140:143], v[124:127]
	v_mfma_f32_16x16x32_bf16 v[84:87], v[24:27], v[140:143], v[120:123]
	v_mfma_f32_16x16x32_bf16 v[88:91], v[12:15], v[218:221], v[116:119]
	v_mfma_f32_16x16x32_bf16 v[92:95], v[24:27], v[218:221], v[112:115]
	v_mfma_f32_16x16x32_bf16 v[108:111], v[12:15], v[226:229], v[108:111]
	v_mfma_f32_16x16x32_bf16 v[104:107], v[24:27], v[226:229], v[104:107]
	v_mfma_f32_16x16x32_bf16 v[100:103], v[12:15], v[234:237], v[100:103]
	v_mfma_f32_16x16x32_bf16 v[96:99], v[24:27], v[234:237], v[96:99]
	v_mfma_f32_16x16x32_bf16 v[152:155], v[8:11], v[148:151], v[28:31]
	v_mfma_f32_16x16x32_bf16 v[144:147], v[80:83], v[148:151], v[84:87]
	v_mfma_f32_16x16x32_bf16 v[136:139], v[8:11], v[222:225], v[88:91]
	v_mfma_f32_16x16x32_bf16 v[128:131], v[80:83], v[222:225], v[92:95]
	v_mfma_f32_16x16x32_bf16 v[120:123], v[8:11], v[230:233], v[108:111]
	v_mfma_f32_16x16x32_bf16 v[112:115], v[80:83], v[230:233], v[104:107]
	v_mfma_f32_16x16x32_bf16 v[104:107], v[8:11], v[238:241], v[100:103]
	v_mfma_f32_16x16x32_bf16 v[28:31], v[80:83], v[238:241], v[96:99]
	s_setprio 0
	s_barrier
	ds_read_b128 v[92:95], v132
	ds_read_b128 v[84:87], v132 offset:1024
	ds_read_b128 v[96:99], v132 offset:2048
	ds_read_b128 v[88:91], v132 offset:3072
	s_waitcnt vmcnt(0)
	s_barrier
	s_waitcnt lgkmcnt(0)
	s_setprio 1
	s_waitcnt lgkmcnt(0)
	v_mfma_f32_16x16x32_bf16 v[100:103], v[92:95], v[140:143], v[156:159]
	v_mfma_f32_16x16x32_bf16 v[108:111], v[96:99], v[140:143], v[160:163]
	v_mfma_f32_16x16x32_bf16 v[116:119], v[92:95], v[218:221], v[194:197]
	v_mfma_f32_16x16x32_bf16 v[124:127], v[96:99], v[218:221], v[198:201]
	v_mfma_f32_16x16x32_bf16 v[160:163], v[92:95], v[226:229], v[202:205]
	v_mfma_f32_16x16x32_bf16 v[194:197], v[96:99], v[226:229], v[206:209]
	v_mfma_f32_16x16x32_bf16 v[198:201], v[92:95], v[234:237], v[210:213]
	v_mfma_f32_16x16x32_bf16 v[202:205], v[96:99], v[234:237], v[214:217]
	v_mfma_f32_16x16x32_bf16 v[156:159], v[84:87], v[148:151], v[100:103]
	v_mfma_f32_16x16x32_bf16 v[148:151], v[88:91], v[148:151], v[108:111]
	v_mfma_f32_16x16x32_bf16 v[140:143], v[84:87], v[222:225], v[116:119]
	v_mfma_f32_16x16x32_bf16 v[132:135], v[88:91], v[222:225], v[124:127]
	v_mfma_f32_16x16x32_bf16 v[124:127], v[84:87], v[230:233], v[160:163]
	v_mfma_f32_16x16x32_bf16 v[116:119], v[88:91], v[230:233], v[194:197]
	v_mfma_f32_16x16x32_bf16 v[108:111], v[84:87], v[238:241], v[198:201]
	v_mfma_f32_16x16x32_bf16 v[100:103], v[88:91], v[238:241], v[202:205]
	s_setprio 0
	s_lshl_b64 s[66:67], s[64:65], 2
	s_barrier
	v_mbcnt_lo_u32_b32 v162, -1, 0
	v_mbcnt_hi_u32_b32 v162, -1, v162
	s_add_u32 s66, s87, s66
	v_add_u32_e32 v160, s76, v162
	s_addc_u32 s67, s88, s67
	v_and_b32_e32 v164, 0x100, v160
	v_and_b32_e32 v162, 15, v162
	v_lshl_add_u64 v[160:161], s[66:67], 0, v[164:165]
	v_lshlrev_b32_e32 v164, 2, v162
	v_lshl_add_u64 v[160:161], v[160:161], 0, v[164:165]
	global_load_dword v178, v[160:161], off
	global_load_dword v176, v[160:161], off offset:64
	global_load_dword v174, v[160:161], off offset:128
	global_load_dword v164, v[160:161], off offset:192
	global_load_dword v172, v[160:161], off offset:512
	global_load_dword v170, v[160:161], off offset:576
	global_load_dword v168, v[160:161], off offset:640
	global_load_dword v166, v[160:161], off offset:704
	v_mbcnt_lo_u32_b32 v194, -1, 0
	v_mbcnt_hi_u32_b32 v194, -1, v194
	s_mov_b64 s[66:67], -1
	v_add_u32_e32 v160, s76, v194
	v_bfe_u32 v161, v160, 8, 1
	v_ashrrev_i32_e32 v196, 6, v160
	v_bfe_u32 v160, v194, 4, 2
	v_and_b32_e32 v198, 3, v196
	v_and_b32_e32 v195, 15, v194
	s_cmp_gt_i32 s74, 1
	v_lshlrev_b32_e32 v193, 6, v161
	v_lshlrev_b32_e32 v197, 4, v160
	s_cbranch_scc0 .LBB0_113
	v_lshlrev_b32_e32 v161, 6, v198
	v_or3_b32 v160, v193, v195, s64
	v_or3_b32 v161, v161, v197, s62
	v_lshl_add_u32 v199, v160, 12, v161
	s_waitcnt vmcnt(0)
	v_mul_f32_e32 v160, v178, v178
	v_pk_mul_f32 v[200:201], v[152:153], v[160:161] op_sel_hi:[1,0]
	v_pk_mul_f32 v[162:163], v[154:155], v[160:161] op_sel_hi:[1,0]
	v_pk_mul_f32 v[202:203], v[158:159], v[160:161] op_sel_hi:[1,0]
	v_pk_mul_f32 v[204:205], v[156:157], v[160:161] op_sel_hi:[1,0]
	v_mul_f32_e32 v160, v144, v200
	v_mul_f32_e32 v161, v145, v201
	v_cvt_pk_bf16_f32 v160, v160, v161
	v_mul_f32_e32 v161, v146, v162
	v_mul_f32_e32 v162, v147, v163
	v_cvt_pk_bf16_f32 v161, v161, v162
	v_mul_f32_e32 v162, v148, v204
	v_mul_f32_e32 v163, v149, v205
	v_cvt_pk_bf16_f32 v162, v162, v163
	v_mul_f32_e32 v163, v150, v202
	v_mul_f32_e32 v200, v151, v203
	v_cvt_pk_bf16_f32 v163, v163, v200
	global_store_dwordx4 v199, v[160:163], s[6:7]
	v_add_u32_e32 v206, 0x10000, v199
	s_mov_b64 s[66:67], 0
	v_mul_f32_e32 v160, v176, v176
	v_pk_mul_f32 v[200:201], v[136:137], v[160:161] op_sel_hi:[1,0]
	v_pk_mul_f32 v[162:163], v[138:139], v[160:161] op_sel_hi:[1,0]
	v_pk_mul_f32 v[202:203], v[142:143], v[160:161] op_sel_hi:[1,0]
	v_pk_mul_f32 v[204:205], v[140:141], v[160:161] op_sel_hi:[1,0]
	v_mul_f32_e32 v160, v128, v200
	v_mul_f32_e32 v161, v129, v201
	v_cvt_pk_bf16_f32 v160, v160, v161
	v_mul_f32_e32 v161, v130, v162
	v_mul_f32_e32 v162, v131, v163
	v_cvt_pk_bf16_f32 v161, v161, v162
	v_mul_f32_e32 v162, v132, v204
	v_mul_f32_e32 v163, v133, v205
	v_cvt_pk_bf16_f32 v162, v162, v163
	v_mul_f32_e32 v163, v134, v202
	v_mul_f32_e32 v200, v135, v203
	v_cvt_pk_bf16_f32 v163, v163, v200
	global_store_dwordx4 v206, v[160:163], s[6:7]
	v_add_u32_e32 v206, 0x20000, v199
	v_add_u32_e32 v199, 0x30000, v199
	v_mul_f32_e32 v160, v174, v174
	v_pk_mul_f32 v[200:201], v[120:121], v[160:161] op_sel_hi:[1,0]
	v_pk_mul_f32 v[162:163], v[122:123], v[160:161] op_sel_hi:[1,0]
	v_pk_mul_f32 v[202:203], v[126:127], v[160:161] op_sel_hi:[1,0]
	v_pk_mul_f32 v[204:205], v[124:125], v[160:161] op_sel_hi:[1,0]
	v_mul_f32_e32 v160, v112, v200
	v_mul_f32_e32 v161, v113, v201
	v_cvt_pk_bf16_f32 v160, v160, v161
	v_mul_f32_e32 v161, v114, v162
	v_mul_f32_e32 v162, v115, v163
	v_cvt_pk_bf16_f32 v161, v161, v162
	v_mul_f32_e32 v162, v116, v204
	v_mul_f32_e32 v163, v117, v205
	v_cvt_pk_bf16_f32 v162, v162, v163
	v_mul_f32_e32 v163, v118, v202
	v_mul_f32_e32 v200, v119, v203
	v_cvt_pk_bf16_f32 v163, v163, v200
	global_store_dwordx4 v206, v[160:163], s[6:7]
	s_nop 1
	v_mul_f32_e32 v160, v164, v164
	v_pk_mul_f32 v[200:201], v[104:105], v[160:161] op_sel_hi:[1,0]
	v_pk_mul_f32 v[162:163], v[106:107], v[160:161] op_sel_hi:[1,0]
	v_pk_mul_f32 v[202:203], v[110:111], v[160:161] op_sel_hi:[1,0]
	v_pk_mul_f32 v[204:205], v[108:109], v[160:161] op_sel_hi:[1,0]
	v_mul_f32_e32 v160, v28, v200
	v_mul_f32_e32 v161, v29, v201
	v_cvt_pk_bf16_f32 v160, v160, v161
	v_mul_f32_e32 v161, v30, v162
	v_mul_f32_e32 v162, v31, v163
	v_cvt_pk_bf16_f32 v161, v161, v162
	v_mul_f32_e32 v162, v100, v204
	v_mul_f32_e32 v163, v101, v205
	v_cvt_pk_bf16_f32 v162, v162, v163
	v_mul_f32_e32 v163, v102, v202
	v_mul_f32_e32 v200, v103, v203
	v_cvt_pk_bf16_f32 v163, v163, v200

.LBB0_178:
	ds_read_b128 v[164:167], v162
	ds_read_b128 v[168:171], v162 offset:1024
	ds_read_b128 v[172:175], v162 offset:2048
	ds_read_b128 v[176:179], v162 offset:3072
	ds_read_b128 v[180:183], v153
	ds_read_b128 v[184:187], v153 offset:1024
	ds_read_b128 v[188:191], v152
	ds_read_b128 v[192:195], v152 offset:1024
	ds_read_b128 v[196:199], v151
	ds_read_b128 v[200:203], v151 offset:1024
	ds_read_b128 v[204:207], v150
	ds_read_b128 v[208:211], v150 offset:1024
	s_waitcnt lgkmcnt(8)
	s_waitcnt vmcnt(10)
	s_barrier
	s_waitcnt lgkmcnt(0)
	s_waitcnt lgkmcnt(0)
	v_mfma_f32_16x16x32_bf16 v[124:127], v[164:167], v[180:183], v[124:127]
	v_mfma_f32_16x16x32_bf16 v[120:123], v[172:175], v[180:183], v[120:123]
	v_mfma_f32_16x16x32_bf16 v[116:119], v[164:167], v[188:191], v[116:119]
	v_mfma_f32_16x16x32_bf16 v[112:115], v[172:175], v[188:191], v[112:115]
	v_mfma_f32_16x16x32_bf16 v[108:111], v[164:167], v[196:199], v[108:111]
	v_mfma_f32_16x16x32_bf16 v[104:107], v[172:175], v[196:199], v[104:107]
	v_mfma_f32_16x16x32_bf16 v[100:103], v[164:167], v[204:207], v[100:103]
	v_mfma_f32_16x16x32_bf16 v[96:99], v[172:175], v[204:207], v[96:99]
	v_mfma_f32_16x16x32_bf16 v[124:127], v[168:171], v[184:187], v[124:127]
	v_mfma_f32_16x16x32_bf16 v[120:123], v[176:179], v[184:187], v[120:123]
	v_mfma_f32_16x16x32_bf16 v[116:119], v[168:171], v[192:195], v[116:119]
	v_mfma_f32_16x16x32_bf16 v[112:115], v[176:179], v[192:195], v[112:115]
	v_mfma_f32_16x16x32_bf16 v[108:111], v[168:171], v[200:203], v[108:111]
	v_mfma_f32_16x16x32_bf16 v[104:107], v[176:179], v[200:203], v[104:107]
	v_mfma_f32_16x16x32_bf16 v[100:103], v[168:171], v[208:211], v[100:103]
	v_mfma_f32_16x16x32_bf16 v[96:99], v[176:179], v[208:211], v[96:99]
	s_barrier
	v_lshl_add_u64 v[230:231], s[50:51], 0, v[130:131]
	s_mov_b64 s[66:67], 0x1880000
	s_add_i32 s65, s98, 0x10000
	v_lshl_add_u64 v[232:233], v[230:231], 0, s[66:67]
	s_mov_b32 m0, s65
	s_mov_b64 s[66:67], 0x1881000
	s_add_i32 s65, s98, 0x12000
	ds_read_b128 v[212:215], v159
	ds_read_b128 v[216:219], v159 offset:1024
	ds_read_b128 v[220:223], v159 offset:2048
	ds_read_b128 v[224:227], v159 offset:3072
	global_load_lds_dwordx4 v[232:233], off
	v_lshl_add_u64 v[232:233], v[230:231], 0, s[66:67]
	s_mov_b32 m0, s65
	s_nop 0
	global_load_lds_dwordx4 v[232:233], off
	s_mov_b64 s[66:67], 0xe000100
	s_mov_b32 s65, s98
	v_lshl_add_u64 v[232:233], v[228:229], 0, s[66:67]
	s_mov_b32 m0, s65
	s_mov_b64 s[66:67], 0xe040100
	s_add_i32 s65, s98, 0x2000
	global_load_lds_dwordx4 v[232:233], off
	v_lshl_add_u64 v[232:233], v[228:229], 0, s[66:67]
	s_mov_b32 m0, s65
	s_nop 0
	global_load_lds_dwordx4 v[232:233], off
	s_waitcnt vmcnt(12)
	s_barrier
	s_waitcnt lgkmcnt(0)
	s_waitcnt lgkmcnt(0)
	v_mfma_f32_16x16x32_bf16 v[92:95], v[212:215], v[180:183], v[92:95]
	v_mfma_f32_16x16x32_bf16 v[88:91], v[220:223], v[180:183], v[88:91]
	v_mfma_f32_16x16x32_bf16 v[84:87], v[212:215], v[188:191], v[84:87]
	v_mfma_f32_16x16x32_bf16 v[80:83], v[220:223], v[188:191], v[80:83]
	v_mfma_f32_16x16x32_bf16 v[76:79], v[212:215], v[196:199], v[76:79]
	v_mfma_f32_16x16x32_bf16 v[72:75], v[220:223], v[196:199], v[72:75]
	v_mfma_f32_16x16x32_bf16 v[68:71], v[212:215], v[204:207], v[68:71]
	v_mfma_f32_16x16x32_bf16 v[64:67], v[220:223], v[204:207], v[64:67]
	v_mfma_f32_16x16x32_bf16 v[92:95], v[216:219], v[184:187], v[92:95]
	v_mfma_f32_16x16x32_bf16 v[88:91], v[224:227], v[184:187], v[88:91]
	v_mfma_f32_16x16x32_bf16 v[84:87], v[216:219], v[192:195], v[84:87]
	v_mfma_f32_16x16x32_bf16 v[80:83], v[224:227], v[192:195], v[80:83]
	v_mfma_f32_16x16x32_bf16 v[76:79], v[216:219], v[200:203], v[76:79]
	v_mfma_f32_16x16x32_bf16 v[72:75], v[224:227], v[200:203], v[72:75]
	v_mfma_f32_16x16x32_bf16 v[68:71], v[216:219], v[208:211], v[68:71]
	v_mfma_f32_16x16x32_bf16 v[64:67], v[224:227], v[208:211], v[64:67]
	s_barrier
	ds_read_b128 v[180:183], v153 offset:16384
	ds_read_b128 v[184:187], v153 offset:17408
	ds_read_b128 v[188:191], v152 offset:16384
	ds_read_b128 v[192:195], v152 offset:17408
	ds_read_b128 v[196:199], v151 offset:16384
	ds_read_b128 v[200:203], v151 offset:17408
	ds_read_b128 v[204:207], v150 offset:16384
	ds_read_b128 v[208:211], v150 offset:17408
	s_mov_b64 s[66:67], 0x1882000
	s_add_i32 s65, s98, 0x14000
	v_lshl_add_u64 v[232:233], v[230:231], 0, s[66:67]
	s_mov_b32 m0, s65
	s_mov_b64 s[66:67], 0x1883000
	s_add_i32 s65, s98, 0x16000
	global_load_lds_dwordx4 v[232:233], off
	v_lshl_add_u64 v[232:233], v[230:231], 0, s[66:67]
	s_mov_b32 m0, s65
	s_nop 0
	global_load_lds_dwordx4 v[232:233], off
	s_barrier
	s_waitcnt lgkmcnt(0)
	s_waitcnt lgkmcnt(0)
	v_mfma_f32_16x16x32_bf16 v[60:63], v[164:167], v[180:183], v[60:63]
	v_mfma_f32_16x16x32_bf16 v[56:59], v[172:175], v[180:183], v[56:59]
	v_mfma_f32_16x16x32_bf16 v[52:55], v[164:167], v[188:191], v[52:55]
	v_mfma_f32_16x16x32_bf16 v[48:51], v[172:175], v[188:191], v[48:51]
	v_mfma_f32_16x16x32_bf16 v[44:47], v[164:167], v[196:199], v[44:47]
	v_mfma_f32_16x16x32_bf16 v[40:43], v[172:175], v[196:199], v[40:43]
	v_mfma_f32_16x16x32_bf16 v[36:39], v[164:167], v[204:207], v[36:39]
	v_mfma_f32_16x16x32_bf16 v[32:35], v[172:175], v[204:207], v[32:35]
	v_mfma_f32_16x16x32_bf16 v[60:63], v[168:171], v[184:187], v[60:63]
	v_mfma_f32_16x16x32_bf16 v[56:59], v[176:179], v[184:187], v[56:59]
	v_mfma_f32_16x16x32_bf16 v[52:55], v[168:171], v[192:195], v[52:55]
	v_mfma_f32_16x16x32_bf16 v[48:51], v[176:179], v[192:195], v[48:51]
	v_mfma_f32_16x16x32_bf16 v[44:47], v[168:171], v[200:203], v[44:47]
	v_mfma_f32_16x16x32_bf16 v[40:43], v[176:179], v[200:203], v[40:43]
	v_mfma_f32_16x16x32_bf16 v[36:39], v[168:171], v[208:211], v[36:39]
	v_mfma_f32_16x16x32_bf16 v[32:35], v[176:179], v[208:211], v[32:35]
	s_barrier
	s_add_i32 s65, s98, 0x4000
	v_lshl_add_u64 v[166:167], v[228:229], 0, s[26:27]
	s_mov_b32 m0, s65
	s_add_i32 s65, s98, 0x6000
	global_load_lds_dwordx4 v[166:167], off
	v_lshl_add_u64 v[166:167], v[228:229], 0, s[28:29]
	s_mov_b32 m0, s65
	s_nop 0
	global_load_lds_dwordx4 v[166:167], off
	s_waitcnt vmcnt(12)
	s_barrier
	v_mfma_f32_16x16x32_bf16 v[28:31], v[212:215], v[180:183], v[28:31]
	v_mfma_f32_16x16x32_bf16 v[24:27], v[220:223], v[180:183], v[24:27]
	v_mfma_f32_16x16x32_bf16 v[20:23], v[212:215], v[188:191], v[20:23]
	v_mfma_f32_16x16x32_bf16 v[16:19], v[220:223], v[188:191], v[16:19]
	v_mfma_f32_16x16x32_bf16 v[12:15], v[212:215], v[196:199], v[12:15]
	v_mfma_f32_16x16x32_bf16 v[8:11], v[220:223], v[196:199], v[8:11]
	v_mfma_f32_16x16x32_bf16 v[4:7], v[212:215], v[204:207], v[4:7]
	v_mfma_f32_16x16x32_bf16 v[0:3], v[220:223], v[204:207], v[0:3]
	v_mfma_f32_16x16x32_bf16 v[28:31], v[216:219], v[184:187], v[28:31]
	v_mfma_f32_16x16x32_bf16 v[24:27], v[224:227], v[184:187], v[24:27]
	v_mfma_f32_16x16x32_bf16 v[20:23], v[216:219], v[192:195], v[20:23]
	v_mfma_f32_16x16x32_bf16 v[16:19], v[224:227], v[192:195], v[16:19]
	v_mfma_f32_16x16x32_bf16 v[12:15], v[216:219], v[200:203], v[12:15]
	v_mfma_f32_16x16x32_bf16 v[8:11], v[224:227], v[200:203], v[8:11]
	v_mfma_f32_16x16x32_bf16 v[4:7], v[216:219], v[208:211], v[4:7]
	v_mfma_f32_16x16x32_bf16 v[0:3], v[224:227], v[208:211], v[0:3]
	s_barrier
	ds_read_b128 v[164:167], v155
	ds_read_b128 v[168:171], v155 offset:1024
	ds_read_b128 v[172:175], v155 offset:2048
	ds_read_b128 v[176:179], v155 offset:3072
	ds_read_b128 v[180:183], v153 offset:32768
	ds_read_b128 v[184:187], v153 offset:33792
	ds_read_b128 v[188:191], v152 offset:32768
	ds_read_b128 v[192:195], v152 offset:33792
	ds_read_b128 v[196:199], v151 offset:32768
	ds_read_b128 v[200:203], v151 offset:33792
	ds_read_b128 v[204:207], v150 offset:32768
	ds_read_b128 v[208:211], v150 offset:33792
	s_waitcnt lgkmcnt(8)
	s_waitcnt vmcnt(10)
	s_barrier
	s_waitcnt lgkmcnt(0)
	s_waitcnt lgkmcnt(0)
	v_mfma_f32_16x16x32_bf16 v[124:127], v[164:167], v[180:183], v[124:127]
	v_mfma_f32_16x16x32_bf16 v[120:123], v[172:175], v[180:183], v[120:123]
	v_mfma_f32_16x16x32_bf16 v[116:119], v[164:167], v[188:191], v[116:119]
	v_mfma_f32_16x16x32_bf16 v[112:115], v[172:175], v[188:191], v[112:115]
	v_mfma_f32_16x16x32_bf16 v[108:111], v[164:167], v[196:199], v[108:111]
	v_mfma_f32_16x16x32_bf16 v[104:107], v[172:175], v[196:199], v[104:107]
	v_mfma_f32_16x16x32_bf16 v[100:103], v[164:167], v[204:207], v[100:103]
	v_mfma_f32_16x16x32_bf16 v[96:99], v[172:175], v[204:207], v[96:99]
	v_mfma_f32_16x16x32_bf16 v[124:127], v[168:171], v[184:187], v[124:127]
	v_mfma_f32_16x16x32_bf16 v[120:123], v[176:179], v[184:187], v[120:123]
	v_mfma_f32_16x16x32_bf16 v[116:119], v[168:171], v[192:195], v[116:119]
	v_mfma_f32_16x16x32_bf16 v[112:115], v[176:179], v[192:195], v[112:115]
	v_mfma_f32_16x16x32_bf16 v[108:111], v[168:171], v[200:203], v[108:111]
	v_mfma_f32_16x16x32_bf16 v[104:107], v[176:179], v[200:203], v[104:107]
	v_mfma_f32_16x16x32_bf16 v[100:103], v[168:171], v[208:211], v[100:103]
	v_mfma_f32_16x16x32_bf16 v[96:99], v[176:179], v[208:211], v[96:99]
	s_barrier
	s_add_i32 s65, s98, 0x18000
	v_lshl_add_u64 v[232:233], v[230:231], 0, s[30:31]
	s_mov_b32 m0, s65
	s_add_i32 s65, s98, 0x1a000
	ds_read_b128 v[212:215], v154
	ds_read_b128 v[216:219], v154 offset:1024
	ds_read_b128 v[220:223], v154 offset:2048
	ds_read_b128 v[224:227], v154 offset:3072
	global_load_lds_dwordx4 v[232:233], off
	v_lshl_add_u64 v[232:233], v[230:231], 0, s[34:35]
	s_mov_b32 m0, s65
	s_nop 0
	global_load_lds_dwordx4 v[232:233], off
	s_add_i32 s65, s98, 0x8000
	v_lshl_add_u64 v[232:233], v[228:229], 0, s[40:41]
	s_mov_b32 m0, s65
	s_add_i32 s65, s98, 0xa000
	global_load_lds_dwordx4 v[232:233], off
	v_lshl_add_u64 v[228:229], v[228:229], 0, s[44:45]
	s_mov_b32 m0, s65
	s_nop 0
	global_load_lds_dwordx4 v[228:229], off
	s_waitcnt vmcnt(12)
	s_barrier
	s_waitcnt lgkmcnt(0)
	s_waitcnt lgkmcnt(0)
	v_mfma_f32_16x16x32_bf16 v[92:95], v[212:215], v[180:183], v[92:95]
	v_mfma_f32_16x16x32_bf16 v[88:91], v[220:223], v[180:183], v[88:91]
	v_mfma_f32_16x16x32_bf16 v[84:87], v[212:215], v[188:191], v[84:87]
	v_mfma_f32_16x16x32_bf16 v[80:83], v[220:223], v[188:191], v[80:83]
	v_mfma_f32_16x16x32_bf16 v[76:79], v[212:215], v[196:199], v[76:79]
	v_mfma_f32_16x16x32_bf16 v[72:75], v[220:223], v[196:199], v[72:75]
	v_mfma_f32_16x16x32_bf16 v[68:71], v[212:215], v[204:207], v[68:71]
	v_mfma_f32_16x16x32_bf16 v[64:67], v[220:223], v[204:207], v[64:67]
	v_mfma_f32_16x16x32_bf16 v[92:95], v[216:219], v[184:187], v[92:95]
	v_mfma_f32_16x16x32_bf16 v[88:91], v[224:227], v[184:187], v[88:91]
	v_mfma_f32_16x16x32_bf16 v[84:87], v[216:219], v[192:195], v[84:87]
	v_mfma_f32_16x16x32_bf16 v[80:83], v[224:227], v[192:195], v[80:83]
	v_mfma_f32_16x16x32_bf16 v[76:79], v[216:219], v[200:203], v[76:79]
	v_mfma_f32_16x16x32_bf16 v[72:75], v[224:227], v[200:203], v[72:75]
	v_mfma_f32_16x16x32_bf16 v[68:71], v[216:219], v[208:211], v[68:71]
	v_mfma_f32_16x16x32_bf16 v[64:67], v[224:227], v[208:211], v[64:67]
	s_barrier
	ds_read_b128 v[180:183], v153 offset:49152
	ds_read_b128 v[184:187], v153 offset:50176
	ds_read_b128 v[188:191], v152 offset:49152
	ds_read_b128 v[192:195], v152 offset:50176
	ds_read_b128 v[196:199], v151 offset:49152
	ds_read_b128 v[200:203], v151 offset:50176
	ds_read_b128 v[204:207], v150 offset:49152
	ds_read_b128 v[208:211], v150 offset:50176
	s_add_i32 s65, s98, 0x1c000
	v_lshl_add_u64 v[232:233], v[230:231], 0, s[46:47]
	s_mov_b32 m0, s65
	s_add_i32 s65, s98, 0x1e000
	global_load_lds_dwordx4 v[232:233], off
	v_lshl_add_u64 v[232:233], v[230:231], 0, s[56:57]
	s_mov_b32 m0, s65
	s_nop 0
	global_load_lds_dwordx4 v[232:233], off
	s_barrier
	s_waitcnt lgkmcnt(0)
	s_waitcnt lgkmcnt(0)
	v_mfma_f32_16x16x32_bf16 v[60:63], v[164:167], v[180:183], v[60:63]
	v_mfma_f32_16x16x32_bf16 v[56:59], v[172:175], v[180:183], v[56:59]
	v_mfma_f32_16x16x32_bf16 v[52:55], v[164:167], v[188:191], v[52:55]
	v_mfma_f32_16x16x32_bf16 v[48:51], v[172:175], v[188:191], v[48:51]
	v_mfma_f32_16x16x32_bf16 v[44:47], v[164:167], v[196:199], v[44:47]
	v_mfma_f32_16x16x32_bf16 v[40:43], v[172:175], v[196:199], v[40:43]
	v_mfma_f32_16x16x32_bf16 v[36:39], v[164:167], v[204:207], v[36:39]
	v_mfma_f32_16x16x32_bf16 v[32:35], v[172:175], v[204:207], v[32:35]
	v_mfma_f32_16x16x32_bf16 v[60:63], v[168:171], v[184:187], v[60:63]
	v_mfma_f32_16x16x32_bf16 v[56:59], v[176:179], v[184:187], v[56:59]
	v_mfma_f32_16x16x32_bf16 v[52:55], v[168:171], v[192:195], v[52:55]
	v_mfma_f32_16x16x32_bf16 v[48:51], v[176:179], v[192:195], v[48:51]
	v_mfma_f32_16x16x32_bf16 v[44:47], v[168:171], v[200:203], v[44:47]
	v_mfma_f32_16x16x32_bf16 v[40:43], v[176:179], v[200:203], v[40:43]
	v_mfma_f32_16x16x32_bf16 v[36:39], v[168:171], v[208:211], v[36:39]
	v_mfma_f32_16x16x32_bf16 v[32:35], v[176:179], v[208:211], v[32:35]
	s_barrier
	v_lshl_add_u64 v[132:133], v[132:133], 0, s[58:59]
	v_lshl_add_u64 v[228:229], s[50:51], 0, v[132:133]
	s_mov_b64 s[66:67], 0xe080080
	s_add_i32 s65, s98, 0xc000
	v_lshl_add_u64 v[166:167], v[228:229], 0, s[66:67]
	s_mov_b32 m0, s65
	s_mov_b64 s[66:67], 0xe0c0080
	s_add_i32 s65, s98, 0xe000
	global_load_lds_dwordx4 v[166:167], off
	v_lshl_add_u64 v[166:167], v[228:229], 0, s[66:67]
	s_mov_b32 m0, s65
	s_nop 0
	global_load_lds_dwordx4 v[166:167], off
	s_waitcnt vmcnt(12)
	s_barrier
	v_mfma_f32_16x16x32_bf16 v[28:31], v[212:215], v[180:183], v[28:31]
	v_mfma_f32_16x16x32_bf16 v[24:27], v[220:223], v[180:183], v[24:27]
	v_mfma_f32_16x16x32_bf16 v[20:23], v[212:215], v[188:191], v[20:23]
	v_mfma_f32_16x16x32_bf16 v[16:19], v[220:223], v[188:191], v[16:19]
	v_mfma_f32_16x16x32_bf16 v[12:15], v[212:215], v[196:199], v[12:15]
	v_mfma_f32_16x16x32_bf16 v[8:11], v[220:223], v[196:199], v[8:11]
	v_mfma_f32_16x16x32_bf16 v[4:7], v[212:215], v[204:207], v[4:7]
	v_mfma_f32_16x16x32_bf16 v[0:3], v[220:223], v[204:207], v[0:3]
	v_mfma_f32_16x16x32_bf16 v[28:31], v[216:219], v[184:187], v[28:31]
	v_mfma_f32_16x16x32_bf16 v[24:27], v[224:227], v[184:187], v[24:27]
	v_mfma_f32_16x16x32_bf16 v[20:23], v[216:219], v[192:195], v[20:23]
	v_mfma_f32_16x16x32_bf16 v[16:19], v[224:227], v[192:195], v[16:19]
	v_mfma_f32_16x16x32_bf16 v[12:15], v[216:219], v[200:203], v[12:15]
	v_mfma_f32_16x16x32_bf16 v[8:11], v[224:227], v[200:203], v[8:11]
	v_mfma_f32_16x16x32_bf16 v[4:7], v[216:219], v[208:211], v[4:7]
	v_mfma_f32_16x16x32_bf16 v[0:3], v[224:227], v[208:211], v[0:3]
	s_add_i32 s24, s24, 2
	v_lshl_add_u64 v[130:131], v[130:131], 0, s[10:11]
	s_cmp_lt_u32 s24, 28
	s_barrier
	s_cbranch_scc1 .LBB0_178
	s_lshl_b32 s24, s85, 5
	s_lshl_b32 s65, s85, 8
	s_and_b32 s24, s24, 0x1800
	s_and_b32 s65, s65, 0x700
	s_or_b32 s24, s65, s24
	v_lshlrev_b32_e32 v128, 3, v156
	v_lshlrev_b32_e32 v130, 5, v156
	v_and_b32_e32 v128, 0xffff0, v128
	v_and_b32_e32 v130, 32, v130
	s_lshl_b32 s65, s24, 12
	v_add_u32_e32 v130, v130, v158
	v_add_lshl_u32 v128, v157, v128, 12
	s_add_u32 s66, s68, s65
	v_lshl_add_u32 v128, v130, 1, v128
	s_addc_u32 s67, s69, 0
	v_lshl_add_u64 v[156:157], s[66:67], 0, v[128:129]
	v_readfirstlane_b32 s65, v161
	ds_read_b128 v[130:133], v162
	ds_read_b128 v[164:167], v162 offset:1024
	ds_read_b128 v[168:171], v162 offset:2048
	ds_read_b128 v[172:175], v162 offset:3072
	ds_read_b128 v[176:179], v153
	ds_read_b128 v[180:183], v153 offset:1024
	ds_read_b128 v[184:187], v152
	ds_read_b128 v[188:191], v152 offset:1024
	ds_read_b128 v[192:195], v151
	ds_read_b128 v[196:199], v151 offset:1024
	ds_read_b128 v[200:203], v150
	ds_read_b128 v[204:207], v150 offset:1024
	v_lshl_add_u64 v[162:163], v[156:157], 0, s[60:61]
	s_mov_b32 m0, s65
	v_readfirstlane_b32 s65, v160
	v_lshl_add_u64 v[156:157], v[156:157], 0, s[62:63]
	s_mov_b32 m0, s65
	s_nop 0
	s_waitcnt vmcnt(8)
	s_barrier
	s_waitcnt lgkmcnt(0)
	s_setprio 1
	s_waitcnt lgkmcnt(0)
	v_mfma_f32_16x16x32_bf16 v[124:127], v[130:133], v[176:179], v[124:127]
	v_mfma_f32_16x16x32_bf16 v[120:123], v[168:171], v[176:179], v[120:123]
	v_mfma_f32_16x16x32_bf16 v[116:119], v[130:133], v[184:187], v[116:119]
	v_mfma_f32_16x16x32_bf16 v[112:115], v[168:171], v[184:187], v[112:115]
	v_mfma_f32_16x16x32_bf16 v[108:111], v[130:133], v[192:195], v[108:111]
	v_mfma_f32_16x16x32_bf16 v[104:107], v[168:171], v[192:195], v[104:107]
	v_mfma_f32_16x16x32_bf16 v[100:103], v[130:133], v[200:203], v[100:103]
	v_mfma_f32_16x16x32_bf16 v[96:99], v[168:171], v[200:203], v[96:99]
	v_mfma_f32_16x16x32_bf16 v[124:127], v[164:167], v[180:183], v[124:127]
	v_mfma_f32_16x16x32_bf16 v[120:123], v[172:175], v[180:183], v[120:123]
	v_mfma_f32_16x16x32_bf16 v[116:119], v[164:167], v[188:191], v[116:119]
	v_mfma_f32_16x16x32_bf16 v[112:115], v[172:175], v[188:191], v[112:115]
	v_mfma_f32_16x16x32_bf16 v[108:111], v[164:167], v[196:199], v[108:111]
	v_mfma_f32_16x16x32_bf16 v[104:107], v[172:175], v[196:199], v[104:107]
	v_mfma_f32_16x16x32_bf16 v[100:103], v[164:167], v[204:207], v[100:103]
	v_mfma_f32_16x16x32_bf16 v[96:99], v[172:175], v[204:207], v[96:99]
	s_setprio 0
	s_barrier
	ds_read_b128 v[160:163], v159
	ds_read_b128 v[208:211], v159 offset:1024
	ds_read_b128 v[212:215], v159 offset:2048
	ds_read_b128 v[156:159], v159 offset:3072
	s_barrier
	s_waitcnt lgkmcnt(0)
	s_setprio 1
	s_waitcnt lgkmcnt(0)
	v_mfma_f32_16x16x32_bf16 v[92:95], v[160:163], v[176:179], v[92:95]
	v_mfma_f32_16x16x32_bf16 v[88:91], v[212:215], v[176:179], v[88:91]
	v_mfma_f32_16x16x32_bf16 v[84:87], v[160:163], v[184:187], v[84:87]
	v_mfma_f32_16x16x32_bf16 v[80:83], v[212:215], v[184:187], v[80:83]
	v_mfma_f32_16x16x32_bf16 v[76:79], v[160:163], v[192:195], v[76:79]
	v_mfma_f32_16x16x32_bf16 v[72:75], v[212:215], v[192:195], v[72:75]
	v_mfma_f32_16x16x32_bf16 v[68:71], v[160:163], v[200:203], v[68:71]
	v_mfma_f32_16x16x32_bf16 v[64:67], v[212:215], v[200:203], v[64:67]
	v_mfma_f32_16x16x32_bf16 v[176:179], v[208:211], v[180:183], v[92:95]
	v_mfma_f32_16x16x32_bf16 v[180:183], v[156:159], v[180:183], v[88:91]
	v_mfma_f32_16x16x32_bf16 v[184:187], v[208:211], v[188:191], v[84:87]
	v_mfma_f32_16x16x32_bf16 v[188:191], v[156:159], v[188:191], v[80:83]
	v_mfma_f32_16x16x32_bf16 v[192:195], v[208:211], v[196:199], v[76:79]
	v_mfma_f32_16x16x32_bf16 v[196:199], v[156:159], v[196:199], v[72:75]
	v_mfma_f32_16x16x32_bf16 v[200:203], v[208:211], v[204:207], v[68:71]
	v_mfma_f32_16x16x32_bf16 v[204:207], v[156:159], v[204:207], v[64:67]
	s_setprio 0
	s_barrier
	s_nop 0
	ds_read_b128 v[64:67], v153 offset:16384
	ds_read_b128 v[68:71], v153 offset:17408
	ds_read_b128 v[72:75], v152 offset:16384
	ds_read_b128 v[76:79], v152 offset:17408
	ds_read_b128 v[80:83], v151 offset:16384
	ds_read_b128 v[84:87], v151 offset:17408
	ds_read_b128 v[88:91], v150 offset:16384
	ds_read_b128 v[92:95], v150 offset:17408
	s_waitcnt vmcnt(4)
	s_barrier
	s_waitcnt lgkmcnt(0)
	s_setprio 1
	s_waitcnt lgkmcnt(0)
	v_mfma_f32_16x16x32_bf16 v[60:63], v[130:133], v[64:67], v[60:63]
	v_mfma_f32_16x16x32_bf16 v[56:59], v[168:171], v[64:67], v[56:59]
	v_mfma_f32_16x16x32_bf16 v[52:55], v[130:133], v[72:75], v[52:55]
	v_mfma_f32_16x16x32_bf16 v[48:51], v[168:171], v[72:75], v[48:51]
	v_mfma_f32_16x16x32_bf16 v[216:219], v[130:133], v[80:83], v[44:47]
	v_mfma_f32_16x16x32_bf16 v[220:223], v[168:171], v[80:83], v[40:43]
	v_mfma_f32_16x16x32_bf16 v[130:133], v[130:133], v[88:91], v[36:39]
	v_mfma_f32_16x16x32_bf16 v[168:171], v[168:171], v[88:91], v[32:35]
	v_mfma_f32_16x16x32_bf16 v[32:35], v[164:167], v[68:71], v[60:63]
	v_mfma_f32_16x16x32_bf16 v[36:39], v[172:175], v[68:71], v[56:59]
	v_mfma_f32_16x16x32_bf16 v[40:43], v[164:167], v[76:79], v[52:55]
	v_mfma_f32_16x16x32_bf16 v[44:47], v[172:175], v[76:79], v[48:51]
	v_mfma_f32_16x16x32_bf16 v[48:51], v[164:167], v[84:87], v[216:219]
	v_mfma_f32_16x16x32_bf16 v[52:55], v[172:175], v[84:87], v[220:223]
	v_mfma_f32_16x16x32_bf16 v[56:59], v[164:167], v[92:95], v[130:133]
	v_mfma_f32_16x16x32_bf16 v[60:63], v[172:175], v[92:95], v[168:171]
	s_setprio 0
	s_setprio 1
	v_mfma_f32_16x16x32_bf16 v[28:31], v[160:163], v[64:67], v[28:31]
	v_mfma_f32_16x16x32_bf16 v[24:27], v[212:215], v[64:67], v[24:27]
	v_mfma_f32_16x16x32_bf16 v[20:23], v[160:163], v[72:75], v[20:23]
	v_mfma_f32_16x16x32_bf16 v[64:67], v[212:215], v[72:75], v[16:19]
	v_mfma_f32_16x16x32_bf16 v[72:75], v[160:163], v[80:83], v[12:15]
	v_mfma_f32_16x16x32_bf16 v[8:11], v[212:215], v[80:83], v[8:11]
	v_mfma_f32_16x16x32_bf16 v[80:83], v[160:163], v[88:91], v[4:7]
	v_mfma_f32_16x16x32_bf16 v[0:3], v[212:215], v[88:91], v[0:3]
	v_mfma_f32_16x16x32_bf16 v[4:7], v[208:211], v[68:71], v[28:31]
	v_mfma_f32_16x16x32_bf16 v[12:15], v[156:159], v[68:71], v[24:27]
	v_mfma_f32_16x16x32_bf16 v[16:19], v[208:211], v[76:79], v[20:23]
	v_mfma_f32_16x16x32_bf16 v[20:23], v[156:159], v[76:79], v[64:67]
	v_mfma_f32_16x16x32_bf16 v[24:27], v[208:211], v[84:87], v[72:75]
	v_mfma_f32_16x16x32_bf16 v[28:31], v[156:159], v[84:87], v[8:11]
	v_mfma_f32_16x16x32_bf16 v[64:67], v[208:211], v[92:95], v[80:83]
	v_mfma_f32_16x16x32_bf16 v[68:71], v[156:159], v[92:95], v[0:3]
	s_setprio 0
	s_barrier
	ds_read_b128 v[8:11], v155
	ds_read_b128 v[0:3], v155 offset:1024
	ds_read_b128 v[76:79], v155 offset:2048
	ds_read_b128 v[72:75], v155 offset:3072
	ds_read_b128 v[130:133], v153 offset:32768
	ds_read_b128 v[156:159], v153 offset:33792
	ds_read_b128 v[160:163], v152 offset:32768
	ds_read_b128 v[164:167], v152 offset:33792
	ds_read_b128 v[168:171], v151 offset:32768
	ds_read_b128 v[172:175], v151 offset:33792
	ds_read_b128 v[208:211], v150 offset:32768
	ds_read_b128 v[212:215], v150 offset:33792
	s_waitcnt vmcnt(2)
	s_barrier
	s_waitcnt lgkmcnt(0)
	s_setprio 1
	s_waitcnt lgkmcnt(0)
	v_mfma_f32_16x16x32_bf16 v[80:83], v[8:11], v[130:133], v[124:127]
	v_mfma_f32_16x16x32_bf16 v[84:87], v[76:79], v[130:133], v[120:123]
	v_mfma_f32_16x16x32_bf16 v[88:91], v[8:11], v[160:163], v[116:119]
	v_mfma_f32_16x16x32_bf16 v[92:95], v[76:79], v[160:163], v[112:115]
	v_mfma_f32_16x16x32_bf16 v[108:111], v[8:11], v[168:171], v[108:111]
	v_mfma_f32_16x16x32_bf16 v[104:107], v[76:79], v[168:171], v[104:107]
	v_mfma_f32_16x16x32_bf16 v[100:103], v[8:11], v[208:211], v[100:103]
	v_mfma_f32_16x16x32_bf16 v[96:99], v[76:79], v[208:211], v[96:99]
	v_mfma_f32_16x16x32_bf16 v[112:115], v[0:3], v[156:159], v[80:83]
	v_mfma_f32_16x16x32_bf16 v[116:119], v[72:75], v[156:159], v[84:87]
	v_mfma_f32_16x16x32_bf16 v[120:123], v[0:3], v[164:167], v[88:91]
	v_mfma_f32_16x16x32_bf16 v[124:127], v[72:75], v[164:167], v[92:95]
	v_mfma_f32_16x16x32_bf16 v[108:111], v[0:3], v[172:175], v[108:111]
	v_mfma_f32_16x16x32_bf16 v[104:107], v[72:75], v[172:175], v[104:107]
	v_mfma_f32_16x16x32_bf16 v[100:103], v[0:3], v[212:215], v[100:103]
	v_mfma_f32_16x16x32_bf16 v[96:99], v[72:75], v[212:215], v[96:99]
	s_setprio 0
	s_barrier
	ds_read_b128 v[88:91], v154
	ds_read_b128 v[80:83], v154 offset:1024
	ds_read_b128 v[92:95], v154 offset:2048
	ds_read_b128 v[84:87], v154 offset:3072
	s_waitcnt vmcnt(0)
	s_barrier
	s_waitcnt lgkmcnt(0)
	s_setprio 1
	s_waitcnt lgkmcnt(0)
	v_mfma_f32_16x16x32_bf16 v[176:179], v[88:91], v[130:133], v[176:179]
	v_mfma_f32_16x16x32_bf16 v[130:133], v[92:95], v[130:133], v[180:183]
	v_mfma_f32_16x16x32_bf16 v[180:183], v[88:91], v[160:163], v[184:187]
	v_mfma_f32_16x16x32_bf16 v[160:163], v[92:95], v[160:163], v[188:191]
	v_mfma_f32_16x16x32_bf16 v[184:187], v[88:91], v[168:171], v[192:195]
	v_mfma_f32_16x16x32_bf16 v[168:171], v[92:95], v[168:171], v[196:199]
	v_mfma_f32_16x16x32_bf16 v[188:191], v[88:91], v[208:211], v[200:203]
	v_mfma_f32_16x16x32_bf16 v[192:195], v[92:95], v[208:211], v[204:207]
	v_mfma_f32_16x16x32_bf16 v[176:179], v[80:83], v[156:159], v[176:179]
	v_mfma_f32_16x16x32_bf16 v[130:133], v[84:87], v[156:159], v[130:133]
	v_mfma_f32_16x16x32_bf16 v[154:157], v[80:83], v[164:167], v[180:183]
	v_mfma_f32_16x16x32_bf16 v[158:161], v[84:87], v[164:167], v[160:163]
	v_mfma_f32_16x16x32_bf16 v[162:165], v[80:83], v[172:175], v[184:187]
	v_mfma_f32_16x16x32_bf16 v[166:169], v[84:87], v[172:175], v[168:171]
	v_mfma_f32_16x16x32_bf16 v[170:173], v[80:83], v[212:215], v[188:191]
	v_mfma_f32_16x16x32_bf16 v[180:183], v[84:87], v[212:215], v[192:195]
	s_setprio 0
	s_barrier
	v_mbcnt_lo_u32_b32 v128, -1, 0
	v_mbcnt_hi_u32_b32 v128, -1, v128
	v_cvt_pk_bf16_f32 v112, v112, v113
	v_cvt_pk_bf16_f32 v113, v114, v115
	v_cvt_pk_bf16_f32 v114, v116, v117
	v_cvt_pk_bf16_f32 v115, v118, v119
	s_lshl_b32 s66, s64, 9
	v_add_u32_e32 v174, s72, v128
	v_ashrrev_i32_e32 v175, 6, v174
	v_and_b32_e32 v184, 15, v128
	v_and_b32_e32 v185, 48, v128
	v_mul_lo_u32 v186, v175, s77
	v_bfe_u32 v187, v128, 3, 3
	v_lshlrev_b32_e32 v128, 4, v128
	v_add_u32_e32 v186, 0x20000, v186
	v_lshrrev_b32_e32 v174, 2, v174
	v_and_b32_e32 v128, 0x70, v128
	v_mul_u32_u24_e32 v184, 0x90, v184
	v_and_b32_e32 v174, 64, v174
	v_add3_u32 v184, v186, v184, v185
	v_or_b32_e32 v185, v186, v128
	v_or3_b32 v174, s24, v174, v187
	v_mad_u32_u24 v185, v187, s78, v185
	ds_write_b128 v184, v[112:115]
	v_cvt_pk_bf16_f32 v112, v176, v177
	v_cvt_pk_bf16_f32 v113, v178, v179
	v_cvt_pk_bf16_f32 v114, v130, v131
	v_cvt_pk_bf16_f32 v115, v132, v133
	ds_write_b128 v184, v[112:115] offset:64
	v_lshlrev_b32_e32 v175, 7, v175
	ds_read_b128 v[112:115], v185
	v_lshlrev_b32_e32 v116, 12, v174
	v_and_or_b32 v116, v175, s79, v116
	v_or3_b32 v128, v116, s66, v128
	ds_read_b128 v[116:119], v185 offset:1152
	v_lshl_add_u64 v[130:131], s[0:1], 0, v[128:129]
	s_mov_b32 s64, 0x8000
	s_waitcnt lgkmcnt(0)
	global_store_dwordx4 v128, v[112:115], s[0:1]
	v_cvt_pk_bf16_f32 v108, v108, v109
	v_cvt_pk_bf16_f32 v109, v110, v111
	v_cvt_pk_bf16_f32 v110, v104, v105
	v_cvt_pk_bf16_f32 v111, v106, v107
	v_cvt_pk_bf16_f32 v104, v162, v163
	s_nop 1
	v_add_co_u32_e32 v112, vcc, s64, v130
	v_cvt_pk_bf16_f32 v114, v124, v125
	v_cvt_pk_bf16_f32 v115, v126, v127
	v_cvt_pk_bf16_f32 v105, v164, v165
	v_cvt_pk_bf16_f32 v106, v166, v167
	s_nop 1
	v_addc_co_u32_e32 v113, vcc, 0, v131, vcc
	global_store_dwordx4 v[112:113], v[116:119], off
	v_cvt_pk_bf16_f32 v112, v120, v121
	v_cvt_pk_bf16_f32 v113, v122, v123
	ds_write_b128 v184, v[112:115]
	v_cvt_pk_bf16_f32 v112, v154, v155
	v_cvt_pk_bf16_f32 v113, v156, v157
	v_cvt_pk_bf16_f32 v114, v158, v159
	v_cvt_pk_bf16_f32 v115, v160, v161
	ds_write_b128 v184, v[112:115] offset:64
	ds_read_b128 v[112:115], v185
	ds_read_b128 v[116:119], v185 offset:1152
	v_add_co_u32_e32 v120, vcc, s74, v130
	ds_write_b128 v184, v[108:111]
	v_cvt_pk_bf16_f32 v107, v168, v169
	ds_write_b128 v184, v[104:107] offset:64
	v_addc_co_u32_e32 v121, vcc, 0, v131, vcc
	ds_read_b128 v[104:107], v185
	ds_read_b128 v[108:111], v185 offset:1152
	s_waitcnt lgkmcnt(0)
	global_store_dwordx4 v[120:121], v[112:115], off
	v_cvt_pk_bf16_f32 v100, v100, v101
	v_cvt_pk_bf16_f32 v101, v102, v103
	v_cvt_pk_bf16_f32 v102, v96, v97
	v_cvt_pk_bf16_f32 v103, v98, v99
	ds_write_b128 v184, v[100:103]
	s_nop 0
	v_add_co_u32_e32 v112, vcc, s75, v130
	v_cvt_pk_bf16_f32 v96, v170, v171
	v_cvt_pk_bf16_f32 v97, v172, v173
	v_cvt_pk_bf16_f32 v98, v180, v181
	v_cvt_pk_bf16_f32 v99, v182, v183
	s_nop 1
	v_addc_co_u32_e32 v113, vcc, 0, v131, vcc
	global_store_dwordx4 v[112:113], v[116:119], off
	v_add_co_u32_e32 v112, vcc, s76, v130
	ds_write_b128 v184, v[96:99] offset:64
	s_nop 0
	v_addc_co_u32_e32 v113, vcc, 0, v131, vcc
	ds_read_b128 v[96:99], v185
	ds_read_b128 v[100:103], v185 offset:1152
	global_store_dwordx4 v[112:113], v[104:107], off
	s_nop 1
	v_add_co_u32_e32 v104, vcc, s80, v130
	s_nop 1
	v_addc_co_u32_e32 v105, vcc, 0, v131, vcc
	global_store_dwordx4 v[104:105], v[108:111], off
	v_add_co_u32_e32 v104, vcc, s81, v130
	s_nop 1
	v_addc_co_u32_e32 v105, vcc, 0, v131, vcc
	s_waitcnt lgkmcnt(0)
	global_store_dwordx4 v[104:105], v[96:99], off
	s_nop 1
	v_add_co_u32_e32 v96, vcc, s82, v130
	s_nop 1
	v_addc_co_u32_e32 v97, vcc, 0, v131, vcc
	global_store_dwordx4 v[96:97], v[100:103], off
	ds_read_b128 v[96:99], v153 offset:49152
	ds_read_b128 v[100:103], v153 offset:50176
	ds_read_b128 v[104:107], v152 offset:49152
	ds_read_b128 v[108:111], v152 offset:50176
	ds_read_b128 v[112:115], v151 offset:49152
	ds_read_b128 v[116:119], v151 offset:50176
	ds_read_b128 v[120:123], v150 offset:49152
	ds_read_b128 v[124:127], v150 offset:50176
	s_barrier
	s_waitcnt lgkmcnt(0)
	s_setprio 1
	s_waitcnt lgkmcnt(0)
	v_mfma_f32_16x16x32_bf16 v[32:35], v[8:11], v[96:99], v[32:35]
	v_mfma_f32_16x16x32_bf16 v[36:39], v[76:79], v[96:99], v[36:39]
	v_mfma_f32_16x16x32_bf16 v[40:43], v[8:11], v[104:107], v[40:43]
	v_mfma_f32_16x16x32_bf16 v[130:133], v[76:79], v[104:107], v[44:47]
	v_mfma_f32_16x16x32_bf16 v[150:153], v[8:11], v[112:115], v[48:51]
	v_mfma_f32_16x16x32_bf16 v[52:55], v[76:79], v[112:115], v[52:55]
	v_mfma_f32_16x16x32_bf16 v[8:11], v[8:11], v[120:123], v[56:59]
	v_mfma_f32_16x16x32_bf16 v[60:63], v[76:79], v[120:123], v[60:63]
	v_mfma_f32_16x16x32_bf16 v[56:59], v[0:3], v[100:103], v[32:35]
	v_mfma_f32_16x16x32_bf16 v[48:51], v[72:75], v[100:103], v[36:39]
	v_mfma_f32_16x16x32_bf16 v[44:47], v[0:3], v[108:111], v[40:43]
	v_mfma_f32_16x16x32_bf16 v[40:43], v[72:75], v[108:111], v[130:133]
	v_mfma_f32_16x16x32_bf16 v[36:39], v[0:3], v[116:119], v[150:153]
	v_mfma_f32_16x16x32_bf16 v[32:35], v[72:75], v[116:119], v[52:55]
	v_mfma_f32_16x16x32_bf16 v[8:11], v[0:3], v[124:127], v[8:11]
	v_mfma_f32_16x16x32_bf16 v[0:3], v[72:75], v[124:127], v[60:63]
	s_setprio 0
	s_setprio 1
	v_mfma_f32_16x16x32_bf16 v[4:7], v[88:91], v[96:99], v[4:7]
	v_mfma_f32_16x16x32_bf16 v[12:15], v[92:95], v[96:99], v[12:15]
	v_mfma_f32_16x16x32_bf16 v[16:19], v[88:91], v[104:107], v[16:19]
	v_mfma_f32_16x16x32_bf16 v[20:23], v[92:95], v[104:107], v[20:23]
	v_mfma_f32_16x16x32_bf16 v[72:75], v[88:91], v[112:115], v[24:27]
	v_mfma_f32_16x16x32_bf16 v[76:79], v[92:95], v[112:115], v[28:31]
	v_mfma_f32_16x16x32_bf16 v[64:67], v[88:91], v[120:123], v[64:67]
	v_mfma_f32_16x16x32_bf16 v[68:71], v[92:95], v[120:123], v[68:71]
	v_mfma_f32_16x16x32_bf16 v[60:63], v[80:83], v[100:103], v[4:7]
	v_mfma_f32_16x16x32_bf16 v[52:55], v[84:87], v[100:103], v[12:15]
	v_mfma_f32_16x16x32_bf16 v[28:31], v[80:83], v[108:111], v[16:19]
	v_mfma_f32_16x16x32_bf16 v[24:27], v[84:87], v[108:111], v[20:23]
	v_mfma_f32_16x16x32_bf16 v[20:23], v[80:83], v[116:119], v[72:75]
	v_mfma_f32_16x16x32_bf16 v[16:19], v[84:87], v[116:119], v[76:79]
	v_mfma_f32_16x16x32_bf16 v[12:15], v[80:83], v[124:127], v[64:67]
	v_mfma_f32_16x16x32_bf16 v[4:7], v[84:87], v[124:127], v[68:71]
	s_setprio 0
	v_cmp_gt_u32_e32 vcc, s83, v136
	s_barrier
	s_and_saveexec_b64 s[64:65], vcc
	s_cbranch_execz .LBB0_181
	s_barrier

.LBB0_234:
	ds_read_b128 v[140:143], v138
	ds_read_b128 v[144:147], v138 offset:1024
	ds_read_b128 v[148:151], v138 offset:2048
	ds_read_b128 v[152:155], v138 offset:3072
	ds_read_b128 v[156:159], v193
	ds_read_b128 v[160:163], v193 offset:1024
	ds_read_b128 v[194:197], v192
	ds_read_b128 v[198:201], v192 offset:1024
	ds_read_b128 v[202:205], v191
	ds_read_b128 v[206:209], v191 offset:1024
	ds_read_b128 v[210:213], v190
	ds_read_b128 v[214:217], v190 offset:1024
	s_waitcnt lgkmcnt(8)
	s_waitcnt vmcnt(10)
	s_barrier
	s_waitcnt lgkmcnt(0)
	s_waitcnt lgkmcnt(0)
	v_mfma_f32_16x16x32_bf16 v[124:127], v[140:143], v[156:159], v[124:127]
	v_mfma_f32_16x16x32_bf16 v[120:123], v[148:151], v[156:159], v[120:123]
	v_mfma_f32_16x16x32_bf16 v[116:119], v[140:143], v[194:197], v[116:119]
	v_mfma_f32_16x16x32_bf16 v[112:115], v[148:151], v[194:197], v[112:115]
	v_mfma_f32_16x16x32_bf16 v[108:111], v[140:143], v[202:205], v[108:111]
	v_mfma_f32_16x16x32_bf16 v[104:107], v[148:151], v[202:205], v[104:107]
	v_mfma_f32_16x16x32_bf16 v[100:103], v[140:143], v[210:213], v[100:103]
	v_mfma_f32_16x16x32_bf16 v[96:99], v[148:151], v[210:213], v[96:99]
	v_mfma_f32_16x16x32_bf16 v[124:127], v[144:147], v[160:163], v[124:127]
	v_mfma_f32_16x16x32_bf16 v[120:123], v[152:155], v[160:163], v[120:123]
	v_mfma_f32_16x16x32_bf16 v[116:119], v[144:147], v[198:201], v[116:119]
	v_mfma_f32_16x16x32_bf16 v[112:115], v[152:155], v[198:201], v[112:115]
	v_mfma_f32_16x16x32_bf16 v[108:111], v[144:147], v[206:209], v[108:111]
	v_mfma_f32_16x16x32_bf16 v[104:107], v[152:155], v[206:209], v[104:107]
	v_mfma_f32_16x16x32_bf16 v[100:103], v[144:147], v[214:217], v[100:103]
	v_mfma_f32_16x16x32_bf16 v[96:99], v[152:155], v[214:217], v[96:99]
	s_barrier
	s_add_i32 s82, s98, 0x10000
	v_lshl_add_u64 v[234:235], s[60:61], 0, v[164:165]
	s_mov_b32 m0, s82
	s_add_i32 s82, s98, 0x12000
	ds_read_b128 v[218:221], v135
	ds_read_b128 v[222:225], v135 offset:1024
	ds_read_b128 v[226:229], v135 offset:2048
	ds_read_b128 v[230:233], v135 offset:3072
	global_load_lds_dwordx4 v[234:235], off
	v_lshl_add_u64 v[236:237], v[234:235], 0, s[2:3]
	s_mov_b32 m0, s82
	s_nop 0
	global_load_lds_dwordx4 v[236:237], off
	s_mov_b32 s82, s98
	v_lshl_add_u64 v[236:237], v[128:129], 0, s[22:23]
	s_mov_b32 m0, s82
	s_add_i32 s82, s98, 0x2000
	global_load_lds_dwordx4 v[236:237], off
	v_lshl_add_u64 v[236:237], v[128:129], 0, s[24:25]
	s_mov_b32 m0, s82
	s_nop 0
	global_load_lds_dwordx4 v[236:237], off
	s_waitcnt vmcnt(12)
	s_barrier
	s_waitcnt lgkmcnt(0)
	s_waitcnt lgkmcnt(0)
	v_mfma_f32_16x16x32_bf16 v[92:95], v[218:221], v[156:159], v[92:95]
	v_mfma_f32_16x16x32_bf16 v[88:91], v[226:229], v[156:159], v[88:91]
	v_mfma_f32_16x16x32_bf16 v[84:87], v[218:221], v[194:197], v[84:87]
	v_mfma_f32_16x16x32_bf16 v[80:83], v[226:229], v[194:197], v[80:83]
	v_mfma_f32_16x16x32_bf16 v[76:79], v[218:221], v[202:205], v[76:79]
	v_mfma_f32_16x16x32_bf16 v[72:75], v[226:229], v[202:205], v[72:75]
	v_mfma_f32_16x16x32_bf16 v[68:71], v[218:221], v[210:213], v[68:71]
	v_mfma_f32_16x16x32_bf16 v[64:67], v[226:229], v[210:213], v[64:67]
	v_mfma_f32_16x16x32_bf16 v[92:95], v[222:225], v[160:163], v[92:95]
	v_mfma_f32_16x16x32_bf16 v[88:91], v[230:233], v[160:163], v[88:91]
	v_mfma_f32_16x16x32_bf16 v[84:87], v[222:225], v[198:201], v[84:87]
	v_mfma_f32_16x16x32_bf16 v[80:83], v[230:233], v[198:201], v[80:83]
	v_mfma_f32_16x16x32_bf16 v[76:79], v[222:225], v[206:209], v[76:79]
	v_mfma_f32_16x16x32_bf16 v[72:75], v[230:233], v[206:209], v[72:75]
	v_mfma_f32_16x16x32_bf16 v[68:71], v[222:225], v[214:217], v[68:71]
	v_mfma_f32_16x16x32_bf16 v[64:67], v[230:233], v[214:217], v[64:67]
	s_barrier
	ds_read_b128 v[156:159], v193 offset:16384
	ds_read_b128 v[160:163], v193 offset:17408
	ds_read_b128 v[194:197], v192 offset:16384
	ds_read_b128 v[198:201], v192 offset:17408
	ds_read_b128 v[202:205], v191 offset:16384
	ds_read_b128 v[206:209], v191 offset:17408
	ds_read_b128 v[210:213], v190 offset:16384
	ds_read_b128 v[214:217], v190 offset:17408
	s_add_i32 s82, s98, 0x14000
	v_lshl_add_u64 v[236:237], v[234:235], 0, s[6:7]
	s_mov_b32 m0, s82
	s_add_i32 s82, s98, 0x16000
	global_load_lds_dwordx4 v[236:237], off
	v_lshl_add_u64 v[236:237], v[234:235], 0, s[8:9]
	s_mov_b32 m0, s82
	s_nop 0
	global_load_lds_dwordx4 v[236:237], off
	s_barrier
	s_waitcnt lgkmcnt(0)
	s_waitcnt lgkmcnt(0)
	v_mfma_f32_16x16x32_bf16 v[60:63], v[140:143], v[156:159], v[60:63]
	v_mfma_f32_16x16x32_bf16 v[56:59], v[148:151], v[156:159], v[56:59]
	v_mfma_f32_16x16x32_bf16 v[52:55], v[140:143], v[194:197], v[52:55]
	v_mfma_f32_16x16x32_bf16 v[48:51], v[148:151], v[194:197], v[48:51]
	v_mfma_f32_16x16x32_bf16 v[44:47], v[140:143], v[202:205], v[44:47]
	v_mfma_f32_16x16x32_bf16 v[40:43], v[148:151], v[202:205], v[40:43]
	v_mfma_f32_16x16x32_bf16 v[36:39], v[140:143], v[210:213], v[36:39]
	v_mfma_f32_16x16x32_bf16 v[32:35], v[148:151], v[210:213], v[32:35]
	v_mfma_f32_16x16x32_bf16 v[60:63], v[144:147], v[160:163], v[60:63]
	v_mfma_f32_16x16x32_bf16 v[56:59], v[152:155], v[160:163], v[56:59]
	v_mfma_f32_16x16x32_bf16 v[52:55], v[144:147], v[198:201], v[52:55]
	v_mfma_f32_16x16x32_bf16 v[48:51], v[152:155], v[198:201], v[48:51]
	v_mfma_f32_16x16x32_bf16 v[44:47], v[144:147], v[206:209], v[44:47]
	v_mfma_f32_16x16x32_bf16 v[40:43], v[152:155], v[206:209], v[40:43]
	v_mfma_f32_16x16x32_bf16 v[36:39], v[144:147], v[214:217], v[36:39]
	v_mfma_f32_16x16x32_bf16 v[32:35], v[152:155], v[214:217], v[32:35]
	s_barrier
	s_add_i32 s82, s98, 0x4000
	v_lshl_add_u64 v[142:143], v[128:129], 0, s[26:27]
	s_mov_b32 m0, s82
	s_add_i32 s82, s98, 0x6000
	global_load_lds_dwordx4 v[142:143], off
	s_mov_b32 m0, s82
	s_nop 0
	global_load_lds_dwordx4 v[128:129], off
	s_waitcnt vmcnt(12)
	s_barrier
	v_mfma_f32_16x16x32_bf16 v[28:31], v[218:221], v[156:159], v[28:31]
	v_mfma_f32_16x16x32_bf16 v[24:27], v[226:229], v[156:159], v[24:27]
	v_mfma_f32_16x16x32_bf16 v[20:23], v[218:221], v[194:197], v[20:23]
	v_mfma_f32_16x16x32_bf16 v[16:19], v[226:229], v[194:197], v[16:19]
	v_mfma_f32_16x16x32_bf16 v[12:15], v[218:221], v[202:205], v[12:15]
	v_mfma_f32_16x16x32_bf16 v[8:11], v[226:229], v[202:205], v[8:11]
	v_mfma_f32_16x16x32_bf16 v[4:7], v[218:221], v[210:213], v[4:7]
	v_mfma_f32_16x16x32_bf16 v[0:3], v[226:229], v[210:213], v[0:3]
	v_mfma_f32_16x16x32_bf16 v[28:31], v[222:225], v[160:163], v[28:31]
	v_mfma_f32_16x16x32_bf16 v[24:27], v[230:233], v[160:163], v[24:27]
	v_mfma_f32_16x16x32_bf16 v[20:23], v[222:225], v[198:201], v[20:23]
	v_mfma_f32_16x16x32_bf16 v[16:19], v[230:233], v[198:201], v[16:19]
	v_mfma_f32_16x16x32_bf16 v[12:15], v[222:225], v[206:209], v[12:15]
	v_mfma_f32_16x16x32_bf16 v[8:11], v[230:233], v[206:209], v[8:11]
	v_mfma_f32_16x16x32_bf16 v[4:7], v[222:225], v[214:217], v[4:7]
	v_mfma_f32_16x16x32_bf16 v[0:3], v[230:233], v[214:217], v[0:3]
	s_barrier
	ds_read_b128 v[140:143], v130
	ds_read_b128 v[144:147], v130 offset:1024
	ds_read_b128 v[148:151], v130 offset:2048
	ds_read_b128 v[152:155], v130 offset:3072
	ds_read_b128 v[156:159], v193 offset:32768
	ds_read_b128 v[160:163], v193 offset:33792
	ds_read_b128 v[194:197], v192 offset:32768
	ds_read_b128 v[198:201], v192 offset:33792
	ds_read_b128 v[202:205], v191 offset:32768
	ds_read_b128 v[206:209], v191 offset:33792
	ds_read_b128 v[210:213], v190 offset:32768
	ds_read_b128 v[214:217], v190 offset:33792
	s_waitcnt lgkmcnt(8)
	s_waitcnt vmcnt(10)
	s_barrier
	s_waitcnt lgkmcnt(0)
	s_waitcnt lgkmcnt(0)
	v_mfma_f32_16x16x32_bf16 v[124:127], v[140:143], v[156:159], v[124:127]
	v_mfma_f32_16x16x32_bf16 v[120:123], v[148:151], v[156:159], v[120:123]
	v_mfma_f32_16x16x32_bf16 v[116:119], v[140:143], v[194:197], v[116:119]
	v_mfma_f32_16x16x32_bf16 v[112:115], v[148:151], v[194:197], v[112:115]
	v_mfma_f32_16x16x32_bf16 v[108:111], v[140:143], v[202:205], v[108:111]
	v_mfma_f32_16x16x32_bf16 v[104:107], v[148:151], v[202:205], v[104:107]
	v_mfma_f32_16x16x32_bf16 v[100:103], v[140:143], v[210:213], v[100:103]
	v_mfma_f32_16x16x32_bf16 v[96:99], v[148:151], v[210:213], v[96:99]
	v_mfma_f32_16x16x32_bf16 v[124:127], v[144:147], v[160:163], v[124:127]
	v_mfma_f32_16x16x32_bf16 v[120:123], v[152:155], v[160:163], v[120:123]
	v_mfma_f32_16x16x32_bf16 v[116:119], v[144:147], v[198:201], v[116:119]
	v_mfma_f32_16x16x32_bf16 v[112:115], v[152:155], v[198:201], v[112:115]
	v_mfma_f32_16x16x32_bf16 v[108:111], v[144:147], v[206:209], v[108:111]
	v_mfma_f32_16x16x32_bf16 v[104:107], v[152:155], v[206:209], v[104:107]
	v_mfma_f32_16x16x32_bf16 v[100:103], v[144:147], v[214:217], v[100:103]
	v_mfma_f32_16x16x32_bf16 v[96:99], v[152:155], v[214:217], v[96:99]
	s_barrier
	s_add_i32 s82, s98, 0x18000
	v_lshl_add_u64 v[234:235], s[56:57], 0, v[164:165]
	s_mov_b32 m0, s82
	s_add_i32 s82, s98, 0x1a000
	ds_read_b128 v[218:221], v132
	ds_read_b128 v[222:225], v132 offset:1024
	ds_read_b128 v[226:229], v132 offset:2048
	ds_read_b128 v[230:233], v132 offset:3072
	global_load_lds_dwordx4 v[234:235], off
	v_lshl_add_u64 v[236:237], v[234:235], 0, s[2:3]
	s_mov_b32 m0, s82
	s_nop 0
	global_load_lds_dwordx4 v[236:237], off
	s_add_i32 s82, s98, 0x8000
	v_lshl_add_u64 v[236:237], v[128:129], 0, s[28:29]
	s_mov_b32 m0, s82
	s_add_i32 s82, s98, 0xa000
	global_load_lds_dwordx4 v[236:237], off
	v_lshl_add_u64 v[236:237], v[128:129], 0, s[30:31]
	s_mov_b32 m0, s82
	s_nop 0
	global_load_lds_dwordx4 v[236:237], off
	s_waitcnt vmcnt(12)
	s_barrier
	s_waitcnt lgkmcnt(0)
	s_waitcnt lgkmcnt(0)
	v_mfma_f32_16x16x32_bf16 v[92:95], v[218:221], v[156:159], v[92:95]
	v_mfma_f32_16x16x32_bf16 v[88:91], v[226:229], v[156:159], v[88:91]
	v_mfma_f32_16x16x32_bf16 v[84:87], v[218:221], v[194:197], v[84:87]
	v_mfma_f32_16x16x32_bf16 v[80:83], v[226:229], v[194:197], v[80:83]
	v_mfma_f32_16x16x32_bf16 v[76:79], v[218:221], v[202:205], v[76:79]
	v_mfma_f32_16x16x32_bf16 v[72:75], v[226:229], v[202:205], v[72:75]
	v_mfma_f32_16x16x32_bf16 v[68:71], v[218:221], v[210:213], v[68:71]
	v_mfma_f32_16x16x32_bf16 v[64:67], v[226:229], v[210:213], v[64:67]
	v_mfma_f32_16x16x32_bf16 v[92:95], v[222:225], v[160:163], v[92:95]
	v_mfma_f32_16x16x32_bf16 v[88:91], v[230:233], v[160:163], v[88:91]
	v_mfma_f32_16x16x32_bf16 v[84:87], v[222:225], v[198:201], v[84:87]
	v_mfma_f32_16x16x32_bf16 v[80:83], v[230:233], v[198:201], v[80:83]
	v_mfma_f32_16x16x32_bf16 v[76:79], v[222:225], v[206:209], v[76:79]
	v_mfma_f32_16x16x32_bf16 v[72:75], v[230:233], v[206:209], v[72:75]
	v_mfma_f32_16x16x32_bf16 v[68:71], v[222:225], v[214:217], v[68:71]
	v_mfma_f32_16x16x32_bf16 v[64:67], v[230:233], v[214:217], v[64:67]
	s_barrier
	ds_read_b128 v[156:159], v193 offset:49152
	ds_read_b128 v[160:163], v193 offset:50176
	ds_read_b128 v[194:197], v192 offset:49152
	ds_read_b128 v[198:201], v192 offset:50176
	ds_read_b128 v[202:205], v191 offset:49152
	ds_read_b128 v[206:209], v191 offset:50176
	ds_read_b128 v[210:213], v190 offset:49152
	ds_read_b128 v[214:217], v190 offset:50176
	s_add_i32 s82, s98, 0x1c000
	v_lshl_add_u64 v[236:237], v[234:235], 0, s[6:7]
	s_mov_b32 m0, s82
	s_add_i32 s82, s98, 0x1e000
	global_load_lds_dwordx4 v[236:237], off
	v_lshl_add_u64 v[236:237], v[234:235], 0, s[8:9]
	s_mov_b32 m0, s82
	s_nop 0
	global_load_lds_dwordx4 v[236:237], off
	s_barrier
	s_waitcnt lgkmcnt(0)
	s_waitcnt lgkmcnt(0)
	v_mfma_f32_16x16x32_bf16 v[60:63], v[140:143], v[156:159], v[60:63]
	v_mfma_f32_16x16x32_bf16 v[56:59], v[148:151], v[156:159], v[56:59]
	v_mfma_f32_16x16x32_bf16 v[52:55], v[140:143], v[194:197], v[52:55]
	v_mfma_f32_16x16x32_bf16 v[48:51], v[148:151], v[194:197], v[48:51]
	v_mfma_f32_16x16x32_bf16 v[44:47], v[140:143], v[202:205], v[44:47]
	v_mfma_f32_16x16x32_bf16 v[40:43], v[148:151], v[202:205], v[40:43]
	v_mfma_f32_16x16x32_bf16 v[36:39], v[140:143], v[210:213], v[36:39]
	v_mfma_f32_16x16x32_bf16 v[32:35], v[148:151], v[210:213], v[32:35]
	v_mfma_f32_16x16x32_bf16 v[60:63], v[144:147], v[160:163], v[60:63]
	v_mfma_f32_16x16x32_bf16 v[56:59], v[152:155], v[160:163], v[56:59]
	v_mfma_f32_16x16x32_bf16 v[52:55], v[144:147], v[198:201], v[52:55]
	v_mfma_f32_16x16x32_bf16 v[48:51], v[152:155], v[198:201], v[48:51]
	v_mfma_f32_16x16x32_bf16 v[44:47], v[144:147], v[206:209], v[44:47]
	v_mfma_f32_16x16x32_bf16 v[40:43], v[152:155], v[206:209], v[40:43]
	v_mfma_f32_16x16x32_bf16 v[36:39], v[144:147], v[214:217], v[36:39]
	v_mfma_f32_16x16x32_bf16 v[32:35], v[152:155], v[214:217], v[32:35]
	s_barrier
	v_lshl_add_u64 v[128:129], v[128:129], 0, s[34:35]
	s_add_i32 s82, s98, 0xc000
	v_lshl_add_u64 v[142:143], v[128:129], 0, s[18:19]
	s_mov_b32 m0, s82
	s_add_i32 s82, s98, 0xe000
	global_load_lds_dwordx4 v[142:143], off
	v_lshl_add_u64 v[142:143], v[128:129], 0, s[20:21]
	s_mov_b32 m0, s82
	s_nop 0
	global_load_lds_dwordx4 v[142:143], off
	s_waitcnt vmcnt(12)
	s_barrier
	v_mfma_f32_16x16x32_bf16 v[28:31], v[218:221], v[156:159], v[28:31]
	v_mfma_f32_16x16x32_bf16 v[24:27], v[226:229], v[156:159], v[24:27]
	v_mfma_f32_16x16x32_bf16 v[20:23], v[218:221], v[194:197], v[20:23]
	v_mfma_f32_16x16x32_bf16 v[16:19], v[226:229], v[194:197], v[16:19]
	v_mfma_f32_16x16x32_bf16 v[12:15], v[218:221], v[202:205], v[12:15]
	v_mfma_f32_16x16x32_bf16 v[8:11], v[226:229], v[202:205], v[8:11]
	v_mfma_f32_16x16x32_bf16 v[4:7], v[218:221], v[210:213], v[4:7]
	v_mfma_f32_16x16x32_bf16 v[0:3], v[226:229], v[210:213], v[0:3]
	v_mfma_f32_16x16x32_bf16 v[28:31], v[222:225], v[160:163], v[28:31]
	v_mfma_f32_16x16x32_bf16 v[24:27], v[230:233], v[160:163], v[24:27]
	v_mfma_f32_16x16x32_bf16 v[20:23], v[222:225], v[198:201], v[20:23]
	v_mfma_f32_16x16x32_bf16 v[16:19], v[230:233], v[198:201], v[16:19]
	v_mfma_f32_16x16x32_bf16 v[12:15], v[222:225], v[206:209], v[12:15]
	v_mfma_f32_16x16x32_bf16 v[8:11], v[230:233], v[206:209], v[8:11]
	v_mfma_f32_16x16x32_bf16 v[4:7], v[222:225], v[214:217], v[4:7]
	v_mfma_f32_16x16x32_bf16 v[0:3], v[230:233], v[214:217], v[0:3]
	s_add_i32 s14, s14, 2
	s_add_u32 s56, s56, s58
	s_addc_u32 s57, s57, s59
	s_add_u32 s60, s60, s58
	s_addc_u32 s61, s61, s59
	s_cmp_lt_u32 s14, 28
	s_barrier
	s_cbranch_scc1 .LBB0_234
	s_lshl_b32 s14, s62, 3
	s_or_b32 s82, s63, s14
	s_lshl_b32 s56, s82, 8
	v_lshlrev_b32_e32 v128, 3, v131
	v_lshlrev_b32_e32 v129, 5, v131
	s_or_b32 s14, s56, 0x80
	v_and_b32_e32 v128, 0x7fff0, v128
	v_and_b32_e32 v129, 32, v129
	s_lshl_b64 s[58:59], s[14:15], 13
	v_add_u32_e32 v129, v129, v134
	v_add_lshl_u32 v128, v133, v128, 13
	s_add_u32 s58, s40, s58
	v_lshl_add_u32 v164, v129, 1, v128
	s_addc_u32 s59, s41, s59
	v_lshl_add_u64 v[128:129], s[58:59], 0, v[164:165]
	v_readfirstlane_b32 s14, v137
	ds_read_b128 v[140:143], v138
	ds_read_b128 v[144:147], v138 offset:1024
	ds_read_b128 v[148:151], v138 offset:2048
	ds_read_b128 v[152:155], v138 offset:3072
	ds_read_b128 v[156:159], v193
	ds_read_b128 v[160:163], v193 offset:1024
	ds_read_b128 v[194:197], v192
	ds_read_b128 v[198:201], v192 offset:1024
	ds_read_b128 v[202:205], v191
	ds_read_b128 v[206:209], v191 offset:1024
	ds_read_b128 v[210:213], v190
	ds_read_b128 v[214:217], v190 offset:1024
	v_lshl_add_u64 v[138:139], v[128:129], 0, s[44:45]
	s_mov_b32 m0, s14
	v_readfirstlane_b32 s14, v136
	v_lshl_add_u64 v[128:129], v[128:129], 0, s[46:47]
	s_mov_b32 m0, s14
	s_mov_b32 s57, s15
	s_mul_i32 s99, s78, s84
	s_add_i32 s99, s99, s33
	s_cmpk_lt_u32 s99, 0x400
	s_cbranch_scc1 .Lxt5_has
	s_mov_b32 s99, 0
	s_branch .Lxt5_set

.Lxt5_set:
	s_waitcnt vmcnt(8)
	s_barrier
	s_waitcnt lgkmcnt(0)
	s_setprio 1
	s_waitcnt lgkmcnt(0)
	v_mfma_f32_16x16x32_bf16 v[124:127], v[140:143], v[156:159], v[124:127]
	v_mfma_f32_16x16x32_bf16 v[120:123], v[148:151], v[156:159], v[120:123]
	v_mfma_f32_16x16x32_bf16 v[116:119], v[140:143], v[194:197], v[116:119]
	v_mfma_f32_16x16x32_bf16 v[112:115], v[148:151], v[194:197], v[112:115]
	v_mfma_f32_16x16x32_bf16 v[108:111], v[140:143], v[202:205], v[108:111]
	v_mfma_f32_16x16x32_bf16 v[104:107], v[148:151], v[202:205], v[104:107]
	v_mfma_f32_16x16x32_bf16 v[100:103], v[140:143], v[210:213], v[100:103]
	v_mfma_f32_16x16x32_bf16 v[96:99], v[148:151], v[210:213], v[96:99]
	v_mfma_f32_16x16x32_bf16 v[124:127], v[144:147], v[160:163], v[124:127]
	v_mfma_f32_16x16x32_bf16 v[120:123], v[152:155], v[160:163], v[120:123]
	v_mfma_f32_16x16x32_bf16 v[116:119], v[144:147], v[198:201], v[116:119]
	v_mfma_f32_16x16x32_bf16 v[112:115], v[152:155], v[198:201], v[112:115]
	v_mfma_f32_16x16x32_bf16 v[108:111], v[144:147], v[206:209], v[108:111]
	v_mfma_f32_16x16x32_bf16 v[104:107], v[152:155], v[206:209], v[104:107]
	v_mfma_f32_16x16x32_bf16 v[100:103], v[144:147], v[214:217], v[100:103]
	v_mfma_f32_16x16x32_bf16 v[96:99], v[152:155], v[214:217], v[96:99]
	s_setprio 0
	s_barrier
	ds_read_b128 v[136:139], v135
	ds_read_b128 v[218:221], v135 offset:1024
	ds_read_b128 v[222:225], v135 offset:2048
	ds_read_b128 v[226:229], v135 offset:3072
	s_cmp_eq_u32 s99, 0
	s_cbranch_scc1 .Lxt5_s1
	s_add_i32 m0, s98, 0x10000
	s_nop 0
	global_load_lds_dwordx4 v[246:247], off
	s_mov_b64 s[100:101], 0x1000
	s_add_i32 m0, s98, 0x12000
	v_lshl_add_u64 v[250:251], v[246:247], 0, s[100:101]
	global_load_lds_dwordx4 v[250:251], off
	s_mov_b32 m0, s98
	s_nop 0
	global_load_lds_dwordx4 v[244:245], off
	s_mov_b64 s[100:101], 0x80000
	s_add_i32 m0, s98, 0x2000
	v_lshl_add_u64 v[250:251], v[244:245], 0, s[100:101]
	global_load_lds_dwordx4 v[250:251], off

.LBB0_274:
	ds_read_b128 v[162:165], v161
	ds_read_b128 v[166:169], v161 offset:1024
	ds_read_b128 v[170:173], v161 offset:2048
	ds_read_b128 v[174:177], v161 offset:3072
	ds_read_b128 v[178:181], v152
	ds_read_b128 v[182:185], v152 offset:1024
	ds_read_b128 v[186:189], v151
	ds_read_b128 v[190:193], v151 offset:1024
	ds_read_b128 v[194:197], v150
	ds_read_b128 v[198:201], v150 offset:1024
	ds_read_b128 v[202:205], v149
	ds_read_b128 v[206:209], v149 offset:1024
	s_waitcnt lgkmcnt(8)
	s_waitcnt vmcnt(10)
	s_barrier
	s_waitcnt lgkmcnt(0)
	s_waitcnt lgkmcnt(0)
	v_mfma_f32_16x16x32_bf16 v[124:127], v[162:165], v[178:181], v[124:127]
	v_mfma_f32_16x16x32_bf16 v[120:123], v[170:173], v[178:181], v[120:123]
	v_mfma_f32_16x16x32_bf16 v[116:119], v[162:165], v[186:189], v[116:119]
	v_mfma_f32_16x16x32_bf16 v[112:115], v[170:173], v[186:189], v[112:115]
	v_mfma_f32_16x16x32_bf16 v[108:111], v[162:165], v[194:197], v[108:111]
	v_mfma_f32_16x16x32_bf16 v[104:107], v[170:173], v[194:197], v[104:107]
	v_mfma_f32_16x16x32_bf16 v[100:103], v[162:165], v[202:205], v[100:103]
	v_mfma_f32_16x16x32_bf16 v[96:99], v[170:173], v[202:205], v[96:99]
	v_mfma_f32_16x16x32_bf16 v[124:127], v[166:169], v[182:185], v[124:127]
	v_mfma_f32_16x16x32_bf16 v[120:123], v[174:177], v[182:185], v[120:123]
	v_mfma_f32_16x16x32_bf16 v[116:119], v[166:169], v[190:193], v[116:119]
	v_mfma_f32_16x16x32_bf16 v[112:115], v[174:177], v[190:193], v[112:115]
	v_mfma_f32_16x16x32_bf16 v[108:111], v[166:169], v[198:201], v[108:111]
	v_mfma_f32_16x16x32_bf16 v[104:107], v[174:177], v[198:201], v[104:107]
	v_mfma_f32_16x16x32_bf16 v[100:103], v[166:169], v[206:209], v[100:103]
	v_mfma_f32_16x16x32_bf16 v[96:99], v[174:177], v[206:209], v[96:99]
	s_barrier
	s_mov_b32 vcc_lo, 0xfffbd000
	s_mov_b32 vcc_hi, -1
	s_add_i32 s67, s98, 0x10000
	v_lshl_add_u64 v[226:227], v[130:131], 0, vcc
	s_mov_b32 m0, s67
	s_add_i32 s67, s98, 0x12000
	ds_read_b128 v[210:213], v158
	ds_read_b128 v[214:217], v158 offset:1024
	ds_read_b128 v[218:221], v158 offset:2048
	ds_read_b128 v[222:225], v158 offset:3072
	global_load_lds_dwordx4 v[226:227], off
	v_lshl_add_u64 v[226:227], v[130:131], 0, s[22:23]
	s_mov_b32 m0, s67
	s_add_i32 s66, s66, 2
	global_load_lds_dwordx4 v[226:227], off
	s_mov_b32 s67, s98
	v_lshl_add_u64 v[226:227], v[132:133], 0, s[24:25]
	s_mov_b32 m0, s67
	s_add_i32 s67, s98, 0x2000
	global_load_lds_dwordx4 v[226:227], off
	v_lshl_add_u64 v[226:227], v[132:133], 0, s[26:27]
	s_mov_b32 m0, s67
	s_nop 0
	global_load_lds_dwordx4 v[226:227], off
	s_waitcnt vmcnt(12)
	s_barrier
	s_waitcnt lgkmcnt(0)
	s_waitcnt lgkmcnt(0)
	v_mfma_f32_16x16x32_bf16 v[92:95], v[210:213], v[178:181], v[92:95]
	v_mfma_f32_16x16x32_bf16 v[88:91], v[218:221], v[178:181], v[88:91]
	v_mfma_f32_16x16x32_bf16 v[84:87], v[210:213], v[186:189], v[84:87]
	v_mfma_f32_16x16x32_bf16 v[80:83], v[218:221], v[186:189], v[80:83]
	v_mfma_f32_16x16x32_bf16 v[76:79], v[210:213], v[194:197], v[76:79]
	v_mfma_f32_16x16x32_bf16 v[72:75], v[218:221], v[194:197], v[72:75]
	v_mfma_f32_16x16x32_bf16 v[68:71], v[210:213], v[202:205], v[68:71]
	v_mfma_f32_16x16x32_bf16 v[64:67], v[218:221], v[202:205], v[64:67]
	v_mfma_f32_16x16x32_bf16 v[92:95], v[214:217], v[182:185], v[92:95]
	v_mfma_f32_16x16x32_bf16 v[88:91], v[222:225], v[182:185], v[88:91]
	v_mfma_f32_16x16x32_bf16 v[84:87], v[214:217], v[190:193], v[84:87]
	v_mfma_f32_16x16x32_bf16 v[80:83], v[222:225], v[190:193], v[80:83]
	v_mfma_f32_16x16x32_bf16 v[76:79], v[214:217], v[198:201], v[76:79]
	v_mfma_f32_16x16x32_bf16 v[72:75], v[222:225], v[198:201], v[72:75]
	v_mfma_f32_16x16x32_bf16 v[68:71], v[214:217], v[206:209], v[68:71]
	v_mfma_f32_16x16x32_bf16 v[64:67], v[222:225], v[206:209], v[64:67]
	s_barrier
	ds_read_b128 v[178:181], v152 offset:16384
	ds_read_b128 v[182:185], v152 offset:17408
	ds_read_b128 v[186:189], v151 offset:16384
	ds_read_b128 v[190:193], v151 offset:17408
	ds_read_b128 v[194:197], v150 offset:16384
	ds_read_b128 v[198:201], v150 offset:17408
	ds_read_b128 v[202:205], v149 offset:16384
	ds_read_b128 v[206:209], v149 offset:17408
	s_add_i32 s67, s98, 0x14000
	v_lshl_add_u64 v[226:227], v[130:131], 0, s[28:29]
	s_mov_b32 m0, s67
	s_add_i32 s67, s98, 0x16000
	global_load_lds_dwordx4 v[226:227], off
	v_lshl_add_u64 v[226:227], v[130:131], 0, s[30:31]
	s_mov_b32 m0, s67
	s_nop 0
	global_load_lds_dwordx4 v[226:227], off
	s_barrier
	s_waitcnt lgkmcnt(0)
	s_waitcnt lgkmcnt(0)
	v_mfma_f32_16x16x32_bf16 v[60:63], v[162:165], v[178:181], v[60:63]
	v_mfma_f32_16x16x32_bf16 v[56:59], v[170:173], v[178:181], v[56:59]
	v_mfma_f32_16x16x32_bf16 v[52:55], v[162:165], v[186:189], v[52:55]
	v_mfma_f32_16x16x32_bf16 v[48:51], v[170:173], v[186:189], v[48:51]
	v_mfma_f32_16x16x32_bf16 v[44:47], v[162:165], v[194:197], v[44:47]
	v_mfma_f32_16x16x32_bf16 v[40:43], v[170:173], v[194:197], v[40:43]
	v_mfma_f32_16x16x32_bf16 v[36:39], v[162:165], v[202:205], v[36:39]
	v_mfma_f32_16x16x32_bf16 v[32:35], v[170:173], v[202:205], v[32:35]
	v_mfma_f32_16x16x32_bf16 v[60:63], v[166:169], v[182:185], v[60:63]
	v_mfma_f32_16x16x32_bf16 v[56:59], v[174:177], v[182:185], v[56:59]
	v_mfma_f32_16x16x32_bf16 v[52:55], v[166:169], v[190:193], v[52:55]
	v_mfma_f32_16x16x32_bf16 v[48:51], v[174:177], v[190:193], v[48:51]
	v_mfma_f32_16x16x32_bf16 v[44:47], v[166:169], v[198:201], v[44:47]
	v_mfma_f32_16x16x32_bf16 v[40:43], v[174:177], v[198:201], v[40:43]
	v_mfma_f32_16x16x32_bf16 v[36:39], v[166:169], v[206:209], v[36:39]
	v_mfma_f32_16x16x32_bf16 v[32:35], v[174:177], v[206:209], v[32:35]
	s_barrier
	s_add_i32 s67, s98, 0x4000
	v_lshl_add_u64 v[164:165], v[132:133], 0, s[34:35]
	s_mov_b32 m0, s67
	s_add_i32 s67, s98, 0x6000
	global_load_lds_dwordx4 v[164:165], off
	v_lshl_add_u64 v[164:165], v[132:133], 0, s[44:45]
	s_mov_b32 m0, s67
	s_nop 0
	global_load_lds_dwordx4 v[164:165], off
	s_waitcnt vmcnt(12)
	s_barrier
	v_mfma_f32_16x16x32_bf16 v[28:31], v[210:213], v[178:181], v[28:31]
	v_mfma_f32_16x16x32_bf16 v[24:27], v[218:221], v[178:181], v[24:27]
	v_mfma_f32_16x16x32_bf16 v[20:23], v[210:213], v[186:189], v[20:23]
	v_mfma_f32_16x16x32_bf16 v[16:19], v[218:221], v[186:189], v[16:19]
	v_mfma_f32_16x16x32_bf16 v[12:15], v[210:213], v[194:197], v[12:15]
	v_mfma_f32_16x16x32_bf16 v[8:11], v[218:221], v[194:197], v[8:11]
	v_mfma_f32_16x16x32_bf16 v[4:7], v[210:213], v[202:205], v[4:7]
	v_mfma_f32_16x16x32_bf16 v[0:3], v[218:221], v[202:205], v[0:3]
	v_mfma_f32_16x16x32_bf16 v[28:31], v[214:217], v[182:185], v[28:31]
	v_mfma_f32_16x16x32_bf16 v[24:27], v[222:225], v[182:185], v[24:27]
	v_mfma_f32_16x16x32_bf16 v[20:23], v[214:217], v[190:193], v[20:23]
	v_mfma_f32_16x16x32_bf16 v[16:19], v[222:225], v[190:193], v[16:19]
	v_mfma_f32_16x16x32_bf16 v[12:15], v[214:217], v[198:201], v[12:15]
	v_mfma_f32_16x16x32_bf16 v[8:11], v[222:225], v[198:201], v[8:11]
	v_mfma_f32_16x16x32_bf16 v[4:7], v[214:217], v[206:209], v[4:7]
	v_mfma_f32_16x16x32_bf16 v[0:3], v[222:225], v[206:209], v[0:3]
	s_barrier
	ds_read_b128 v[162:165], v154
	ds_read_b128 v[166:169], v154 offset:1024
	ds_read_b128 v[170:173], v154 offset:2048
	ds_read_b128 v[174:177], v154 offset:3072
	ds_read_b128 v[178:181], v152 offset:32768
	ds_read_b128 v[182:185], v152 offset:33792
	ds_read_b128 v[186:189], v151 offset:32768
	ds_read_b128 v[190:193], v151 offset:33792
	ds_read_b128 v[194:197], v150 offset:32768
	ds_read_b128 v[198:201], v150 offset:33792
	ds_read_b128 v[202:205], v149 offset:32768
	ds_read_b128 v[206:209], v149 offset:33792
	s_waitcnt lgkmcnt(8)
	s_waitcnt vmcnt(10)
	s_barrier
	s_waitcnt lgkmcnt(0)
	s_waitcnt lgkmcnt(0)
	v_mfma_f32_16x16x32_bf16 v[124:127], v[162:165], v[178:181], v[124:127]
	v_mfma_f32_16x16x32_bf16 v[120:123], v[170:173], v[178:181], v[120:123]
	v_mfma_f32_16x16x32_bf16 v[116:119], v[162:165], v[186:189], v[116:119]
	v_mfma_f32_16x16x32_bf16 v[112:115], v[170:173], v[186:189], v[112:115]
	v_mfma_f32_16x16x32_bf16 v[108:111], v[162:165], v[194:197], v[108:111]
	v_mfma_f32_16x16x32_bf16 v[104:107], v[170:173], v[194:197], v[104:107]
	v_mfma_f32_16x16x32_bf16 v[100:103], v[162:165], v[202:205], v[100:103]
	v_mfma_f32_16x16x32_bf16 v[96:99], v[170:173], v[202:205], v[96:99]
	v_mfma_f32_16x16x32_bf16 v[124:127], v[166:169], v[182:185], v[124:127]
	v_mfma_f32_16x16x32_bf16 v[120:123], v[174:177], v[182:185], v[120:123]
	v_mfma_f32_16x16x32_bf16 v[116:119], v[166:169], v[190:193], v[116:119]
	v_mfma_f32_16x16x32_bf16 v[112:115], v[174:177], v[190:193], v[112:115]
	v_mfma_f32_16x16x32_bf16 v[108:111], v[166:169], v[198:201], v[108:111]
	v_mfma_f32_16x16x32_bf16 v[104:107], v[174:177], v[198:201], v[104:107]
	v_mfma_f32_16x16x32_bf16 v[100:103], v[166:169], v[206:209], v[100:103]
	v_mfma_f32_16x16x32_bf16 v[96:99], v[174:177], v[206:209], v[96:99]
	s_barrier
	s_add_i32 s67, s98, 0x18000
	v_lshl_add_u64 v[226:227], v[130:131], 0, s[46:47]
	s_mov_b32 m0, s67
	s_add_i32 s67, s98, 0x1a000
	ds_read_b128 v[210:213], v153
	ds_read_b128 v[214:217], v153 offset:1024
	ds_read_b128 v[218:221], v153 offset:2048
	ds_read_b128 v[222:225], v153 offset:3072
	global_load_lds_dwordx4 v[226:227], off
	v_lshl_add_u64 v[226:227], v[130:131], 0, s[56:57]
	s_mov_b32 m0, s67
	s_nop 0
	global_load_lds_dwordx4 v[226:227], off
	s_add_i32 s67, s98, 0x8000
	v_lshl_add_u64 v[226:227], v[132:133], 0, s[58:59]
	s_mov_b32 m0, s67
	s_add_i32 s67, s98, 0xa000
	global_load_lds_dwordx4 v[226:227], off
	s_mov_b32 m0, s67
	s_nop 0
	global_load_lds_dwordx4 v[132:133], off
	s_waitcnt vmcnt(12)
	s_barrier
	s_waitcnt lgkmcnt(0)
	s_waitcnt lgkmcnt(0)
	v_mfma_f32_16x16x32_bf16 v[92:95], v[210:213], v[178:181], v[92:95]
	v_mfma_f32_16x16x32_bf16 v[88:91], v[218:221], v[178:181], v[88:91]
	v_mfma_f32_16x16x32_bf16 v[84:87], v[210:213], v[186:189], v[84:87]
	v_mfma_f32_16x16x32_bf16 v[80:83], v[218:221], v[186:189], v[80:83]
	v_mfma_f32_16x16x32_bf16 v[76:79], v[210:213], v[194:197], v[76:79]
	v_mfma_f32_16x16x32_bf16 v[72:75], v[218:221], v[194:197], v[72:75]
	v_mfma_f32_16x16x32_bf16 v[68:71], v[210:213], v[202:205], v[68:71]
	v_mfma_f32_16x16x32_bf16 v[64:67], v[218:221], v[202:205], v[64:67]
	v_mfma_f32_16x16x32_bf16 v[92:95], v[214:217], v[182:185], v[92:95]
	v_mfma_f32_16x16x32_bf16 v[88:91], v[222:225], v[182:185], v[88:91]
	v_mfma_f32_16x16x32_bf16 v[84:87], v[214:217], v[190:193], v[84:87]
	v_mfma_f32_16x16x32_bf16 v[80:83], v[222:225], v[190:193], v[80:83]
	v_mfma_f32_16x16x32_bf16 v[76:79], v[214:217], v[198:201], v[76:79]
	v_mfma_f32_16x16x32_bf16 v[72:75], v[222:225], v[198:201], v[72:75]
	v_mfma_f32_16x16x32_bf16 v[68:71], v[214:217], v[206:209], v[68:71]
	v_mfma_f32_16x16x32_bf16 v[64:67], v[222:225], v[206:209], v[64:67]
	s_barrier
	ds_read_b128 v[178:181], v152 offset:49152
	ds_read_b128 v[182:185], v152 offset:50176
	ds_read_b128 v[186:189], v151 offset:49152
	ds_read_b128 v[190:193], v151 offset:50176
	ds_read_b128 v[194:197], v150 offset:49152
	ds_read_b128 v[198:201], v150 offset:50176
	ds_read_b128 v[202:205], v149 offset:49152
	ds_read_b128 v[206:209], v149 offset:50176
	s_add_i32 s67, s98, 0x1c000
	v_lshl_add_u64 v[226:227], v[130:131], 0, s[58:59]
	s_mov_b32 m0, s67
	s_add_i32 s67, s98, 0x1e000
	global_load_lds_dwordx4 v[226:227], off
	s_mov_b32 m0, s67
	s_nop 0
	global_load_lds_dwordx4 v[130:131], off
	s_barrier
	s_waitcnt lgkmcnt(0)
	s_waitcnt lgkmcnt(0)
	v_mfma_f32_16x16x32_bf16 v[60:63], v[162:165], v[178:181], v[60:63]
	v_mfma_f32_16x16x32_bf16 v[56:59], v[170:173], v[178:181], v[56:59]
	v_mfma_f32_16x16x32_bf16 v[52:55], v[162:165], v[186:189], v[52:55]
	v_mfma_f32_16x16x32_bf16 v[48:51], v[170:173], v[186:189], v[48:51]
	v_mfma_f32_16x16x32_bf16 v[44:47], v[162:165], v[194:197], v[44:47]
	v_mfma_f32_16x16x32_bf16 v[40:43], v[170:173], v[194:197], v[40:43]
	v_mfma_f32_16x16x32_bf16 v[36:39], v[162:165], v[202:205], v[36:39]
	v_mfma_f32_16x16x32_bf16 v[32:35], v[170:173], v[202:205], v[32:35]
	v_mfma_f32_16x16x32_bf16 v[60:63], v[166:169], v[182:185], v[60:63]
	v_mfma_f32_16x16x32_bf16 v[56:59], v[174:177], v[182:185], v[56:59]
	v_mfma_f32_16x16x32_bf16 v[52:55], v[166:169], v[190:193], v[52:55]
	v_mfma_f32_16x16x32_bf16 v[48:51], v[174:177], v[190:193], v[48:51]
	v_mfma_f32_16x16x32_bf16 v[44:47], v[166:169], v[198:201], v[44:47]
	v_mfma_f32_16x16x32_bf16 v[40:43], v[174:177], v[198:201], v[40:43]
	v_mfma_f32_16x16x32_bf16 v[36:39], v[166:169], v[206:209], v[36:39]
	v_mfma_f32_16x16x32_bf16 v[32:35], v[174:177], v[206:209], v[32:35]
	s_barrier
	v_lshl_add_u64 v[132:133], v[132:133], 0, s[62:63]
	s_mov_b32 vcc_lo, 0xffe01000
	s_mov_b32 vcc_hi, -1
	v_lshl_add_u64 v[164:165], v[132:133], 0, vcc
	s_add_i32 s67, s98, 0xc000
	s_mov_b32 vcc_lo, 0xffe02000
	s_mov_b32 m0, s67
	s_mov_b32 vcc_hi, -1
	s_add_i32 s67, s98, 0xe000
	global_load_lds_dwordx4 v[164:165], off
	v_lshl_add_u64 v[164:165], v[132:133], 0, vcc
	s_mov_b32 m0, s67
	s_nop 0
	global_load_lds_dwordx4 v[164:165], off
	s_waitcnt vmcnt(12)
	s_barrier
	v_mfma_f32_16x16x32_bf16 v[28:31], v[210:213], v[178:181], v[28:31]
	v_mfma_f32_16x16x32_bf16 v[24:27], v[218:221], v[178:181], v[24:27]
	v_mfma_f32_16x16x32_bf16 v[20:23], v[210:213], v[186:189], v[20:23]
	v_mfma_f32_16x16x32_bf16 v[16:19], v[218:221], v[186:189], v[16:19]
	v_mfma_f32_16x16x32_bf16 v[12:15], v[210:213], v[194:197], v[12:15]
	v_mfma_f32_16x16x32_bf16 v[8:11], v[218:221], v[194:197], v[8:11]
	v_mfma_f32_16x16x32_bf16 v[4:7], v[210:213], v[202:205], v[4:7]
	v_mfma_f32_16x16x32_bf16 v[0:3], v[218:221], v[202:205], v[0:3]
	v_mfma_f32_16x16x32_bf16 v[28:31], v[214:217], v[182:185], v[28:31]
	v_mfma_f32_16x16x32_bf16 v[24:27], v[222:225], v[182:185], v[24:27]
	v_mfma_f32_16x16x32_bf16 v[20:23], v[214:217], v[190:193], v[20:23]
	v_mfma_f32_16x16x32_bf16 v[16:19], v[222:225], v[190:193], v[16:19]
	v_mfma_f32_16x16x32_bf16 v[12:15], v[214:217], v[198:201], v[12:15]
	v_mfma_f32_16x16x32_bf16 v[8:11], v[222:225], v[198:201], v[8:11]
	v_mfma_f32_16x16x32_bf16 v[4:7], v[214:217], v[206:209], v[4:7]
	v_mfma_f32_16x16x32_bf16 v[0:3], v[222:225], v[206:209], v[0:3]
	v_lshl_add_u64 v[130:131], v[130:131], 0, s[60:61]
	s_cmp_lt_u32 s66, s65
	s_barrier
	s_cbranch_scc1 .LBB0_274
	s_lshl_b32 s65, s86, 5
	s_lshl_b32 s66, s86, 8
	s_and_b32 s65, s65, 0x1800
	s_and_b32 s66, s66, 0x700
	s_or_b32 s97, s66, s65
	s_lshl_b32 s65, s97, 6
	s_add_u32 s65, s68, s65
	s_addc_u32 s86, s69, 0
	s_add_i32 s20, s20, -1
	s_lshl_b64 s[66:67], s[20:21], 20
	v_add_u32_e32 v128, v156, v157
	s_add_u32 s66, s65, s66
	v_or_b32_e32 v128, v128, v155
	s_addc_u32 s67, s86, s67
	v_lshl_add_u64 v[156:157], s[66:67], 0, v[128:129]
	v_readfirstlane_b32 s20, v160
	v_lshl_add_u64 v[206:207], v[156:157], 0, s[4:5]
	s_mov_b32 m0, s20
	v_readfirstlane_b32 s20, v159
	ds_read_b128 v[130:133], v161
	ds_read_b128 v[162:165], v161 offset:1024
	ds_read_b128 v[166:169], v161 offset:2048
	ds_read_b128 v[170:173], v161 offset:3072
	ds_read_b128 v[174:177], v152
	ds_read_b128 v[178:181], v152 offset:1024
	ds_read_b128 v[182:185], v151
	ds_read_b128 v[186:189], v151 offset:1024
	ds_read_b128 v[190:193], v150
	ds_read_b128 v[194:197], v150 offset:1024
	ds_read_b128 v[198:201], v149
	ds_read_b128 v[202:205], v149 offset:1024
	v_lshl_add_u64 v[156:157], v[156:157], 0, s[6:7]
	s_mov_b32 m0, s20
	s_nop 0
	s_waitcnt vmcnt(8)
	s_barrier
	s_waitcnt lgkmcnt(0)
	s_setprio 1
	s_waitcnt lgkmcnt(0)
	v_mfma_f32_16x16x32_bf16 v[124:127], v[130:133], v[174:177], v[124:127]
	v_mfma_f32_16x16x32_bf16 v[120:123], v[166:169], v[174:177], v[120:123]
	v_mfma_f32_16x16x32_bf16 v[116:119], v[130:133], v[182:185], v[116:119]
	v_mfma_f32_16x16x32_bf16 v[112:115], v[166:169], v[182:185], v[112:115]
	v_mfma_f32_16x16x32_bf16 v[108:111], v[130:133], v[190:193], v[108:111]
	v_mfma_f32_16x16x32_bf16 v[104:107], v[166:169], v[190:193], v[104:107]
	v_mfma_f32_16x16x32_bf16 v[100:103], v[130:133], v[198:201], v[100:103]
	v_mfma_f32_16x16x32_bf16 v[96:99], v[166:169], v[198:201], v[96:99]
	v_mfma_f32_16x16x32_bf16 v[124:127], v[162:165], v[178:181], v[124:127]
	v_mfma_f32_16x16x32_bf16 v[120:123], v[170:173], v[178:181], v[120:123]
	v_mfma_f32_16x16x32_bf16 v[116:119], v[162:165], v[186:189], v[116:119]
	v_mfma_f32_16x16x32_bf16 v[112:115], v[170:173], v[186:189], v[112:115]
	v_mfma_f32_16x16x32_bf16 v[108:111], v[162:165], v[194:197], v[108:111]
	v_mfma_f32_16x16x32_bf16 v[104:107], v[170:173], v[194:197], v[104:107]
	v_mfma_f32_16x16x32_bf16 v[100:103], v[162:165], v[202:205], v[100:103]
	v_mfma_f32_16x16x32_bf16 v[96:99], v[170:173], v[202:205], v[96:99]
	s_setprio 0
	s_barrier
	ds_read_b128 v[206:209], v158
	ds_read_b128 v[210:213], v158 offset:1024
	ds_read_b128 v[214:217], v158 offset:2048
	ds_read_b128 v[156:159], v158 offset:3072
	s_barrier
	s_waitcnt lgkmcnt(0)
	s_setprio 1
	s_waitcnt lgkmcnt(0)
	v_mfma_f32_16x16x32_bf16 v[92:95], v[206:209], v[174:177], v[92:95]
	v_mfma_f32_16x16x32_bf16 v[88:91], v[214:217], v[174:177], v[88:91]
	v_mfma_f32_16x16x32_bf16 v[84:87], v[206:209], v[182:185], v[84:87]
	v_mfma_f32_16x16x32_bf16 v[80:83], v[214:217], v[182:185], v[80:83]
	v_mfma_f32_16x16x32_bf16 v[76:79], v[206:209], v[190:193], v[76:79]
	v_mfma_f32_16x16x32_bf16 v[72:75], v[214:217], v[190:193], v[72:75]
	v_mfma_f32_16x16x32_bf16 v[68:71], v[206:209], v[198:201], v[68:71]
	v_mfma_f32_16x16x32_bf16 v[64:67], v[214:217], v[198:201], v[64:67]
	v_mfma_f32_16x16x32_bf16 v[174:177], v[210:213], v[178:181], v[92:95]
	v_mfma_f32_16x16x32_bf16 v[178:181], v[156:159], v[178:181], v[88:91]
	v_mfma_f32_16x16x32_bf16 v[182:185], v[210:213], v[186:189], v[84:87]
	v_mfma_f32_16x16x32_bf16 v[186:189], v[156:159], v[186:189], v[80:83]
	v_mfma_f32_16x16x32_bf16 v[190:193], v[210:213], v[194:197], v[76:79]
	v_mfma_f32_16x16x32_bf16 v[194:197], v[156:159], v[194:197], v[72:75]
	v_mfma_f32_16x16x32_bf16 v[198:201], v[210:213], v[202:205], v[68:71]
	v_mfma_f32_16x16x32_bf16 v[202:205], v[156:159], v[202:205], v[64:67]
	s_setprio 0
	s_barrier
	s_nop 0
	ds_read_b128 v[64:67], v152 offset:16384
	ds_read_b128 v[68:71], v152 offset:17408
	ds_read_b128 v[72:75], v151 offset:16384
	ds_read_b128 v[76:79], v151 offset:17408
	ds_read_b128 v[80:83], v150 offset:16384
	ds_read_b128 v[84:87], v150 offset:17408
	ds_read_b128 v[88:91], v149 offset:16384
	ds_read_b128 v[92:95], v149 offset:17408
	s_waitcnt vmcnt(4)
	s_barrier
	s_waitcnt lgkmcnt(0)
	s_setprio 1
	s_waitcnt lgkmcnt(0)
	v_mfma_f32_16x16x32_bf16 v[60:63], v[130:133], v[64:67], v[60:63]
	v_mfma_f32_16x16x32_bf16 v[56:59], v[166:169], v[64:67], v[56:59]
	v_mfma_f32_16x16x32_bf16 v[52:55], v[130:133], v[72:75], v[52:55]
	v_mfma_f32_16x16x32_bf16 v[48:51], v[166:169], v[72:75], v[48:51]
	v_mfma_f32_16x16x32_bf16 v[218:221], v[130:133], v[80:83], v[44:47]
	v_mfma_f32_16x16x32_bf16 v[222:225], v[166:169], v[80:83], v[40:43]
	v_mfma_f32_16x16x32_bf16 v[130:133], v[130:133], v[88:91], v[36:39]
	v_mfma_f32_16x16x32_bf16 v[166:169], v[166:169], v[88:91], v[32:35]
	v_mfma_f32_16x16x32_bf16 v[32:35], v[162:165], v[68:71], v[60:63]
	v_mfma_f32_16x16x32_bf16 v[36:39], v[170:173], v[68:71], v[56:59]
	v_mfma_f32_16x16x32_bf16 v[40:43], v[162:165], v[76:79], v[52:55]
	v_mfma_f32_16x16x32_bf16 v[44:47], v[170:173], v[76:79], v[48:51]
	v_mfma_f32_16x16x32_bf16 v[48:51], v[162:165], v[84:87], v[218:221]
	v_mfma_f32_16x16x32_bf16 v[52:55], v[170:173], v[84:87], v[222:225]
	v_mfma_f32_16x16x32_bf16 v[56:59], v[162:165], v[92:95], v[130:133]
	v_mfma_f32_16x16x32_bf16 v[60:63], v[170:173], v[92:95], v[166:169]
	s_setprio 0
	s_setprio 1
	v_mfma_f32_16x16x32_bf16 v[28:31], v[206:209], v[64:67], v[28:31]
	v_mfma_f32_16x16x32_bf16 v[24:27], v[214:217], v[64:67], v[24:27]
	v_mfma_f32_16x16x32_bf16 v[20:23], v[206:209], v[72:75], v[20:23]
	v_mfma_f32_16x16x32_bf16 v[64:67], v[214:217], v[72:75], v[16:19]
	v_mfma_f32_16x16x32_bf16 v[72:75], v[206:209], v[80:83], v[12:15]
	v_mfma_f32_16x16x32_bf16 v[8:11], v[214:217], v[80:83], v[8:11]
	v_mfma_f32_16x16x32_bf16 v[80:83], v[206:209], v[88:91], v[4:7]
	v_mfma_f32_16x16x32_bf16 v[0:3], v[214:217], v[88:91], v[0:3]
	v_mfma_f32_16x16x32_bf16 v[4:7], v[210:213], v[68:71], v[28:31]
	v_mfma_f32_16x16x32_bf16 v[12:15], v[156:159], v[68:71], v[24:27]
	v_mfma_f32_16x16x32_bf16 v[16:19], v[210:213], v[76:79], v[20:23]
	v_mfma_f32_16x16x32_bf16 v[20:23], v[156:159], v[76:79], v[64:67]
	v_mfma_f32_16x16x32_bf16 v[24:27], v[210:213], v[84:87], v[72:75]
	v_mfma_f32_16x16x32_bf16 v[28:31], v[156:159], v[84:87], v[8:11]
	v_mfma_f32_16x16x32_bf16 v[64:67], v[210:213], v[92:95], v[80:83]
	v_mfma_f32_16x16x32_bf16 v[68:71], v[156:159], v[92:95], v[0:3]
	s_setprio 0
	s_barrier
	ds_read_b128 v[8:11], v154
	ds_read_b128 v[0:3], v154 offset:1024
	ds_read_b128 v[76:79], v154 offset:2048
	ds_read_b128 v[72:75], v154 offset:3072
	ds_read_b128 v[130:133], v152 offset:32768
	ds_read_b128 v[154:157], v152 offset:33792
	ds_read_b128 v[158:161], v151 offset:32768
	ds_read_b128 v[162:165], v151 offset:33792
	ds_read_b128 v[166:169], v150 offset:32768
	ds_read_b128 v[170:173], v150 offset:33792
	ds_read_b128 v[206:209], v149 offset:32768
	ds_read_b128 v[210:213], v149 offset:33792
	s_waitcnt vmcnt(2)
	s_barrier
	s_waitcnt lgkmcnt(0)
	s_setprio 1
	s_waitcnt lgkmcnt(0)
	v_mfma_f32_16x16x32_bf16 v[80:83], v[8:11], v[130:133], v[124:127]
	v_mfma_f32_16x16x32_bf16 v[84:87], v[76:79], v[130:133], v[120:123]
	v_mfma_f32_16x16x32_bf16 v[88:91], v[8:11], v[158:161], v[116:119]
	v_mfma_f32_16x16x32_bf16 v[92:95], v[76:79], v[158:161], v[112:115]
	v_mfma_f32_16x16x32_bf16 v[108:111], v[8:11], v[166:169], v[108:111]
	v_mfma_f32_16x16x32_bf16 v[104:107], v[76:79], v[166:169], v[104:107]
	v_mfma_f32_16x16x32_bf16 v[100:103], v[8:11], v[206:209], v[100:103]
	v_mfma_f32_16x16x32_bf16 v[96:99], v[76:79], v[206:209], v[96:99]
	v_mfma_f32_16x16x32_bf16 v[112:115], v[0:3], v[154:157], v[80:83]
	v_mfma_f32_16x16x32_bf16 v[116:119], v[72:75], v[154:157], v[84:87]
	v_mfma_f32_16x16x32_bf16 v[120:123], v[0:3], v[162:165], v[88:91]
	v_mfma_f32_16x16x32_bf16 v[124:127], v[72:75], v[162:165], v[92:95]
	v_mfma_f32_16x16x32_bf16 v[108:111], v[0:3], v[170:173], v[108:111]
	v_mfma_f32_16x16x32_bf16 v[104:107], v[72:75], v[170:173], v[104:107]
	v_mfma_f32_16x16x32_bf16 v[100:103], v[0:3], v[210:213], v[100:103]
	v_mfma_f32_16x16x32_bf16 v[96:99], v[72:75], v[210:213], v[96:99]
	s_setprio 0
	s_barrier
	ds_read_b128 v[88:91], v153
	ds_read_b128 v[80:83], v153 offset:1024
	ds_read_b128 v[92:95], v153 offset:2048
	ds_read_b128 v[84:87], v153 offset:3072
	s_waitcnt vmcnt(0)
	s_barrier
	s_waitcnt lgkmcnt(0)
	s_setprio 1
	s_waitcnt lgkmcnt(0)
	v_mfma_f32_16x16x32_bf16 v[174:177], v[88:91], v[130:133], v[174:177]
	v_mfma_f32_16x16x32_bf16 v[130:133], v[92:95], v[130:133], v[178:181]
	v_mfma_f32_16x16x32_bf16 v[178:181], v[88:91], v[158:161], v[182:185]
	v_mfma_f32_16x16x32_bf16 v[158:161], v[92:95], v[158:161], v[186:189]
	v_mfma_f32_16x16x32_bf16 v[182:185], v[88:91], v[166:169], v[190:193]
	v_mfma_f32_16x16x32_bf16 v[166:169], v[92:95], v[166:169], v[194:197]
	v_mfma_f32_16x16x32_bf16 v[186:189], v[88:91], v[206:209], v[198:201]
	v_mfma_f32_16x16x32_bf16 v[190:193], v[92:95], v[206:209], v[202:205]
	v_mfma_f32_16x16x32_bf16 v[174:177], v[80:83], v[154:157], v[174:177]
	v_mfma_f32_16x16x32_bf16 v[130:133], v[84:87], v[154:157], v[130:133]
	v_mfma_f32_16x16x32_bf16 v[154:157], v[80:83], v[162:165], v[178:181]
	v_mfma_f32_16x16x32_bf16 v[158:161], v[84:87], v[162:165], v[158:161]
	v_mfma_f32_16x16x32_bf16 v[162:165], v[80:83], v[170:173], v[182:185]
	v_mfma_f32_16x16x32_bf16 v[166:169], v[84:87], v[170:173], v[166:169]
	v_mfma_f32_16x16x32_bf16 v[170:173], v[80:83], v[210:213], v[186:189]
	v_mfma_f32_16x16x32_bf16 v[178:181], v[84:87], v[210:213], v[190:193]
	s_setprio 0
	s_barrier
	v_mbcnt_lo_u32_b32 v128, -1, 0
	v_mbcnt_hi_u32_b32 v128, -1, v128
	v_cvt_pk_bf16_f32 v112, v112, v113
	v_cvt_pk_bf16_f32 v113, v114, v115
	v_cvt_pk_bf16_f32 v114, v116, v117
	v_cvt_pk_bf16_f32 v115, v118, v119
	s_lshl_b32 s89, s64, 9
	v_add_u32_e32 v153, s72, v128
	v_ashrrev_i32_e32 v182, 6, v153
	v_and_b32_e32 v183, 15, v128
	v_and_b32_e32 v184, 48, v128
	v_mul_lo_u32 v185, v182, s77
	v_bfe_u32 v186, v128, 3, 3
	v_lshlrev_b32_e32 v128, 4, v128
	v_add_u32_e32 v185, 0x20000, v185
	v_lshrrev_b32_e32 v153, 2, v153
	v_and_b32_e32 v128, 0x70, v128
	v_mul_u32_u24_e32 v183, 0x90, v183
	v_and_b32_e32 v153, 64, v153
	v_add3_u32 v183, v185, v183, v184
	v_or_b32_e32 v184, v185, v128
	v_or3_b32 v153, s97, v153, v186
	v_mad_u32_u24 v184, v186, s79, v184
	ds_write_b128 v183, v[112:115]
	v_cvt_pk_bf16_f32 v112, v174, v175
	v_cvt_pk_bf16_f32 v113, v176, v177
	v_cvt_pk_bf16_f32 v114, v130, v131
	v_cvt_pk_bf16_f32 v115, v132, v133
	ds_write_b128 v183, v[112:115] offset:64
	v_lshlrev_b32_e32 v182, 7, v182
	ds_read_b128 v[112:115], v184
	v_lshlrev_b32_e32 v116, 12, v153
	v_and_or_b32 v116, v182, s80, v116
	v_or3_b32 v128, v116, s89, v128
	ds_read_b128 v[116:119], v184 offset:1152
	v_lshl_add_u64 v[130:131], s[0:1], 0, v[128:129]
	s_mov_b32 s20, 0x8000
	s_waitcnt lgkmcnt(0)
	global_store_dwordx4 v128, v[112:115], s[0:1]
	v_cvt_pk_bf16_f32 v108, v108, v109
	v_cvt_pk_bf16_f32 v109, v110, v111
	v_cvt_pk_bf16_f32 v110, v104, v105
	v_cvt_pk_bf16_f32 v111, v106, v107
	v_cvt_pk_bf16_f32 v104, v162, v163
	s_nop 1
	v_add_co_u32_e32 v112, vcc, s20, v130
	v_cvt_pk_bf16_f32 v114, v124, v125
	v_cvt_pk_bf16_f32 v115, v126, v127
	v_cvt_pk_bf16_f32 v105, v164, v165
	v_cvt_pk_bf16_f32 v106, v166, v167
	s_nop 1
	v_addc_co_u32_e32 v113, vcc, 0, v131, vcc
	global_store_dwordx4 v[112:113], v[116:119], off
	v_cvt_pk_bf16_f32 v112, v120, v121
	v_cvt_pk_bf16_f32 v113, v122, v123
	ds_write_b128 v183, v[112:115]
	v_cvt_pk_bf16_f32 v112, v154, v155
	v_cvt_pk_bf16_f32 v113, v156, v157
	v_cvt_pk_bf16_f32 v114, v158, v159
	v_cvt_pk_bf16_f32 v115, v160, v161
	ds_write_b128 v183, v[112:115] offset:64
	ds_read_b128 v[112:115], v184
	ds_read_b128 v[116:119], v184 offset:1152
	v_add_co_u32_e32 v120, vcc, s74, v130
	ds_write_b128 v183, v[108:111]
	v_cvt_pk_bf16_f32 v107, v168, v169
	ds_write_b128 v183, v[104:107] offset:64
	v_addc_co_u32_e32 v121, vcc, 0, v131, vcc
	ds_read_b128 v[104:107], v184
	ds_read_b128 v[108:111], v184 offset:1152
	s_waitcnt lgkmcnt(0)
	global_store_dwordx4 v[120:121], v[112:115], off
	v_cvt_pk_bf16_f32 v100, v100, v101
	v_cvt_pk_bf16_f32 v101, v102, v103
	v_cvt_pk_bf16_f32 v102, v96, v97
	v_cvt_pk_bf16_f32 v103, v98, v99
	ds_write_b128 v183, v[100:103]
	s_nop 0
	v_add_co_u32_e32 v112, vcc, s75, v130
	v_cvt_pk_bf16_f32 v96, v170, v171
	v_cvt_pk_bf16_f32 v97, v172, v173
	v_cvt_pk_bf16_f32 v98, v178, v179
	v_cvt_pk_bf16_f32 v99, v180, v181
	s_nop 1
	v_addc_co_u32_e32 v113, vcc, 0, v131, vcc
	global_store_dwordx4 v[112:113], v[116:119], off
	v_add_co_u32_e32 v112, vcc, s78, v130
	ds_write_b128 v183, v[96:99] offset:64
	s_nop 0
	v_addc_co_u32_e32 v113, vcc, 0, v131, vcc
	ds_read_b128 v[96:99], v184
	ds_read_b128 v[100:103], v184 offset:1152
	global_store_dwordx4 v[112:113], v[104:107], off
	s_nop 1
	v_add_co_u32_e32 v104, vcc, s81, v130
	s_nop 1
	v_addc_co_u32_e32 v105, vcc, 0, v131, vcc
	global_store_dwordx4 v[104:105], v[108:111], off
	v_add_co_u32_e32 v104, vcc, s82, v130
	s_nop 1
	v_addc_co_u32_e32 v105, vcc, 0, v131, vcc
	s_waitcnt lgkmcnt(0)
	global_store_dwordx4 v[104:105], v[96:99], off
	s_nop 1
	v_add_co_u32_e32 v96, vcc, s83, v130
	s_nop 1
	v_addc_co_u32_e32 v97, vcc, 0, v131, vcc
	global_store_dwordx4 v[96:97], v[100:103], off
	ds_read_b128 v[96:99], v152 offset:49152
	ds_read_b128 v[100:103], v152 offset:50176
	ds_read_b128 v[104:107], v151 offset:49152
	ds_read_b128 v[108:111], v151 offset:50176
	ds_read_b128 v[112:115], v150 offset:49152
	ds_read_b128 v[116:119], v150 offset:50176
	ds_read_b128 v[120:123], v149 offset:49152
	ds_read_b128 v[124:127], v149 offset:50176
	s_barrier
	s_waitcnt lgkmcnt(0)
	s_setprio 1
	s_waitcnt lgkmcnt(0)
	v_mfma_f32_16x16x32_bf16 v[32:35], v[8:11], v[96:99], v[32:35]
	v_mfma_f32_16x16x32_bf16 v[36:39], v[76:79], v[96:99], v[36:39]
	v_mfma_f32_16x16x32_bf16 v[40:43], v[8:11], v[104:107], v[40:43]
	v_mfma_f32_16x16x32_bf16 v[130:133], v[76:79], v[104:107], v[44:47]
	v_mfma_f32_16x16x32_bf16 v[150:153], v[8:11], v[112:115], v[48:51]
	v_mfma_f32_16x16x32_bf16 v[52:55], v[76:79], v[112:115], v[52:55]
	v_mfma_f32_16x16x32_bf16 v[8:11], v[8:11], v[120:123], v[56:59]
	v_mfma_f32_16x16x32_bf16 v[60:63], v[76:79], v[120:123], v[60:63]
	v_mfma_f32_16x16x32_bf16 v[56:59], v[0:3], v[100:103], v[32:35]
	v_mfma_f32_16x16x32_bf16 v[48:51], v[72:75], v[100:103], v[36:39]
	v_mfma_f32_16x16x32_bf16 v[44:47], v[0:3], v[108:111], v[40:43]
	v_mfma_f32_16x16x32_bf16 v[40:43], v[72:75], v[108:111], v[130:133]
	v_mfma_f32_16x16x32_bf16 v[36:39], v[0:3], v[116:119], v[150:153]
	v_mfma_f32_16x16x32_bf16 v[32:35], v[72:75], v[116:119], v[52:55]
	v_mfma_f32_16x16x32_bf16 v[8:11], v[0:3], v[124:127], v[8:11]
	v_mfma_f32_16x16x32_bf16 v[0:3], v[72:75], v[124:127], v[60:63]
	s_setprio 0
	s_setprio 1
	v_mfma_f32_16x16x32_bf16 v[4:7], v[88:91], v[96:99], v[4:7]
	v_mfma_f32_16x16x32_bf16 v[12:15], v[92:95], v[96:99], v[12:15]
	v_mfma_f32_16x16x32_bf16 v[16:19], v[88:91], v[104:107], v[16:19]
	v_mfma_f32_16x16x32_bf16 v[20:23], v[92:95], v[104:107], v[20:23]
	v_mfma_f32_16x16x32_bf16 v[72:75], v[88:91], v[112:115], v[24:27]
	v_mfma_f32_16x16x32_bf16 v[76:79], v[92:95], v[112:115], v[28:31]
	v_mfma_f32_16x16x32_bf16 v[64:67], v[88:91], v[120:123], v[64:67]
	v_mfma_f32_16x16x32_bf16 v[68:71], v[92:95], v[120:123], v[68:71]
	v_mfma_f32_16x16x32_bf16 v[60:63], v[80:83], v[100:103], v[4:7]
	v_mfma_f32_16x16x32_bf16 v[52:55], v[84:87], v[100:103], v[12:15]
	v_mfma_f32_16x16x32_bf16 v[28:31], v[80:83], v[108:111], v[16:19]
	v_mfma_f32_16x16x32_bf16 v[24:27], v[84:87], v[108:111], v[20:23]
	v_mfma_f32_16x16x32_bf16 v[20:23], v[80:83], v[116:119], v[72:75]
	v_mfma_f32_16x16x32_bf16 v[16:19], v[84:87], v[116:119], v[76:79]
	v_mfma_f32_16x16x32_bf16 v[12:15], v[80:83], v[124:127], v[64:67]
	v_mfma_f32_16x16x32_bf16 v[4:7], v[84:87], v[124:127], v[68:71]
	s_setprio 0
	v_cmp_gt_u32_e32 vcc, s85, v135
	s_barrier
	s_and_saveexec_b64 s[64:65], vcc
	s_cbranch_execz .LBB0_277
	s_barrier

.LBB0_356:
	ds_read_b128 v[138:141], v134
	ds_read_b128 v[142:145], v134 offset:1024
	ds_read_b128 v[146:149], v134 offset:2048
	ds_read_b128 v[150:153], v134 offset:3072
	ds_read_b128 v[154:157], v187
	ds_read_b128 v[158:161], v187 offset:1024
	ds_read_b128 v[188:191], v186
	ds_read_b128 v[192:195], v186 offset:1024
	ds_read_b128 v[196:199], v185
	ds_read_b128 v[200:203], v185 offset:1024
	ds_read_b128 v[204:207], v184
	ds_read_b128 v[208:211], v184 offset:1024
	s_waitcnt lgkmcnt(8)
	s_waitcnt vmcnt(10)
	s_barrier
	s_waitcnt lgkmcnt(0)
	s_waitcnt lgkmcnt(0)
	v_mfma_f32_16x16x32_bf16 v[124:127], v[138:141], v[154:157], v[124:127]
	v_mfma_f32_16x16x32_bf16 v[120:123], v[146:149], v[154:157], v[120:123]
	v_mfma_f32_16x16x32_bf16 v[116:119], v[138:141], v[188:191], v[116:119]
	v_mfma_f32_16x16x32_bf16 v[112:115], v[146:149], v[188:191], v[112:115]
	v_mfma_f32_16x16x32_bf16 v[108:111], v[138:141], v[196:199], v[108:111]
	v_mfma_f32_16x16x32_bf16 v[104:107], v[146:149], v[196:199], v[104:107]
	v_mfma_f32_16x16x32_bf16 v[100:103], v[138:141], v[204:207], v[100:103]
	v_mfma_f32_16x16x32_bf16 v[96:99], v[146:149], v[204:207], v[96:99]
	v_mfma_f32_16x16x32_bf16 v[124:127], v[142:145], v[158:161], v[124:127]
	v_mfma_f32_16x16x32_bf16 v[120:123], v[150:153], v[158:161], v[120:123]
	v_mfma_f32_16x16x32_bf16 v[116:119], v[142:145], v[192:195], v[116:119]
	v_mfma_f32_16x16x32_bf16 v[112:115], v[150:153], v[192:195], v[112:115]
	v_mfma_f32_16x16x32_bf16 v[108:111], v[142:145], v[200:203], v[108:111]
	v_mfma_f32_16x16x32_bf16 v[104:107], v[150:153], v[200:203], v[104:107]
	v_mfma_f32_16x16x32_bf16 v[100:103], v[142:145], v[208:211], v[100:103]
	v_mfma_f32_16x16x32_bf16 v[96:99], v[150:153], v[208:211], v[96:99]
	s_barrier
	s_add_u32 s70, s18, 1
	s_addc_u32 s71, s19, 0
	s_lshl_b64 s[72:73], s[70:71], s22
	s_add_u32 s74, s17, s72
	s_addc_u32 s75, s29, s73
	v_lshl_add_u64 v[162:163], s[74:75], 0, v[128:129]
	s_add_i32 s23, s98, 0x10000
	s_add_u32 s74, s74, s25
	s_mov_b32 m0, s23
	s_addc_u32 s75, s75, 0
	s_add_i32 s23, s98, 0x12000
	ds_read_b128 v[212:215], v131
	ds_read_b128 v[216:219], v131 offset:1024
	ds_read_b128 v[220:223], v131 offset:2048
	ds_read_b128 v[224:227], v131 offset:3072
	global_load_lds_dwordx4 v[162:163], off
	v_lshl_add_u64 v[162:163], s[74:75], 0, v[128:129]
	s_mov_b32 m0, s23
	s_nop 0
	global_load_lds_dwordx4 v[162:163], off
	s_lshl_b64 s[70:71], s[70:71], s28
	s_add_u32 s74, s15, s70
	s_addc_u32 s75, s30, s71
	v_lshl_add_u64 v[162:163], s[74:75], 0, v[164:165]
	s_mov_b32 s23, s98
	s_add_u32 s74, s74, s24
	s_mov_b32 m0, s23
	s_addc_u32 s75, s75, 0
	s_add_i32 s23, s98, 0x2000
	global_load_lds_dwordx4 v[162:163], off
	v_lshl_add_u64 v[162:163], s[74:75], 0, v[164:165]
	s_mov_b32 m0, s23
	s_nop 0
	global_load_lds_dwordx4 v[162:163], off
	s_waitcnt vmcnt(12)
	s_barrier
	s_waitcnt lgkmcnt(0)
	s_waitcnt lgkmcnt(0)
	v_mfma_f32_16x16x32_bf16 v[92:95], v[212:215], v[154:157], v[92:95]
	v_mfma_f32_16x16x32_bf16 v[88:91], v[220:223], v[154:157], v[88:91]
	v_mfma_f32_16x16x32_bf16 v[84:87], v[212:215], v[188:191], v[84:87]
	v_mfma_f32_16x16x32_bf16 v[80:83], v[220:223], v[188:191], v[80:83]
	v_mfma_f32_16x16x32_bf16 v[76:79], v[212:215], v[196:199], v[76:79]
	v_mfma_f32_16x16x32_bf16 v[72:75], v[220:223], v[196:199], v[72:75]
	v_mfma_f32_16x16x32_bf16 v[68:71], v[212:215], v[204:207], v[68:71]
	v_mfma_f32_16x16x32_bf16 v[64:67], v[220:223], v[204:207], v[64:67]
	v_mfma_f32_16x16x32_bf16 v[92:95], v[216:219], v[158:161], v[92:95]
	v_mfma_f32_16x16x32_bf16 v[88:91], v[224:227], v[158:161], v[88:91]
	v_mfma_f32_16x16x32_bf16 v[84:87], v[216:219], v[192:195], v[84:87]
	v_mfma_f32_16x16x32_bf16 v[80:83], v[224:227], v[192:195], v[80:83]
	v_mfma_f32_16x16x32_bf16 v[76:79], v[216:219], v[200:203], v[76:79]
	v_mfma_f32_16x16x32_bf16 v[72:75], v[224:227], v[200:203], v[72:75]
	v_mfma_f32_16x16x32_bf16 v[68:71], v[216:219], v[208:211], v[68:71]
	v_mfma_f32_16x16x32_bf16 v[64:67], v[224:227], v[208:211], v[64:67]
	s_barrier
	ds_read_b128 v[154:157], v187 offset:16384
	ds_read_b128 v[158:161], v187 offset:17408
	ds_read_b128 v[188:191], v186 offset:16384
	ds_read_b128 v[192:195], v186 offset:17408
	ds_read_b128 v[196:199], v185 offset:16384
	ds_read_b128 v[200:203], v185 offset:17408
	ds_read_b128 v[204:207], v184 offset:16384
	ds_read_b128 v[208:211], v184 offset:17408
	s_add_u32 s72, s20, s72
	s_addc_u32 s73, s21, s73
	v_lshl_add_u64 v[162:163], s[72:73], 0, v[128:129]
	s_add_i32 s23, s98, 0x14000
	s_add_u32 s72, s72, s25
	s_mov_b32 m0, s23
	s_addc_u32 s73, s73, 0
	s_add_i32 s23, s98, 0x16000
	global_load_lds_dwordx4 v[162:163], off
	v_lshl_add_u64 v[162:163], s[72:73], 0, v[128:129]
	s_mov_b32 m0, s23
	s_nop 0
	global_load_lds_dwordx4 v[162:163], off
	s_barrier
	s_waitcnt lgkmcnt(0)
	s_waitcnt lgkmcnt(0)
	v_mfma_f32_16x16x32_bf16 v[60:63], v[138:141], v[154:157], v[60:63]
	v_mfma_f32_16x16x32_bf16 v[56:59], v[146:149], v[154:157], v[56:59]
	v_mfma_f32_16x16x32_bf16 v[52:55], v[138:141], v[188:191], v[52:55]
	v_mfma_f32_16x16x32_bf16 v[48:51], v[146:149], v[188:191], v[48:51]
	v_mfma_f32_16x16x32_bf16 v[44:47], v[138:141], v[196:199], v[44:47]
	v_mfma_f32_16x16x32_bf16 v[40:43], v[146:149], v[196:199], v[40:43]
	v_mfma_f32_16x16x32_bf16 v[36:39], v[138:141], v[204:207], v[36:39]
	v_mfma_f32_16x16x32_bf16 v[32:35], v[146:149], v[204:207], v[32:35]
	v_mfma_f32_16x16x32_bf16 v[60:63], v[142:145], v[158:161], v[60:63]
	v_mfma_f32_16x16x32_bf16 v[56:59], v[150:153], v[158:161], v[56:59]
	v_mfma_f32_16x16x32_bf16 v[52:55], v[142:145], v[192:195], v[52:55]
	v_mfma_f32_16x16x32_bf16 v[48:51], v[150:153], v[192:195], v[48:51]
	v_mfma_f32_16x16x32_bf16 v[44:47], v[142:145], v[200:203], v[44:47]
	v_mfma_f32_16x16x32_bf16 v[40:43], v[150:153], v[200:203], v[40:43]
	v_mfma_f32_16x16x32_bf16 v[36:39], v[142:145], v[208:211], v[36:39]
	v_mfma_f32_16x16x32_bf16 v[32:35], v[150:153], v[208:211], v[32:35]
	s_barrier
	s_add_u32 s70, s26, s70
	s_addc_u32 s71, s27, s71
	v_lshl_add_u64 v[162:163], s[70:71], 0, v[164:165]
	s_add_i32 s23, s98, 0x4000
	s_add_u32 s70, s70, s24
	s_mov_b32 m0, s23
	s_addc_u32 s71, s71, 0
	s_add_i32 s23, s98, 0x6000
	global_load_lds_dwordx4 v[162:163], off
	v_lshl_add_u64 v[162:163], s[70:71], 0, v[164:165]
	s_mov_b32 m0, s23
	s_nop 0
	global_load_lds_dwordx4 v[162:163], off
	s_waitcnt vmcnt(12)
	s_barrier
	v_mfma_f32_16x16x32_bf16 v[28:31], v[212:215], v[154:157], v[28:31]
	v_mfma_f32_16x16x32_bf16 v[24:27], v[220:223], v[154:157], v[24:27]
	v_mfma_f32_16x16x32_bf16 v[20:23], v[212:215], v[188:191], v[20:23]
	v_mfma_f32_16x16x32_bf16 v[16:19], v[220:223], v[188:191], v[16:19]
	v_mfma_f32_16x16x32_bf16 v[12:15], v[212:215], v[196:199], v[12:15]
	v_mfma_f32_16x16x32_bf16 v[8:11], v[220:223], v[196:199], v[8:11]
	v_mfma_f32_16x16x32_bf16 v[4:7], v[212:215], v[204:207], v[4:7]
	v_mfma_f32_16x16x32_bf16 v[0:3], v[220:223], v[204:207], v[0:3]
	v_mfma_f32_16x16x32_bf16 v[28:31], v[216:219], v[158:161], v[28:31]
	v_mfma_f32_16x16x32_bf16 v[24:27], v[224:227], v[158:161], v[24:27]
	v_mfma_f32_16x16x32_bf16 v[20:23], v[216:219], v[192:195], v[20:23]
	v_mfma_f32_16x16x32_bf16 v[16:19], v[224:227], v[192:195], v[16:19]
	v_mfma_f32_16x16x32_bf16 v[12:15], v[216:219], v[200:203], v[12:15]
	v_mfma_f32_16x16x32_bf16 v[8:11], v[224:227], v[200:203], v[8:11]
	v_mfma_f32_16x16x32_bf16 v[4:7], v[216:219], v[208:211], v[4:7]
	v_mfma_f32_16x16x32_bf16 v[0:3], v[224:227], v[208:211], v[0:3]
	s_barrier
	ds_read_b128 v[138:141], v130
	ds_read_b128 v[142:145], v130 offset:1024
	ds_read_b128 v[146:149], v130 offset:2048
	ds_read_b128 v[150:153], v130 offset:3072
	ds_read_b128 v[154:157], v187 offset:32768
	ds_read_b128 v[158:161], v187 offset:33792
	ds_read_b128 v[188:191], v186 offset:32768
	ds_read_b128 v[192:195], v186 offset:33792
	ds_read_b128 v[196:199], v185 offset:32768
	ds_read_b128 v[200:203], v185 offset:33792
	ds_read_b128 v[204:207], v184 offset:32768
	ds_read_b128 v[208:211], v184 offset:33792
	s_waitcnt lgkmcnt(8)
	s_waitcnt vmcnt(10)
	s_barrier
	s_waitcnt lgkmcnt(0)
	s_waitcnt lgkmcnt(0)
	v_mfma_f32_16x16x32_bf16 v[124:127], v[138:141], v[154:157], v[124:127]
	v_mfma_f32_16x16x32_bf16 v[120:123], v[146:149], v[154:157], v[120:123]
	v_mfma_f32_16x16x32_bf16 v[116:119], v[138:141], v[188:191], v[116:119]
	v_mfma_f32_16x16x32_bf16 v[112:115], v[146:149], v[188:191], v[112:115]
	v_mfma_f32_16x16x32_bf16 v[108:111], v[138:141], v[196:199], v[108:111]
	v_mfma_f32_16x16x32_bf16 v[104:107], v[146:149], v[196:199], v[104:107]
	v_mfma_f32_16x16x32_bf16 v[100:103], v[138:141], v[204:207], v[100:103]
	v_mfma_f32_16x16x32_bf16 v[96:99], v[146:149], v[204:207], v[96:99]
	v_mfma_f32_16x16x32_bf16 v[124:127], v[142:145], v[158:161], v[124:127]
	v_mfma_f32_16x16x32_bf16 v[120:123], v[150:153], v[158:161], v[120:123]
	v_mfma_f32_16x16x32_bf16 v[116:119], v[142:145], v[192:195], v[116:119]
	v_mfma_f32_16x16x32_bf16 v[112:115], v[150:153], v[192:195], v[112:115]
	v_mfma_f32_16x16x32_bf16 v[108:111], v[142:145], v[200:203], v[108:111]
	v_mfma_f32_16x16x32_bf16 v[104:107], v[150:153], v[200:203], v[104:107]
	v_mfma_f32_16x16x32_bf16 v[100:103], v[142:145], v[208:211], v[100:103]
	v_mfma_f32_16x16x32_bf16 v[96:99], v[150:153], v[208:211], v[96:99]
	s_barrier
	s_add_u32 s18, s18, 2
	s_addc_u32 s19, s19, 0
	s_lshl_b64 s[70:71], s[18:19], s22
	s_add_u32 s72, s17, s70
	s_addc_u32 s73, s29, s71
	v_lshl_add_u64 v[162:163], s[72:73], 0, v[128:129]
	s_add_i32 s23, s98, 0x18000
	s_add_u32 s72, s72, s25
	s_mov_b32 m0, s23
	s_addc_u32 s73, s73, 0
	s_add_i32 s23, s98, 0x1a000
	ds_read_b128 v[212:215], v136
	ds_read_b128 v[216:219], v136 offset:1024
	ds_read_b128 v[220:223], v136 offset:2048
	ds_read_b128 v[224:227], v136 offset:3072
	global_load_lds_dwordx4 v[162:163], off
	v_lshl_add_u64 v[162:163], s[72:73], 0, v[128:129]
	s_mov_b32 m0, s23
	s_nop 0
	global_load_lds_dwordx4 v[162:163], off
	s_lshl_b64 s[72:73], s[18:19], s28
	s_add_u32 s72, s15, s72
	s_addc_u32 s73, s30, s73
	v_lshl_add_u64 v[162:163], s[72:73], 0, v[164:165]
	s_add_i32 s23, s98, 0x8000
	s_add_u32 s72, s72, s24
	s_mov_b32 m0, s23
	s_addc_u32 s73, s73, 0
	s_add_i32 s23, s98, 0xa000
	global_load_lds_dwordx4 v[162:163], off
	v_lshl_add_u64 v[162:163], s[72:73], 0, v[164:165]
	s_mov_b32 m0, s23
	s_nop 0
	global_load_lds_dwordx4 v[162:163], off
	s_waitcnt vmcnt(12)
	s_barrier
	s_waitcnt lgkmcnt(0)
	s_waitcnt lgkmcnt(0)
	v_mfma_f32_16x16x32_bf16 v[92:95], v[212:215], v[154:157], v[92:95]
	v_mfma_f32_16x16x32_bf16 v[88:91], v[220:223], v[154:157], v[88:91]
	v_mfma_f32_16x16x32_bf16 v[84:87], v[212:215], v[188:191], v[84:87]
	v_mfma_f32_16x16x32_bf16 v[80:83], v[220:223], v[188:191], v[80:83]
	v_mfma_f32_16x16x32_bf16 v[76:79], v[212:215], v[196:199], v[76:79]
	v_mfma_f32_16x16x32_bf16 v[72:75], v[220:223], v[196:199], v[72:75]
	v_mfma_f32_16x16x32_bf16 v[68:71], v[212:215], v[204:207], v[68:71]
	v_mfma_f32_16x16x32_bf16 v[64:67], v[220:223], v[204:207], v[64:67]
	v_mfma_f32_16x16x32_bf16 v[92:95], v[216:219], v[158:161], v[92:95]
	v_mfma_f32_16x16x32_bf16 v[88:91], v[224:227], v[158:161], v[88:91]
	v_mfma_f32_16x16x32_bf16 v[84:87], v[216:219], v[192:195], v[84:87]
	v_mfma_f32_16x16x32_bf16 v[80:83], v[224:227], v[192:195], v[80:83]
	v_mfma_f32_16x16x32_bf16 v[76:79], v[216:219], v[200:203], v[76:79]
	v_mfma_f32_16x16x32_bf16 v[72:75], v[224:227], v[200:203], v[72:75]
	v_mfma_f32_16x16x32_bf16 v[68:71], v[216:219], v[208:211], v[68:71]
	v_mfma_f32_16x16x32_bf16 v[64:67], v[224:227], v[208:211], v[64:67]
	s_barrier
	ds_read_b128 v[154:157], v187 offset:49152
	ds_read_b128 v[158:161], v187 offset:50176
	ds_read_b128 v[188:191], v186 offset:49152
	ds_read_b128 v[192:195], v186 offset:50176
	ds_read_b128 v[196:199], v185 offset:49152
	ds_read_b128 v[200:203], v185 offset:50176
	ds_read_b128 v[204:207], v184 offset:49152
	ds_read_b128 v[208:211], v184 offset:50176
	s_add_u32 s70, s20, s70
	s_addc_u32 s71, s21, s71
	v_lshl_add_u64 v[162:163], s[70:71], 0, v[128:129]
	s_add_i32 s23, s98, 0x1c000
	s_add_u32 s70, s70, s25
	s_mov_b32 m0, s23
	s_addc_u32 s71, s71, 0
	s_add_i32 s23, s98, 0x1e000
	global_load_lds_dwordx4 v[162:163], off
	v_lshl_add_u64 v[162:163], s[70:71], 0, v[128:129]
	s_mov_b32 m0, s23
	s_nop 0
	global_load_lds_dwordx4 v[162:163], off
	s_barrier
	s_waitcnt lgkmcnt(0)
	s_waitcnt lgkmcnt(0)
	v_mfma_f32_16x16x32_bf16 v[60:63], v[138:141], v[154:157], v[60:63]
	v_mfma_f32_16x16x32_bf16 v[56:59], v[146:149], v[154:157], v[56:59]
	v_mfma_f32_16x16x32_bf16 v[52:55], v[138:141], v[188:191], v[52:55]
	v_mfma_f32_16x16x32_bf16 v[48:51], v[146:149], v[188:191], v[48:51]
	v_mfma_f32_16x16x32_bf16 v[44:47], v[138:141], v[196:199], v[44:47]
	v_mfma_f32_16x16x32_bf16 v[40:43], v[146:149], v[196:199], v[40:43]
	v_mfma_f32_16x16x32_bf16 v[36:39], v[138:141], v[204:207], v[36:39]
	v_mfma_f32_16x16x32_bf16 v[32:35], v[146:149], v[204:207], v[32:35]
	v_mfma_f32_16x16x32_bf16 v[60:63], v[142:145], v[158:161], v[60:63]
	v_mfma_f32_16x16x32_bf16 v[56:59], v[150:153], v[158:161], v[56:59]
	v_mfma_f32_16x16x32_bf16 v[52:55], v[142:145], v[192:195], v[52:55]
	v_mfma_f32_16x16x32_bf16 v[48:51], v[150:153], v[192:195], v[48:51]
	v_mfma_f32_16x16x32_bf16 v[44:47], v[142:145], v[200:203], v[44:47]
	v_mfma_f32_16x16x32_bf16 v[40:43], v[150:153], v[200:203], v[40:43]
	v_mfma_f32_16x16x32_bf16 v[36:39], v[142:145], v[208:211], v[36:39]
	v_mfma_f32_16x16x32_bf16 v[32:35], v[150:153], v[208:211], v[32:35]
	s_barrier
	s_lshl_b64 s[70:71], s[18:19], s28
	s_add_u32 s70, s26, s70
	s_addc_u32 s71, s27, s71
	v_lshl_add_u64 v[162:163], s[70:71], 0, v[164:165]
	s_add_i32 s23, s98, 0xc000
	s_add_u32 s70, s70, s24
	s_mov_b32 m0, s23
	s_addc_u32 s71, s71, 0
	s_add_i32 s23, s98, 0xe000
	global_load_lds_dwordx4 v[162:163], off
	v_lshl_add_u64 v[162:163], s[70:71], 0, v[164:165]
	s_mov_b32 m0, s23
	s_nop 0
	global_load_lds_dwordx4 v[162:163], off
	s_waitcnt vmcnt(12)
	s_barrier
	v_mfma_f32_16x16x32_bf16 v[28:31], v[212:215], v[154:157], v[28:31]
	v_mfma_f32_16x16x32_bf16 v[24:27], v[220:223], v[154:157], v[24:27]
	v_mfma_f32_16x16x32_bf16 v[20:23], v[212:215], v[188:191], v[20:23]
	v_mfma_f32_16x16x32_bf16 v[16:19], v[220:223], v[188:191], v[16:19]
	v_mfma_f32_16x16x32_bf16 v[12:15], v[212:215], v[196:199], v[12:15]
	v_mfma_f32_16x16x32_bf16 v[8:11], v[220:223], v[196:199], v[8:11]
	v_mfma_f32_16x16x32_bf16 v[4:7], v[212:215], v[204:207], v[4:7]
	v_mfma_f32_16x16x32_bf16 v[0:3], v[220:223], v[204:207], v[0:3]
	v_mfma_f32_16x16x32_bf16 v[28:31], v[216:219], v[158:161], v[28:31]
	v_mfma_f32_16x16x32_bf16 v[24:27], v[224:227], v[158:161], v[24:27]
	v_mfma_f32_16x16x32_bf16 v[20:23], v[216:219], v[192:195], v[20:23]
	v_mfma_f32_16x16x32_bf16 v[16:19], v[224:227], v[192:195], v[16:19]
	v_mfma_f32_16x16x32_bf16 v[12:15], v[216:219], v[200:203], v[12:15]
	v_mfma_f32_16x16x32_bf16 v[8:11], v[224:227], v[200:203], v[8:11]
	v_mfma_f32_16x16x32_bf16 v[4:7], v[216:219], v[208:211], v[4:7]
	v_mfma_f32_16x16x32_bf16 v[0:3], v[224:227], v[208:211], v[0:3]
	s_add_i32 s23, s18, -3
	s_cmp_lt_u32 s23, 28
	s_barrier
	s_cbranch_scc1 .LBB0_356
	s_lshl_b64 s[18:19], 31, s28
	s_add_u32 s18, s26, s18
	s_addc_u32 s19, s27, s19
	v_lshl_add_u64 v[128:129], s[18:19], 0, v[164:165]
	v_readfirstlane_b32 s15, v133
	s_add_u32 s18, s18, s24
	s_mov_b32 m0, s15
	s_addc_u32 s19, s19, 0
	v_readfirstlane_b32 s15, v132
	ds_read_b128 v[138:141], v134
	ds_read_b128 v[142:145], v134 offset:1024
	ds_read_b128 v[146:149], v134 offset:2048
	ds_read_b128 v[150:153], v134 offset:3072
	ds_read_b128 v[154:157], v187
	ds_read_b128 v[158:161], v187 offset:1024
	ds_read_b128 v[188:191], v186
	ds_read_b128 v[192:195], v186 offset:1024
	ds_read_b128 v[196:199], v185
	ds_read_b128 v[200:203], v185 offset:1024
	ds_read_b128 v[204:207], v184
	ds_read_b128 v[208:211], v184 offset:1024
	v_lshl_add_u64 v[128:129], s[18:19], 0, v[164:165]
	s_mov_b32 m0, s15
	s_nop 0
	s_waitcnt vmcnt(8)
	s_barrier
	s_waitcnt lgkmcnt(0)
	s_setprio 1
	s_waitcnt lgkmcnt(0)
	v_mfma_f32_16x16x32_bf16 v[124:127], v[138:141], v[154:157], v[124:127]
	v_mfma_f32_16x16x32_bf16 v[120:123], v[146:149], v[154:157], v[120:123]
	v_mfma_f32_16x16x32_bf16 v[116:119], v[138:141], v[188:191], v[116:119]
	v_mfma_f32_16x16x32_bf16 v[112:115], v[146:149], v[188:191], v[112:115]
	v_mfma_f32_16x16x32_bf16 v[108:111], v[138:141], v[196:199], v[108:111]
	v_mfma_f32_16x16x32_bf16 v[104:107], v[146:149], v[196:199], v[104:107]
	v_mfma_f32_16x16x32_bf16 v[100:103], v[138:141], v[204:207], v[100:103]
	v_mfma_f32_16x16x32_bf16 v[96:99], v[146:149], v[204:207], v[96:99]
	v_mfma_f32_16x16x32_bf16 v[124:127], v[142:145], v[158:161], v[124:127]
	v_mfma_f32_16x16x32_bf16 v[120:123], v[150:153], v[158:161], v[120:123]
	v_mfma_f32_16x16x32_bf16 v[116:119], v[142:145], v[192:195], v[116:119]
	v_mfma_f32_16x16x32_bf16 v[112:115], v[150:153], v[192:195], v[112:115]
	v_mfma_f32_16x16x32_bf16 v[108:111], v[142:145], v[200:203], v[108:111]
	v_mfma_f32_16x16x32_bf16 v[104:107], v[150:153], v[200:203], v[104:107]
	v_mfma_f32_16x16x32_bf16 v[100:103], v[142:145], v[208:211], v[100:103]
	v_mfma_f32_16x16x32_bf16 v[96:99], v[150:153], v[208:211], v[96:99]
	s_setprio 0
	s_barrier
	ds_read_b128 v[132:135], v131
	ds_read_b128 v[212:215], v131 offset:1024
	ds_read_b128 v[216:219], v131 offset:2048
	ds_read_b128 v[220:223], v131 offset:3072
	s_barrier
	s_waitcnt lgkmcnt(0)
	s_setprio 1
	s_waitcnt lgkmcnt(0)
	v_mfma_f32_16x16x32_bf16 v[92:95], v[132:135], v[154:157], v[92:95]
	v_mfma_f32_16x16x32_bf16 v[88:91], v[216:219], v[154:157], v[88:91]
	v_mfma_f32_16x16x32_bf16 v[84:87], v[132:135], v[188:191], v[84:87]
	v_mfma_f32_16x16x32_bf16 v[80:83], v[216:219], v[188:191], v[80:83]
	v_mfma_f32_16x16x32_bf16 v[76:79], v[132:135], v[196:199], v[76:79]
	v_mfma_f32_16x16x32_bf16 v[72:75], v[216:219], v[196:199], v[72:75]
	v_mfma_f32_16x16x32_bf16 v[68:71], v[132:135], v[204:207], v[68:71]
	v_mfma_f32_16x16x32_bf16 v[64:67], v[216:219], v[204:207], v[64:67]
	v_mfma_f32_16x16x32_bf16 v[154:157], v[212:215], v[158:161], v[92:95]
	v_mfma_f32_16x16x32_bf16 v[158:161], v[220:223], v[158:161], v[88:91]
	v_mfma_f32_16x16x32_bf16 v[188:191], v[212:215], v[192:195], v[84:87]
	v_mfma_f32_16x16x32_bf16 v[192:195], v[220:223], v[192:195], v[80:83]
	v_mfma_f32_16x16x32_bf16 v[196:199], v[212:215], v[200:203], v[76:79]
	v_mfma_f32_16x16x32_bf16 v[200:203], v[220:223], v[200:203], v[72:75]
	v_mfma_f32_16x16x32_bf16 v[204:207], v[212:215], v[208:211], v[68:71]
	v_mfma_f32_16x16x32_bf16 v[208:211], v[220:223], v[208:211], v[64:67]
	s_setprio 0
	s_barrier
	s_nop 0
	ds_read_b128 v[64:67], v187 offset:16384
	ds_read_b128 v[68:71], v187 offset:17408
	ds_read_b128 v[72:75], v186 offset:16384
	ds_read_b128 v[76:79], v186 offset:17408
	ds_read_b128 v[80:83], v185 offset:16384
	ds_read_b128 v[84:87], v185 offset:17408
	ds_read_b128 v[88:91], v184 offset:16384
	ds_read_b128 v[92:95], v184 offset:17408
	s_waitcnt vmcnt(4)
	s_barrier
	s_waitcnt lgkmcnt(0)
	s_setprio 1
	s_waitcnt lgkmcnt(0)
	v_mfma_f32_16x16x32_bf16 v[60:63], v[138:141], v[64:67], v[60:63]
	v_mfma_f32_16x16x32_bf16 v[56:59], v[146:149], v[64:67], v[56:59]
	v_mfma_f32_16x16x32_bf16 v[52:55], v[138:141], v[72:75], v[52:55]
	v_mfma_f32_16x16x32_bf16 v[48:51], v[146:149], v[72:75], v[48:51]
	v_mfma_f32_16x16x32_bf16 v[224:227], v[138:141], v[80:83], v[44:47]
	v_mfma_f32_16x16x32_bf16 v[228:231], v[146:149], v[80:83], v[40:43]
	v_mfma_f32_16x16x32_bf16 v[138:141], v[138:141], v[88:91], v[36:39]
	v_mfma_f32_16x16x32_bf16 v[146:149], v[146:149], v[88:91], v[32:35]
	v_mfma_f32_16x16x32_bf16 v[32:35], v[142:145], v[68:71], v[60:63]
	v_mfma_f32_16x16x32_bf16 v[36:39], v[150:153], v[68:71], v[56:59]
	v_mfma_f32_16x16x32_bf16 v[40:43], v[142:145], v[76:79], v[52:55]
	v_mfma_f32_16x16x32_bf16 v[44:47], v[150:153], v[76:79], v[48:51]
	v_mfma_f32_16x16x32_bf16 v[48:51], v[142:145], v[84:87], v[224:227]
	v_mfma_f32_16x16x32_bf16 v[52:55], v[150:153], v[84:87], v[228:231]
	v_mfma_f32_16x16x32_bf16 v[56:59], v[142:145], v[92:95], v[138:141]
	v_mfma_f32_16x16x32_bf16 v[60:63], v[150:153], v[92:95], v[146:149]
	s_setprio 0
	s_setprio 1
	v_mfma_f32_16x16x32_bf16 v[28:31], v[132:135], v[64:67], v[28:31]
	v_mfma_f32_16x16x32_bf16 v[24:27], v[216:219], v[64:67], v[24:27]
	v_mfma_f32_16x16x32_bf16 v[20:23], v[132:135], v[72:75], v[20:23]
	v_mfma_f32_16x16x32_bf16 v[16:19], v[216:219], v[72:75], v[16:19]
	v_mfma_f32_16x16x32_bf16 v[64:67], v[132:135], v[80:83], v[12:15]
	v_mfma_f32_16x16x32_bf16 v[8:11], v[216:219], v[80:83], v[8:11]
	v_mfma_f32_16x16x32_bf16 v[72:75], v[132:135], v[88:91], v[4:7]
	v_mfma_f32_16x16x32_bf16 v[0:3], v[216:219], v[88:91], v[0:3]
	v_mfma_f32_16x16x32_bf16 v[4:7], v[212:215], v[68:71], v[28:31]
	v_mfma_f32_16x16x32_bf16 v[12:15], v[220:223], v[68:71], v[24:27]
	v_mfma_f32_16x16x32_bf16 v[20:23], v[212:215], v[76:79], v[20:23]
	v_mfma_f32_16x16x32_bf16 v[28:31], v[220:223], v[76:79], v[16:19]
	v_mfma_f32_16x16x32_bf16 v[64:67], v[212:215], v[84:87], v[64:67]
	v_mfma_f32_16x16x32_bf16 v[68:71], v[220:223], v[84:87], v[8:11]
	v_mfma_f32_16x16x32_bf16 v[72:75], v[212:215], v[92:95], v[72:75]
	v_mfma_f32_16x16x32_bf16 v[76:79], v[220:223], v[92:95], v[0:3]
	s_setprio 0
	s_barrier
	ds_read_b128 v[8:11], v130
	ds_read_b128 v[0:3], v130 offset:1024
	ds_read_b128 v[16:19], v130 offset:2048
	ds_read_b128 v[80:83], v130 offset:3072
	ds_read_b128 v[138:141], v187 offset:32768
	ds_read_b128 v[212:215], v187 offset:33792
	ds_read_b128 v[216:219], v186 offset:32768
	ds_read_b128 v[220:223], v186 offset:33792
	ds_read_b128 v[224:227], v185 offset:32768
	ds_read_b128 v[228:231], v185 offset:33792
	ds_read_b128 v[232:235], v184 offset:32768
	ds_read_b128 v[236:239], v184 offset:33792
	s_waitcnt vmcnt(2)
	s_barrier
	s_waitcnt lgkmcnt(0)
	s_setprio 1
	s_waitcnt lgkmcnt(0)
	v_mfma_f32_16x16x32_bf16 v[24:27], v[8:11], v[138:141], v[124:127]
	v_mfma_f32_16x16x32_bf16 v[84:87], v[16:19], v[138:141], v[120:123]
	v_mfma_f32_16x16x32_bf16 v[88:91], v[8:11], v[216:219], v[116:119]
	v_mfma_f32_16x16x32_bf16 v[92:95], v[16:19], v[216:219], v[112:115]
	v_mfma_f32_16x16x32_bf16 v[108:111], v[8:11], v[224:227], v[108:111]
	v_mfma_f32_16x16x32_bf16 v[104:107], v[16:19], v[224:227], v[104:107]
	v_mfma_f32_16x16x32_bf16 v[100:103], v[8:11], v[232:235], v[100:103]
	v_mfma_f32_16x16x32_bf16 v[96:99], v[16:19], v[232:235], v[96:99]
	v_mfma_f32_16x16x32_bf16 v[148:151], v[0:3], v[212:215], v[24:27]
	v_mfma_f32_16x16x32_bf16 v[144:147], v[80:83], v[212:215], v[84:87]
	v_mfma_f32_16x16x32_bf16 v[132:135], v[0:3], v[220:223], v[88:91]
	v_mfma_f32_16x16x32_bf16 v[128:131], v[80:83], v[220:223], v[92:95]
	v_mfma_f32_16x16x32_bf16 v[116:119], v[0:3], v[228:231], v[108:111]
	v_mfma_f32_16x16x32_bf16 v[112:115], v[80:83], v[228:231], v[104:107]
	v_mfma_f32_16x16x32_bf16 v[100:103], v[0:3], v[236:239], v[100:103]
	v_mfma_f32_16x16x32_bf16 v[24:27], v[80:83], v[236:239], v[96:99]
	s_setprio 0
	s_barrier
	ds_read_b128 v[92:95], v136
	ds_read_b128 v[84:87], v136 offset:1024
	ds_read_b128 v[96:99], v136 offset:2048
	ds_read_b128 v[88:91], v136 offset:3072
	s_waitcnt vmcnt(0)
	s_barrier
	s_waitcnt lgkmcnt(0)
	s_setprio 1
	s_waitcnt lgkmcnt(0)
	v_mfma_f32_16x16x32_bf16 v[104:107], v[92:95], v[138:141], v[154:157]
	v_mfma_f32_16x16x32_bf16 v[108:111], v[96:99], v[138:141], v[158:161]
	v_mfma_f32_16x16x32_bf16 v[120:123], v[92:95], v[216:219], v[188:191]
	v_mfma_f32_16x16x32_bf16 v[124:127], v[96:99], v[216:219], v[192:195]
	v_mfma_f32_16x16x32_bf16 v[160:163], v[92:95], v[224:227], v[196:199]
	v_mfma_f32_16x16x32_bf16 v[188:191], v[96:99], v[224:227], v[200:203]
	v_mfma_f32_16x16x32_bf16 v[192:195], v[92:95], v[232:235], v[204:207]
	v_mfma_f32_16x16x32_bf16 v[196:199], v[96:99], v[232:235], v[208:211]
	v_mfma_f32_16x16x32_bf16 v[156:159], v[84:87], v[212:215], v[104:107]
	v_mfma_f32_16x16x32_bf16 v[152:155], v[88:91], v[212:215], v[108:111]
	v_mfma_f32_16x16x32_bf16 v[140:143], v[84:87], v[220:223], v[120:123]
	v_mfma_f32_16x16x32_bf16 v[136:139], v[88:91], v[220:223], v[124:127]
	v_mfma_f32_16x16x32_bf16 v[124:127], v[84:87], v[228:231], v[160:163]
	v_mfma_f32_16x16x32_bf16 v[120:123], v[88:91], v[228:231], v[188:191]
	v_mfma_f32_16x16x32_bf16 v[108:111], v[84:87], v[236:239], v[192:195]
	v_mfma_f32_16x16x32_bf16 v[104:107], v[88:91], v[236:239], v[196:199]
	s_setprio 0
	s_barrier
	v_mbcnt_lo_u32_b32 v164, -1, 0
	v_mbcnt_hi_u32_b32 v164, -1, v164
	s_cmp_lt_i32 s64, 3
	v_add_u32_e32 v160, s34, v164
	v_ashrrev_i32_e32 v192, 6, v160
	v_bfe_u32 v190, v160, 8, 1
	v_and_b32_e32 v191, 3, v192
	v_and_b32_e32 v188, 15, v164
	v_bfe_u32 v189, v160, 4, 2
	s_mov_b64 s[18:19], 0
	s_cbranch_scc1 .LBB0_362
	v_lshrrev_b32_e32 v160, 4, v160
	v_lshlrev_b32_e32 v162, 9, v189
	v_lshlrev_b32_e32 v163, 9, v160
	s_mov_b64 s[20:21], -1
	s_cmp_gt_i32 s64, 3
	v_lshlrev_b32_e32 v161, 4, v188
	v_and_b32_e32 v160, 0x400, v162
	v_and_b32_e32 v162, 0x200, v163
	s_cbranch_scc0 .LBB0_360
	s_lshl_b32 s15, s66, 20
	s_lshl_b32 s20, s66, 16
	s_and_b32 s15, s15, 0xff000000
	s_and_b32 s20, s20, 0xf0000
	s_lshl_b32 s17, s68, 21
	s_or_b32 s15, s20, s15
	v_lshlrev_b32_e32 v163, 14, v191
	s_add_i32 s15, s15, s17
	v_lshlrev_b32_e32 v166, 12, v190
	v_or3_b32 v163, s15, v161, v163
	v_or3_b32 v163, v163, v166, v162
	v_add_u32_e32 v166, v163, v160
	s_mov_b64 s[20:21], 0

.LBB0_465:
	ds_read_b128 v[164:167], v162
	ds_read_b128 v[168:171], v162 offset:1024
	ds_read_b128 v[172:175], v162 offset:2048
	ds_read_b128 v[176:179], v162 offset:3072
	ds_read_b128 v[180:183], v153
	ds_read_b128 v[184:187], v153 offset:1024
	ds_read_b128 v[188:191], v152
	ds_read_b128 v[192:195], v152 offset:1024
	ds_read_b128 v[196:199], v151
	ds_read_b128 v[200:203], v151 offset:1024
	ds_read_b128 v[204:207], v150
	ds_read_b128 v[208:211], v150 offset:1024
	s_waitcnt lgkmcnt(8)
	s_waitcnt vmcnt(10)
	s_barrier
	s_waitcnt lgkmcnt(0)
	s_waitcnt lgkmcnt(0)
	v_mfma_f32_16x16x32_bf16 v[124:127], v[164:167], v[180:183], v[124:127]
	v_mfma_f32_16x16x32_bf16 v[120:123], v[172:175], v[180:183], v[120:123]
	v_mfma_f32_16x16x32_bf16 v[116:119], v[164:167], v[188:191], v[116:119]
	v_mfma_f32_16x16x32_bf16 v[112:115], v[172:175], v[188:191], v[112:115]
	v_mfma_f32_16x16x32_bf16 v[108:111], v[164:167], v[196:199], v[108:111]
	v_mfma_f32_16x16x32_bf16 v[104:107], v[172:175], v[196:199], v[104:107]
	v_mfma_f32_16x16x32_bf16 v[100:103], v[164:167], v[204:207], v[100:103]
	v_mfma_f32_16x16x32_bf16 v[96:99], v[172:175], v[204:207], v[96:99]
	v_mfma_f32_16x16x32_bf16 v[124:127], v[168:171], v[184:187], v[124:127]
	v_mfma_f32_16x16x32_bf16 v[120:123], v[176:179], v[184:187], v[120:123]
	v_mfma_f32_16x16x32_bf16 v[116:119], v[168:171], v[192:195], v[116:119]
	v_mfma_f32_16x16x32_bf16 v[112:115], v[176:179], v[192:195], v[112:115]
	v_mfma_f32_16x16x32_bf16 v[108:111], v[168:171], v[200:203], v[108:111]
	v_mfma_f32_16x16x32_bf16 v[104:107], v[176:179], v[200:203], v[104:107]
	v_mfma_f32_16x16x32_bf16 v[100:103], v[168:171], v[208:211], v[100:103]
	v_mfma_f32_16x16x32_bf16 v[96:99], v[176:179], v[208:211], v[96:99]
	s_barrier
	v_lshl_add_u64 v[230:231], s[50:51], 0, v[130:131]
	s_mov_b64 s[68:69], 0x3880000
	s_add_i32 s36, s98, 0x10000
	v_lshl_add_u64 v[232:233], v[230:231], 0, s[68:69]
	s_mov_b32 m0, s36
	s_mov_b64 s[68:69], 0x3881000
	s_add_i32 s36, s98, 0x12000
	ds_read_b128 v[212:215], v159
	ds_read_b128 v[216:219], v159 offset:1024
	ds_read_b128 v[220:223], v159 offset:2048
	ds_read_b128 v[224:227], v159 offset:3072
	global_load_lds_dwordx4 v[232:233], off
	v_lshl_add_u64 v[232:233], v[230:231], 0, s[68:69]
	s_mov_b32 m0, s36
	s_nop 0
	global_load_lds_dwordx4 v[232:233], off
	s_mov_b64 s[68:69], 0xe000100
	s_mov_b32 s36, s98
	v_lshl_add_u64 v[232:233], v[228:229], 0, s[68:69]
	s_mov_b32 m0, s36
	s_mov_b64 s[68:69], 0xe040100
	s_add_i32 s36, s98, 0x2000
	global_load_lds_dwordx4 v[232:233], off
	v_lshl_add_u64 v[232:233], v[228:229], 0, s[68:69]
	s_mov_b32 m0, s36
	s_nop 0
	global_load_lds_dwordx4 v[232:233], off
	s_waitcnt vmcnt(12)
	s_barrier
	s_waitcnt lgkmcnt(0)
	s_waitcnt lgkmcnt(0)
	v_mfma_f32_16x16x32_bf16 v[92:95], v[212:215], v[180:183], v[92:95]
	v_mfma_f32_16x16x32_bf16 v[88:91], v[220:223], v[180:183], v[88:91]
	v_mfma_f32_16x16x32_bf16 v[84:87], v[212:215], v[188:191], v[84:87]
	v_mfma_f32_16x16x32_bf16 v[80:83], v[220:223], v[188:191], v[80:83]
	v_mfma_f32_16x16x32_bf16 v[76:79], v[212:215], v[196:199], v[76:79]
	v_mfma_f32_16x16x32_bf16 v[72:75], v[220:223], v[196:199], v[72:75]
	v_mfma_f32_16x16x32_bf16 v[68:71], v[212:215], v[204:207], v[68:71]
	v_mfma_f32_16x16x32_bf16 v[64:67], v[220:223], v[204:207], v[64:67]
	v_mfma_f32_16x16x32_bf16 v[92:95], v[216:219], v[184:187], v[92:95]
	v_mfma_f32_16x16x32_bf16 v[88:91], v[224:227], v[184:187], v[88:91]
	v_mfma_f32_16x16x32_bf16 v[84:87], v[216:219], v[192:195], v[84:87]
	v_mfma_f32_16x16x32_bf16 v[80:83], v[224:227], v[192:195], v[80:83]
	v_mfma_f32_16x16x32_bf16 v[76:79], v[216:219], v[200:203], v[76:79]
	v_mfma_f32_16x16x32_bf16 v[72:75], v[224:227], v[200:203], v[72:75]
	v_mfma_f32_16x16x32_bf16 v[68:71], v[216:219], v[208:211], v[68:71]
	v_mfma_f32_16x16x32_bf16 v[64:67], v[224:227], v[208:211], v[64:67]
	s_barrier
	ds_read_b128 v[180:183], v153 offset:16384
	ds_read_b128 v[184:187], v153 offset:17408
	ds_read_b128 v[188:191], v152 offset:16384
	ds_read_b128 v[192:195], v152 offset:17408
	ds_read_b128 v[196:199], v151 offset:16384
	ds_read_b128 v[200:203], v151 offset:17408
	ds_read_b128 v[204:207], v150 offset:16384
	ds_read_b128 v[208:211], v150 offset:17408
	s_mov_b64 s[68:69], 0x3882000
	s_add_i32 s36, s98, 0x14000
	v_lshl_add_u64 v[232:233], v[230:231], 0, s[68:69]
	s_mov_b32 m0, s36
	s_mov_b64 s[68:69], 0x3883000
	s_add_i32 s36, s98, 0x16000
	global_load_lds_dwordx4 v[232:233], off
	v_lshl_add_u64 v[232:233], v[230:231], 0, s[68:69]
	s_mov_b32 m0, s36
	s_nop 0
	global_load_lds_dwordx4 v[232:233], off
	s_barrier
	s_waitcnt lgkmcnt(0)
	s_waitcnt lgkmcnt(0)
	v_mfma_f32_16x16x32_bf16 v[60:63], v[164:167], v[180:183], v[60:63]
	v_mfma_f32_16x16x32_bf16 v[56:59], v[172:175], v[180:183], v[56:59]
	v_mfma_f32_16x16x32_bf16 v[52:55], v[164:167], v[188:191], v[52:55]
	v_mfma_f32_16x16x32_bf16 v[48:51], v[172:175], v[188:191], v[48:51]
	v_mfma_f32_16x16x32_bf16 v[44:47], v[164:167], v[196:199], v[44:47]
	v_mfma_f32_16x16x32_bf16 v[40:43], v[172:175], v[196:199], v[40:43]
	v_mfma_f32_16x16x32_bf16 v[36:39], v[164:167], v[204:207], v[36:39]
	v_mfma_f32_16x16x32_bf16 v[32:35], v[172:175], v[204:207], v[32:35]
	v_mfma_f32_16x16x32_bf16 v[60:63], v[168:171], v[184:187], v[60:63]
	v_mfma_f32_16x16x32_bf16 v[56:59], v[176:179], v[184:187], v[56:59]
	v_mfma_f32_16x16x32_bf16 v[52:55], v[168:171], v[192:195], v[52:55]
	v_mfma_f32_16x16x32_bf16 v[48:51], v[176:179], v[192:195], v[48:51]
	v_mfma_f32_16x16x32_bf16 v[44:47], v[168:171], v[200:203], v[44:47]
	v_mfma_f32_16x16x32_bf16 v[40:43], v[176:179], v[200:203], v[40:43]
	v_mfma_f32_16x16x32_bf16 v[36:39], v[168:171], v[208:211], v[36:39]
	v_mfma_f32_16x16x32_bf16 v[32:35], v[176:179], v[208:211], v[32:35]
	s_barrier
	s_add_i32 s36, s98, 0x4000
	v_lshl_add_u64 v[166:167], v[228:229], 0, s[26:27]
	s_mov_b32 m0, s36
	s_add_i32 s36, s98, 0x6000
	global_load_lds_dwordx4 v[166:167], off
	v_lshl_add_u64 v[166:167], v[228:229], 0, s[28:29]
	s_mov_b32 m0, s36
	s_nop 0
	global_load_lds_dwordx4 v[166:167], off
	s_waitcnt vmcnt(12)
	s_barrier
	v_mfma_f32_16x16x32_bf16 v[28:31], v[212:215], v[180:183], v[28:31]
	v_mfma_f32_16x16x32_bf16 v[24:27], v[220:223], v[180:183], v[24:27]
	v_mfma_f32_16x16x32_bf16 v[20:23], v[212:215], v[188:191], v[20:23]
	v_mfma_f32_16x16x32_bf16 v[16:19], v[220:223], v[188:191], v[16:19]
	v_mfma_f32_16x16x32_bf16 v[12:15], v[212:215], v[196:199], v[12:15]
	v_mfma_f32_16x16x32_bf16 v[8:11], v[220:223], v[196:199], v[8:11]
	v_mfma_f32_16x16x32_bf16 v[4:7], v[212:215], v[204:207], v[4:7]
	v_mfma_f32_16x16x32_bf16 v[0:3], v[220:223], v[204:207], v[0:3]
	v_mfma_f32_16x16x32_bf16 v[28:31], v[216:219], v[184:187], v[28:31]
	v_mfma_f32_16x16x32_bf16 v[24:27], v[224:227], v[184:187], v[24:27]
	v_mfma_f32_16x16x32_bf16 v[20:23], v[216:219], v[192:195], v[20:23]
	v_mfma_f32_16x16x32_bf16 v[16:19], v[224:227], v[192:195], v[16:19]
	v_mfma_f32_16x16x32_bf16 v[12:15], v[216:219], v[200:203], v[12:15]
	v_mfma_f32_16x16x32_bf16 v[8:11], v[224:227], v[200:203], v[8:11]
	v_mfma_f32_16x16x32_bf16 v[4:7], v[216:219], v[208:211], v[4:7]
	v_mfma_f32_16x16x32_bf16 v[0:3], v[224:227], v[208:211], v[0:3]
	s_barrier
	ds_read_b128 v[164:167], v155
	ds_read_b128 v[168:171], v155 offset:1024
	ds_read_b128 v[172:175], v155 offset:2048
	ds_read_b128 v[176:179], v155 offset:3072
	ds_read_b128 v[180:183], v153 offset:32768
	ds_read_b128 v[184:187], v153 offset:33792
	ds_read_b128 v[188:191], v152 offset:32768
	ds_read_b128 v[192:195], v152 offset:33792
	ds_read_b128 v[196:199], v151 offset:32768
	ds_read_b128 v[200:203], v151 offset:33792
	ds_read_b128 v[204:207], v150 offset:32768
	ds_read_b128 v[208:211], v150 offset:33792
	s_waitcnt lgkmcnt(8)
	s_waitcnt vmcnt(10)
	s_barrier
	s_waitcnt lgkmcnt(0)
	s_waitcnt lgkmcnt(0)
	v_mfma_f32_16x16x32_bf16 v[124:127], v[164:167], v[180:183], v[124:127]
	v_mfma_f32_16x16x32_bf16 v[120:123], v[172:175], v[180:183], v[120:123]
	v_mfma_f32_16x16x32_bf16 v[116:119], v[164:167], v[188:191], v[116:119]
	v_mfma_f32_16x16x32_bf16 v[112:115], v[172:175], v[188:191], v[112:115]
	v_mfma_f32_16x16x32_bf16 v[108:111], v[164:167], v[196:199], v[108:111]
	v_mfma_f32_16x16x32_bf16 v[104:107], v[172:175], v[196:199], v[104:107]
	v_mfma_f32_16x16x32_bf16 v[100:103], v[164:167], v[204:207], v[100:103]
	v_mfma_f32_16x16x32_bf16 v[96:99], v[172:175], v[204:207], v[96:99]
	v_mfma_f32_16x16x32_bf16 v[124:127], v[168:171], v[184:187], v[124:127]
	v_mfma_f32_16x16x32_bf16 v[120:123], v[176:179], v[184:187], v[120:123]
	v_mfma_f32_16x16x32_bf16 v[116:119], v[168:171], v[192:195], v[116:119]
	v_mfma_f32_16x16x32_bf16 v[112:115], v[176:179], v[192:195], v[112:115]
	v_mfma_f32_16x16x32_bf16 v[108:111], v[168:171], v[200:203], v[108:111]
	v_mfma_f32_16x16x32_bf16 v[104:107], v[176:179], v[200:203], v[104:107]
	v_mfma_f32_16x16x32_bf16 v[100:103], v[168:171], v[208:211], v[100:103]
	v_mfma_f32_16x16x32_bf16 v[96:99], v[176:179], v[208:211], v[96:99]
	s_barrier
	s_add_i32 s36, s98, 0x18000
	v_lshl_add_u64 v[232:233], v[230:231], 0, s[30:31]
	s_mov_b32 m0, s36
	s_add_i32 s36, s98, 0x1a000
	ds_read_b128 v[212:215], v154
	ds_read_b128 v[216:219], v154 offset:1024
	ds_read_b128 v[220:223], v154 offset:2048
	ds_read_b128 v[224:227], v154 offset:3072
	global_load_lds_dwordx4 v[232:233], off
	v_lshl_add_u64 v[232:233], v[230:231], 0, s[34:35]
	s_mov_b32 m0, s36
	s_nop 0
	global_load_lds_dwordx4 v[232:233], off
	s_add_i32 s36, s98, 0x8000
	v_lshl_add_u64 v[232:233], v[228:229], 0, s[44:45]
	s_mov_b32 m0, s36
	s_add_i32 s36, s98, 0xa000
	global_load_lds_dwordx4 v[232:233], off
	v_lshl_add_u64 v[228:229], v[228:229], 0, s[46:47]
	s_mov_b32 m0, s36
	s_nop 0
	global_load_lds_dwordx4 v[228:229], off
	s_waitcnt vmcnt(12)
	s_barrier
	s_waitcnt lgkmcnt(0)
	s_waitcnt lgkmcnt(0)
	v_mfma_f32_16x16x32_bf16 v[92:95], v[212:215], v[180:183], v[92:95]
	v_mfma_f32_16x16x32_bf16 v[88:91], v[220:223], v[180:183], v[88:91]
	v_mfma_f32_16x16x32_bf16 v[84:87], v[212:215], v[188:191], v[84:87]
	v_mfma_f32_16x16x32_bf16 v[80:83], v[220:223], v[188:191], v[80:83]
	v_mfma_f32_16x16x32_bf16 v[76:79], v[212:215], v[196:199], v[76:79]
	v_mfma_f32_16x16x32_bf16 v[72:75], v[220:223], v[196:199], v[72:75]
	v_mfma_f32_16x16x32_bf16 v[68:71], v[212:215], v[204:207], v[68:71]
	v_mfma_f32_16x16x32_bf16 v[64:67], v[220:223], v[204:207], v[64:67]
	v_mfma_f32_16x16x32_bf16 v[92:95], v[216:219], v[184:187], v[92:95]
	v_mfma_f32_16x16x32_bf16 v[88:91], v[224:227], v[184:187], v[88:91]
	v_mfma_f32_16x16x32_bf16 v[84:87], v[216:219], v[192:195], v[84:87]
	v_mfma_f32_16x16x32_bf16 v[80:83], v[224:227], v[192:195], v[80:83]
	v_mfma_f32_16x16x32_bf16 v[76:79], v[216:219], v[200:203], v[76:79]
	v_mfma_f32_16x16x32_bf16 v[72:75], v[224:227], v[200:203], v[72:75]
	v_mfma_f32_16x16x32_bf16 v[68:71], v[216:219], v[208:211], v[68:71]
	v_mfma_f32_16x16x32_bf16 v[64:67], v[224:227], v[208:211], v[64:67]
	s_barrier
	ds_read_b128 v[180:183], v153 offset:49152
	ds_read_b128 v[184:187], v153 offset:50176
	ds_read_b128 v[188:191], v152 offset:49152
	ds_read_b128 v[192:195], v152 offset:50176
	ds_read_b128 v[196:199], v151 offset:49152
	ds_read_b128 v[200:203], v151 offset:50176
	ds_read_b128 v[204:207], v150 offset:49152
	ds_read_b128 v[208:211], v150 offset:50176
	s_add_i32 s36, s98, 0x1c000
	v_lshl_add_u64 v[232:233], v[230:231], 0, s[56:57]
	s_mov_b32 m0, s36
	s_add_i32 s36, s98, 0x1e000
	global_load_lds_dwordx4 v[232:233], off
	v_lshl_add_u64 v[232:233], v[230:231], 0, s[58:59]
	s_mov_b32 m0, s36
	s_nop 0
	global_load_lds_dwordx4 v[232:233], off
	s_barrier
	s_waitcnt lgkmcnt(0)
	s_waitcnt lgkmcnt(0)
	v_mfma_f32_16x16x32_bf16 v[60:63], v[164:167], v[180:183], v[60:63]
	v_mfma_f32_16x16x32_bf16 v[56:59], v[172:175], v[180:183], v[56:59]
	v_mfma_f32_16x16x32_bf16 v[52:55], v[164:167], v[188:191], v[52:55]
	v_mfma_f32_16x16x32_bf16 v[48:51], v[172:175], v[188:191], v[48:51]
	v_mfma_f32_16x16x32_bf16 v[44:47], v[164:167], v[196:199], v[44:47]
	v_mfma_f32_16x16x32_bf16 v[40:43], v[172:175], v[196:199], v[40:43]
	v_mfma_f32_16x16x32_bf16 v[36:39], v[164:167], v[204:207], v[36:39]
	v_mfma_f32_16x16x32_bf16 v[32:35], v[172:175], v[204:207], v[32:35]
	v_mfma_f32_16x16x32_bf16 v[60:63], v[168:171], v[184:187], v[60:63]
	v_mfma_f32_16x16x32_bf16 v[56:59], v[176:179], v[184:187], v[56:59]
	v_mfma_f32_16x16x32_bf16 v[52:55], v[168:171], v[192:195], v[52:55]
	v_mfma_f32_16x16x32_bf16 v[48:51], v[176:179], v[192:195], v[48:51]
	v_mfma_f32_16x16x32_bf16 v[44:47], v[168:171], v[200:203], v[44:47]
	v_mfma_f32_16x16x32_bf16 v[40:43], v[176:179], v[200:203], v[40:43]
	v_mfma_f32_16x16x32_bf16 v[36:39], v[168:171], v[208:211], v[36:39]
	v_mfma_f32_16x16x32_bf16 v[32:35], v[176:179], v[208:211], v[32:35]
	s_barrier
	v_lshl_add_u64 v[132:133], v[132:133], 0, s[60:61]
	v_lshl_add_u64 v[228:229], s[50:51], 0, v[132:133]
	s_mov_b64 s[68:69], 0xe080080
	s_add_i32 s36, s98, 0xc000
	v_lshl_add_u64 v[166:167], v[228:229], 0, s[68:69]
	s_mov_b32 m0, s36
	s_mov_b64 s[68:69], 0xe0c0080
	s_add_i32 s36, s98, 0xe000
	global_load_lds_dwordx4 v[166:167], off
	v_lshl_add_u64 v[166:167], v[228:229], 0, s[68:69]
	s_mov_b32 m0, s36
	s_nop 0
	global_load_lds_dwordx4 v[166:167], off
	s_waitcnt vmcnt(12)
	s_barrier
	v_mfma_f32_16x16x32_bf16 v[28:31], v[212:215], v[180:183], v[28:31]
	v_mfma_f32_16x16x32_bf16 v[24:27], v[220:223], v[180:183], v[24:27]
	v_mfma_f32_16x16x32_bf16 v[20:23], v[212:215], v[188:191], v[20:23]
	v_mfma_f32_16x16x32_bf16 v[16:19], v[220:223], v[188:191], v[16:19]
	v_mfma_f32_16x16x32_bf16 v[12:15], v[212:215], v[196:199], v[12:15]
	v_mfma_f32_16x16x32_bf16 v[8:11], v[220:223], v[196:199], v[8:11]
	v_mfma_f32_16x16x32_bf16 v[4:7], v[212:215], v[204:207], v[4:7]
	v_mfma_f32_16x16x32_bf16 v[0:3], v[220:223], v[204:207], v[0:3]
	v_mfma_f32_16x16x32_bf16 v[28:31], v[216:219], v[184:187], v[28:31]
	v_mfma_f32_16x16x32_bf16 v[24:27], v[224:227], v[184:187], v[24:27]
	v_mfma_f32_16x16x32_bf16 v[20:23], v[216:219], v[192:195], v[20:23]
	v_mfma_f32_16x16x32_bf16 v[16:19], v[224:227], v[192:195], v[16:19]
	v_mfma_f32_16x16x32_bf16 v[12:15], v[216:219], v[200:203], v[12:15]
	v_mfma_f32_16x16x32_bf16 v[8:11], v[224:227], v[200:203], v[8:11]
	v_mfma_f32_16x16x32_bf16 v[4:7], v[216:219], v[208:211], v[4:7]
	v_mfma_f32_16x16x32_bf16 v[0:3], v[224:227], v[208:211], v[0:3]
	s_add_i32 s24, s24, 2
	v_lshl_add_u64 v[130:131], v[130:131], 0, s[10:11]
	s_cmp_lt_u32 s24, 28
	s_barrier
	s_cbranch_scc1 .LBB0_465
	s_lshl_b32 s24, s86, 5
	s_lshl_b32 s36, s86, 8
	s_and_b32 s24, s24, 0x1800
	s_and_b32 s36, s36, 0x700
	s_or_b32 s24, s36, s24
	v_lshlrev_b32_e32 v128, 3, v156
	v_lshlrev_b32_e32 v130, 5, v156
	v_and_b32_e32 v128, 0xffff0, v128
	v_and_b32_e32 v130, 32, v130
	s_lshl_b32 s36, s24, 12
	v_add_u32_e32 v130, v130, v158
	v_add_lshl_u32 v128, v157, v128, 12
	s_add_u32 s68, s70, s36
	v_lshl_add_u32 v128, v130, 1, v128
	s_addc_u32 s69, s71, 0
	v_lshl_add_u64 v[156:157], s[68:69], 0, v[128:129]
	v_readfirstlane_b32 s36, v161
	ds_read_b128 v[130:133], v162
	ds_read_b128 v[164:167], v162 offset:1024
	ds_read_b128 v[168:171], v162 offset:2048
	ds_read_b128 v[172:175], v162 offset:3072
	ds_read_b128 v[176:179], v153
	ds_read_b128 v[180:183], v153 offset:1024
	ds_read_b128 v[184:187], v152
	ds_read_b128 v[188:191], v152 offset:1024
	ds_read_b128 v[192:195], v151
	ds_read_b128 v[196:199], v151 offset:1024
	ds_read_b128 v[200:203], v150
	ds_read_b128 v[204:207], v150 offset:1024
	v_lshl_add_u64 v[162:163], v[156:157], 0, s[62:63]
	s_mov_b32 m0, s36
	v_readfirstlane_b32 s36, v160
	v_lshl_add_u64 v[156:157], v[156:157], 0, s[64:65]
	s_mov_b32 m0, s36
	s_nop 0
	s_waitcnt vmcnt(8)
	s_barrier
	s_waitcnt lgkmcnt(0)
	s_setprio 1
	s_waitcnt lgkmcnt(0)
	v_mfma_f32_16x16x32_bf16 v[124:127], v[130:133], v[176:179], v[124:127]
	v_mfma_f32_16x16x32_bf16 v[120:123], v[168:171], v[176:179], v[120:123]
	v_mfma_f32_16x16x32_bf16 v[116:119], v[130:133], v[184:187], v[116:119]
	v_mfma_f32_16x16x32_bf16 v[112:115], v[168:171], v[184:187], v[112:115]
	v_mfma_f32_16x16x32_bf16 v[108:111], v[130:133], v[192:195], v[108:111]
	v_mfma_f32_16x16x32_bf16 v[104:107], v[168:171], v[192:195], v[104:107]
	v_mfma_f32_16x16x32_bf16 v[100:103], v[130:133], v[200:203], v[100:103]
	v_mfma_f32_16x16x32_bf16 v[96:99], v[168:171], v[200:203], v[96:99]
	v_mfma_f32_16x16x32_bf16 v[124:127], v[164:167], v[180:183], v[124:127]
	v_mfma_f32_16x16x32_bf16 v[120:123], v[172:175], v[180:183], v[120:123]
	v_mfma_f32_16x16x32_bf16 v[116:119], v[164:167], v[188:191], v[116:119]
	v_mfma_f32_16x16x32_bf16 v[112:115], v[172:175], v[188:191], v[112:115]
	v_mfma_f32_16x16x32_bf16 v[108:111], v[164:167], v[196:199], v[108:111]
	v_mfma_f32_16x16x32_bf16 v[104:107], v[172:175], v[196:199], v[104:107]
	v_mfma_f32_16x16x32_bf16 v[100:103], v[164:167], v[204:207], v[100:103]
	v_mfma_f32_16x16x32_bf16 v[96:99], v[172:175], v[204:207], v[96:99]
	s_setprio 0
	s_barrier
	ds_read_b128 v[160:163], v159
	ds_read_b128 v[208:211], v159 offset:1024
	ds_read_b128 v[212:215], v159 offset:2048
	ds_read_b128 v[156:159], v159 offset:3072
	s_barrier
	s_waitcnt lgkmcnt(0)
	s_setprio 1
	s_waitcnt lgkmcnt(0)
	v_mfma_f32_16x16x32_bf16 v[92:95], v[160:163], v[176:179], v[92:95]
	v_mfma_f32_16x16x32_bf16 v[88:91], v[212:215], v[176:179], v[88:91]
	v_mfma_f32_16x16x32_bf16 v[84:87], v[160:163], v[184:187], v[84:87]
	v_mfma_f32_16x16x32_bf16 v[80:83], v[212:215], v[184:187], v[80:83]
	v_mfma_f32_16x16x32_bf16 v[76:79], v[160:163], v[192:195], v[76:79]
	v_mfma_f32_16x16x32_bf16 v[72:75], v[212:215], v[192:195], v[72:75]
	v_mfma_f32_16x16x32_bf16 v[68:71], v[160:163], v[200:203], v[68:71]
	v_mfma_f32_16x16x32_bf16 v[64:67], v[212:215], v[200:203], v[64:67]
	v_mfma_f32_16x16x32_bf16 v[176:179], v[208:211], v[180:183], v[92:95]
	v_mfma_f32_16x16x32_bf16 v[180:183], v[156:159], v[180:183], v[88:91]
	v_mfma_f32_16x16x32_bf16 v[184:187], v[208:211], v[188:191], v[84:87]
	v_mfma_f32_16x16x32_bf16 v[188:191], v[156:159], v[188:191], v[80:83]
	v_mfma_f32_16x16x32_bf16 v[192:195], v[208:211], v[196:199], v[76:79]
	v_mfma_f32_16x16x32_bf16 v[196:199], v[156:159], v[196:199], v[72:75]
	v_mfma_f32_16x16x32_bf16 v[200:203], v[208:211], v[204:207], v[68:71]
	v_mfma_f32_16x16x32_bf16 v[204:207], v[156:159], v[204:207], v[64:67]
	s_setprio 0
	s_barrier
	s_nop 0
	ds_read_b128 v[64:67], v153 offset:16384
	ds_read_b128 v[68:71], v153 offset:17408
	ds_read_b128 v[72:75], v152 offset:16384
	ds_read_b128 v[76:79], v152 offset:17408
	ds_read_b128 v[80:83], v151 offset:16384
	ds_read_b128 v[84:87], v151 offset:17408
	ds_read_b128 v[88:91], v150 offset:16384
	ds_read_b128 v[92:95], v150 offset:17408
	s_waitcnt vmcnt(4)
	s_barrier
	s_waitcnt lgkmcnt(0)
	s_setprio 1
	s_waitcnt lgkmcnt(0)
	v_mfma_f32_16x16x32_bf16 v[60:63], v[130:133], v[64:67], v[60:63]
	v_mfma_f32_16x16x32_bf16 v[56:59], v[168:171], v[64:67], v[56:59]
	v_mfma_f32_16x16x32_bf16 v[52:55], v[130:133], v[72:75], v[52:55]
	v_mfma_f32_16x16x32_bf16 v[48:51], v[168:171], v[72:75], v[48:51]
	v_mfma_f32_16x16x32_bf16 v[216:219], v[130:133], v[80:83], v[44:47]
	v_mfma_f32_16x16x32_bf16 v[220:223], v[168:171], v[80:83], v[40:43]
	v_mfma_f32_16x16x32_bf16 v[130:133], v[130:133], v[88:91], v[36:39]
	v_mfma_f32_16x16x32_bf16 v[168:171], v[168:171], v[88:91], v[32:35]
	v_mfma_f32_16x16x32_bf16 v[32:35], v[164:167], v[68:71], v[60:63]
	v_mfma_f32_16x16x32_bf16 v[36:39], v[172:175], v[68:71], v[56:59]
	v_mfma_f32_16x16x32_bf16 v[40:43], v[164:167], v[76:79], v[52:55]
	v_mfma_f32_16x16x32_bf16 v[44:47], v[172:175], v[76:79], v[48:51]
	v_mfma_f32_16x16x32_bf16 v[48:51], v[164:167], v[84:87], v[216:219]
	v_mfma_f32_16x16x32_bf16 v[52:55], v[172:175], v[84:87], v[220:223]
	v_mfma_f32_16x16x32_bf16 v[56:59], v[164:167], v[92:95], v[130:133]
	v_mfma_f32_16x16x32_bf16 v[60:63], v[172:175], v[92:95], v[168:171]
	s_setprio 0
	s_setprio 1
	v_mfma_f32_16x16x32_bf16 v[28:31], v[160:163], v[64:67], v[28:31]
	v_mfma_f32_16x16x32_bf16 v[24:27], v[212:215], v[64:67], v[24:27]
	v_mfma_f32_16x16x32_bf16 v[20:23], v[160:163], v[72:75], v[20:23]
	v_mfma_f32_16x16x32_bf16 v[64:67], v[212:215], v[72:75], v[16:19]
	v_mfma_f32_16x16x32_bf16 v[72:75], v[160:163], v[80:83], v[12:15]
	v_mfma_f32_16x16x32_bf16 v[8:11], v[212:215], v[80:83], v[8:11]
	v_mfma_f32_16x16x32_bf16 v[80:83], v[160:163], v[88:91], v[4:7]
	v_mfma_f32_16x16x32_bf16 v[0:3], v[212:215], v[88:91], v[0:3]
	v_mfma_f32_16x16x32_bf16 v[4:7], v[208:211], v[68:71], v[28:31]
	v_mfma_f32_16x16x32_bf16 v[12:15], v[156:159], v[68:71], v[24:27]
	v_mfma_f32_16x16x32_bf16 v[16:19], v[208:211], v[76:79], v[20:23]
	v_mfma_f32_16x16x32_bf16 v[20:23], v[156:159], v[76:79], v[64:67]
	v_mfma_f32_16x16x32_bf16 v[24:27], v[208:211], v[84:87], v[72:75]
	v_mfma_f32_16x16x32_bf16 v[28:31], v[156:159], v[84:87], v[8:11]
	v_mfma_f32_16x16x32_bf16 v[64:67], v[208:211], v[92:95], v[80:83]
	v_mfma_f32_16x16x32_bf16 v[68:71], v[156:159], v[92:95], v[0:3]
	s_setprio 0
	s_barrier
	ds_read_b128 v[8:11], v155
	ds_read_b128 v[0:3], v155 offset:1024
	ds_read_b128 v[76:79], v155 offset:2048
	ds_read_b128 v[72:75], v155 offset:3072
	ds_read_b128 v[130:133], v153 offset:32768
	ds_read_b128 v[156:159], v153 offset:33792
	ds_read_b128 v[160:163], v152 offset:32768
	ds_read_b128 v[164:167], v152 offset:33792
	ds_read_b128 v[168:171], v151 offset:32768
	ds_read_b128 v[172:175], v151 offset:33792
	ds_read_b128 v[208:211], v150 offset:32768
	ds_read_b128 v[212:215], v150 offset:33792
	s_waitcnt vmcnt(2)
	s_barrier
	s_waitcnt lgkmcnt(0)
	s_setprio 1
	s_waitcnt lgkmcnt(0)
	v_mfma_f32_16x16x32_bf16 v[80:83], v[8:11], v[130:133], v[124:127]
	v_mfma_f32_16x16x32_bf16 v[84:87], v[76:79], v[130:133], v[120:123]
	v_mfma_f32_16x16x32_bf16 v[88:91], v[8:11], v[160:163], v[116:119]
	v_mfma_f32_16x16x32_bf16 v[92:95], v[76:79], v[160:163], v[112:115]
	v_mfma_f32_16x16x32_bf16 v[108:111], v[8:11], v[168:171], v[108:111]
	v_mfma_f32_16x16x32_bf16 v[104:107], v[76:79], v[168:171], v[104:107]
	v_mfma_f32_16x16x32_bf16 v[100:103], v[8:11], v[208:211], v[100:103]
	v_mfma_f32_16x16x32_bf16 v[96:99], v[76:79], v[208:211], v[96:99]
	v_mfma_f32_16x16x32_bf16 v[112:115], v[0:3], v[156:159], v[80:83]
	v_mfma_f32_16x16x32_bf16 v[116:119], v[72:75], v[156:159], v[84:87]
	v_mfma_f32_16x16x32_bf16 v[120:123], v[0:3], v[164:167], v[88:91]
	v_mfma_f32_16x16x32_bf16 v[124:127], v[72:75], v[164:167], v[92:95]
	v_mfma_f32_16x16x32_bf16 v[108:111], v[0:3], v[172:175], v[108:111]
	v_mfma_f32_16x16x32_bf16 v[104:107], v[72:75], v[172:175], v[104:107]
	v_mfma_f32_16x16x32_bf16 v[100:103], v[0:3], v[212:215], v[100:103]
	v_mfma_f32_16x16x32_bf16 v[96:99], v[72:75], v[212:215], v[96:99]
	s_setprio 0
	s_barrier
	ds_read_b128 v[88:91], v154
	ds_read_b128 v[80:83], v154 offset:1024
	ds_read_b128 v[92:95], v154 offset:2048
	ds_read_b128 v[84:87], v154 offset:3072
	s_waitcnt vmcnt(0)
	s_barrier
	s_waitcnt lgkmcnt(0)
	s_setprio 1
	s_waitcnt lgkmcnt(0)
	v_mfma_f32_16x16x32_bf16 v[176:179], v[88:91], v[130:133], v[176:179]
	v_mfma_f32_16x16x32_bf16 v[130:133], v[92:95], v[130:133], v[180:183]
	v_mfma_f32_16x16x32_bf16 v[180:183], v[88:91], v[160:163], v[184:187]
	v_mfma_f32_16x16x32_bf16 v[160:163], v[92:95], v[160:163], v[188:191]
	v_mfma_f32_16x16x32_bf16 v[184:187], v[88:91], v[168:171], v[192:195]
	v_mfma_f32_16x16x32_bf16 v[168:171], v[92:95], v[168:171], v[196:199]
	v_mfma_f32_16x16x32_bf16 v[188:191], v[88:91], v[208:211], v[200:203]
	v_mfma_f32_16x16x32_bf16 v[192:195], v[92:95], v[208:211], v[204:207]
	v_mfma_f32_16x16x32_bf16 v[176:179], v[80:83], v[156:159], v[176:179]
	v_mfma_f32_16x16x32_bf16 v[130:133], v[84:87], v[156:159], v[130:133]
	v_mfma_f32_16x16x32_bf16 v[154:157], v[80:83], v[164:167], v[180:183]
	v_mfma_f32_16x16x32_bf16 v[158:161], v[84:87], v[164:167], v[160:163]
	v_mfma_f32_16x16x32_bf16 v[162:165], v[80:83], v[172:175], v[184:187]
	v_mfma_f32_16x16x32_bf16 v[166:169], v[84:87], v[172:175], v[168:171]
	v_mfma_f32_16x16x32_bf16 v[170:173], v[80:83], v[212:215], v[188:191]
	v_mfma_f32_16x16x32_bf16 v[180:183], v[84:87], v[212:215], v[192:195]
	s_setprio 0
	s_barrier
	v_mbcnt_lo_u32_b32 v128, -1, 0
	v_mbcnt_hi_u32_b32 v128, -1, v128
	v_cvt_pk_bf16_f32 v112, v112, v113
	v_cvt_pk_bf16_f32 v113, v114, v115
	v_cvt_pk_bf16_f32 v114, v116, v117
	v_cvt_pk_bf16_f32 v115, v118, v119
	s_lshl_b32 s68, s66, 9
	v_add_u32_e32 v174, s74, v128
	v_ashrrev_i32_e32 v175, 6, v174
	v_and_b32_e32 v184, 15, v128
	v_and_b32_e32 v185, 48, v128
	v_mul_lo_u32 v186, v175, s79
	v_bfe_u32 v187, v128, 3, 3
	v_lshlrev_b32_e32 v128, 4, v128
	v_add_u32_e32 v186, 0x20000, v186
	v_lshrrev_b32_e32 v174, 2, v174
	v_and_b32_e32 v128, 0x70, v128
	v_mul_u32_u24_e32 v184, 0x90, v184
	v_and_b32_e32 v174, 64, v174
	v_add3_u32 v184, v186, v184, v185
	v_or_b32_e32 v185, v186, v128
	v_or3_b32 v174, s24, v174, v187
	v_mad_u32_u24 v185, v187, s80, v185
	ds_write_b128 v184, v[112:115]
	v_cvt_pk_bf16_f32 v112, v176, v177
	v_cvt_pk_bf16_f32 v113, v178, v179
	v_cvt_pk_bf16_f32 v114, v130, v131
	v_cvt_pk_bf16_f32 v115, v132, v133
	ds_write_b128 v184, v[112:115] offset:64
	v_lshlrev_b32_e32 v175, 7, v175
	ds_read_b128 v[112:115], v185
	v_lshlrev_b32_e32 v116, 12, v174
	v_and_or_b32 v116, v175, s81, v116
	v_or3_b32 v128, v116, s68, v128
	ds_read_b128 v[116:119], v185 offset:1152
	v_lshl_add_u64 v[130:131], s[0:1], 0, v[128:129]
	s_mov_b32 s36, 0x8000
	s_waitcnt lgkmcnt(0)
	global_store_dwordx4 v128, v[112:115], s[0:1]
	v_cvt_pk_bf16_f32 v108, v108, v109
	v_cvt_pk_bf16_f32 v109, v110, v111
	v_cvt_pk_bf16_f32 v110, v104, v105
	v_cvt_pk_bf16_f32 v111, v106, v107
	v_cvt_pk_bf16_f32 v104, v162, v163
	s_nop 1
	v_add_co_u32_e32 v112, vcc, s36, v130
	v_cvt_pk_bf16_f32 v114, v124, v125
	v_cvt_pk_bf16_f32 v115, v126, v127
	v_cvt_pk_bf16_f32 v105, v164, v165
	v_cvt_pk_bf16_f32 v106, v166, v167
	s_nop 1
	v_addc_co_u32_e32 v113, vcc, 0, v131, vcc
	global_store_dwordx4 v[112:113], v[116:119], off
	v_cvt_pk_bf16_f32 v112, v120, v121
	v_cvt_pk_bf16_f32 v113, v122, v123
	ds_write_b128 v184, v[112:115]
	v_cvt_pk_bf16_f32 v112, v154, v155
	v_cvt_pk_bf16_f32 v113, v156, v157
	v_cvt_pk_bf16_f32 v114, v158, v159
	v_cvt_pk_bf16_f32 v115, v160, v161
	ds_write_b128 v184, v[112:115] offset:64
	ds_read_b128 v[112:115], v185
	ds_read_b128 v[116:119], v185 offset:1152
	v_add_co_u32_e32 v120, vcc, s76, v130
	ds_write_b128 v184, v[108:111]
	v_cvt_pk_bf16_f32 v107, v168, v169
	ds_write_b128 v184, v[104:107] offset:64
	v_addc_co_u32_e32 v121, vcc, 0, v131, vcc
	ds_read_b128 v[104:107], v185
	ds_read_b128 v[108:111], v185 offset:1152
	s_waitcnt lgkmcnt(0)
	global_store_dwordx4 v[120:121], v[112:115], off
	v_cvt_pk_bf16_f32 v100, v100, v101
	v_cvt_pk_bf16_f32 v101, v102, v103
	v_cvt_pk_bf16_f32 v102, v96, v97
	v_cvt_pk_bf16_f32 v103, v98, v99
	ds_write_b128 v184, v[100:103]
	s_nop 0
	v_add_co_u32_e32 v112, vcc, s77, v130
	v_cvt_pk_bf16_f32 v96, v170, v171
	v_cvt_pk_bf16_f32 v97, v172, v173
	v_cvt_pk_bf16_f32 v98, v180, v181
	v_cvt_pk_bf16_f32 v99, v182, v183
	s_nop 1
	v_addc_co_u32_e32 v113, vcc, 0, v131, vcc
	global_store_dwordx4 v[112:113], v[116:119], off
	v_add_co_u32_e32 v112, vcc, s78, v130
	ds_write_b128 v184, v[96:99] offset:64
	s_nop 0
	v_addc_co_u32_e32 v113, vcc, 0, v131, vcc
	ds_read_b128 v[96:99], v185
	ds_read_b128 v[100:103], v185 offset:1152
	global_store_dwordx4 v[112:113], v[104:107], off
	s_nop 1
	v_add_co_u32_e32 v104, vcc, s82, v130
	s_nop 1
	v_addc_co_u32_e32 v105, vcc, 0, v131, vcc
	global_store_dwordx4 v[104:105], v[108:111], off
	v_add_co_u32_e32 v104, vcc, s83, v130
	s_nop 1
	v_addc_co_u32_e32 v105, vcc, 0, v131, vcc
	s_waitcnt lgkmcnt(0)
	global_store_dwordx4 v[104:105], v[96:99], off
	s_nop 1
	v_add_co_u32_e32 v96, vcc, s91, v130
	s_nop 1
	v_addc_co_u32_e32 v97, vcc, 0, v131, vcc
	global_store_dwordx4 v[96:97], v[100:103], off
	ds_read_b128 v[96:99], v153 offset:49152
	ds_read_b128 v[100:103], v153 offset:50176
	ds_read_b128 v[104:107], v152 offset:49152
	ds_read_b128 v[108:111], v152 offset:50176
	ds_read_b128 v[112:115], v151 offset:49152
	ds_read_b128 v[116:119], v151 offset:50176
	ds_read_b128 v[120:123], v150 offset:49152
	ds_read_b128 v[124:127], v150 offset:50176
	s_barrier
	s_waitcnt lgkmcnt(0)
	s_setprio 1
	s_waitcnt lgkmcnt(0)
	v_mfma_f32_16x16x32_bf16 v[32:35], v[8:11], v[96:99], v[32:35]
	v_mfma_f32_16x16x32_bf16 v[36:39], v[76:79], v[96:99], v[36:39]
	v_mfma_f32_16x16x32_bf16 v[40:43], v[8:11], v[104:107], v[40:43]
	v_mfma_f32_16x16x32_bf16 v[130:133], v[76:79], v[104:107], v[44:47]
	v_mfma_f32_16x16x32_bf16 v[150:153], v[8:11], v[112:115], v[48:51]
	v_mfma_f32_16x16x32_bf16 v[52:55], v[76:79], v[112:115], v[52:55]
	v_mfma_f32_16x16x32_bf16 v[8:11], v[8:11], v[120:123], v[56:59]
	v_mfma_f32_16x16x32_bf16 v[60:63], v[76:79], v[120:123], v[60:63]
	v_mfma_f32_16x16x32_bf16 v[56:59], v[0:3], v[100:103], v[32:35]
	v_mfma_f32_16x16x32_bf16 v[48:51], v[72:75], v[100:103], v[36:39]
	v_mfma_f32_16x16x32_bf16 v[44:47], v[0:3], v[108:111], v[40:43]
	v_mfma_f32_16x16x32_bf16 v[40:43], v[72:75], v[108:111], v[130:133]
	v_mfma_f32_16x16x32_bf16 v[36:39], v[0:3], v[116:119], v[150:153]
	v_mfma_f32_16x16x32_bf16 v[32:35], v[72:75], v[116:119], v[52:55]
	v_mfma_f32_16x16x32_bf16 v[8:11], v[0:3], v[124:127], v[8:11]
	v_mfma_f32_16x16x32_bf16 v[0:3], v[72:75], v[124:127], v[60:63]
	s_setprio 0
	s_setprio 1
	v_mfma_f32_16x16x32_bf16 v[4:7], v[88:91], v[96:99], v[4:7]
	v_mfma_f32_16x16x32_bf16 v[12:15], v[92:95], v[96:99], v[12:15]
	v_mfma_f32_16x16x32_bf16 v[16:19], v[88:91], v[104:107], v[16:19]
	v_mfma_f32_16x16x32_bf16 v[20:23], v[92:95], v[104:107], v[20:23]
	v_mfma_f32_16x16x32_bf16 v[72:75], v[88:91], v[112:115], v[24:27]
	v_mfma_f32_16x16x32_bf16 v[76:79], v[92:95], v[112:115], v[28:31]
	v_mfma_f32_16x16x32_bf16 v[64:67], v[88:91], v[120:123], v[64:67]
	v_mfma_f32_16x16x32_bf16 v[68:71], v[92:95], v[120:123], v[68:71]
	v_mfma_f32_16x16x32_bf16 v[60:63], v[80:83], v[100:103], v[4:7]
	v_mfma_f32_16x16x32_bf16 v[52:55], v[84:87], v[100:103], v[12:15]
	v_mfma_f32_16x16x32_bf16 v[28:31], v[80:83], v[108:111], v[16:19]
	v_mfma_f32_16x16x32_bf16 v[24:27], v[84:87], v[108:111], v[20:23]
	v_mfma_f32_16x16x32_bf16 v[20:23], v[80:83], v[116:119], v[72:75]
	v_mfma_f32_16x16x32_bf16 v[16:19], v[84:87], v[116:119], v[76:79]
	v_mfma_f32_16x16x32_bf16 v[12:15], v[80:83], v[124:127], v[64:67]
	v_mfma_f32_16x16x32_bf16 v[4:7], v[84:87], v[124:127], v[68:71]
	s_setprio 0
	v_cmp_gt_u32_e32 vcc, s92, v136
	s_barrier
	s_and_saveexec_b64 s[66:67], vcc
	s_cbranch_execz .LBB0_468
	s_barrier

.LBB0_521:
	ds_read_b128 v[140:143], v138
	ds_read_b128 v[144:147], v138 offset:1024
	ds_read_b128 v[148:151], v138 offset:2048
	ds_read_b128 v[152:155], v138 offset:3072
	ds_read_b128 v[156:159], v193
	ds_read_b128 v[160:163], v193 offset:1024
	ds_read_b128 v[194:197], v192
	ds_read_b128 v[198:201], v192 offset:1024
	ds_read_b128 v[202:205], v191
	ds_read_b128 v[206:209], v191 offset:1024
	ds_read_b128 v[210:213], v190
	ds_read_b128 v[214:217], v190 offset:1024
	s_waitcnt lgkmcnt(8)
	s_waitcnt vmcnt(10)
	s_barrier
	s_waitcnt lgkmcnt(0)
	s_waitcnt lgkmcnt(0)
	v_mfma_f32_16x16x32_bf16 v[124:127], v[140:143], v[156:159], v[124:127]
	v_mfma_f32_16x16x32_bf16 v[120:123], v[148:151], v[156:159], v[120:123]
	v_mfma_f32_16x16x32_bf16 v[116:119], v[140:143], v[194:197], v[116:119]
	v_mfma_f32_16x16x32_bf16 v[112:115], v[148:151], v[194:197], v[112:115]
	v_mfma_f32_16x16x32_bf16 v[108:111], v[140:143], v[202:205], v[108:111]
	v_mfma_f32_16x16x32_bf16 v[104:107], v[148:151], v[202:205], v[104:107]
	v_mfma_f32_16x16x32_bf16 v[100:103], v[140:143], v[210:213], v[100:103]
	v_mfma_f32_16x16x32_bf16 v[96:99], v[148:151], v[210:213], v[96:99]
	v_mfma_f32_16x16x32_bf16 v[124:127], v[144:147], v[160:163], v[124:127]
	v_mfma_f32_16x16x32_bf16 v[120:123], v[152:155], v[160:163], v[120:123]
	v_mfma_f32_16x16x32_bf16 v[116:119], v[144:147], v[198:201], v[116:119]
	v_mfma_f32_16x16x32_bf16 v[112:115], v[152:155], v[198:201], v[112:115]
	v_mfma_f32_16x16x32_bf16 v[108:111], v[144:147], v[206:209], v[108:111]
	v_mfma_f32_16x16x32_bf16 v[104:107], v[152:155], v[206:209], v[104:107]
	v_mfma_f32_16x16x32_bf16 v[100:103], v[144:147], v[214:217], v[100:103]
	v_mfma_f32_16x16x32_bf16 v[96:99], v[152:155], v[214:217], v[96:99]
	s_barrier
	s_add_i32 s36, s98, 0x10000
	v_lshl_add_u64 v[234:235], s[58:59], 0, v[164:165]
	s_mov_b32 m0, s36
	s_add_i32 s36, s98, 0x12000
	ds_read_b128 v[218:221], v135
	ds_read_b128 v[222:225], v135 offset:1024
	ds_read_b128 v[226:229], v135 offset:2048
	ds_read_b128 v[230:233], v135 offset:3072
	global_load_lds_dwordx4 v[234:235], off
	v_lshl_add_u64 v[236:237], v[234:235], 0, s[2:3]
	s_mov_b32 m0, s36
	s_nop 0
	global_load_lds_dwordx4 v[236:237], off
	s_mov_b32 s36, s98
	v_lshl_add_u64 v[236:237], v[128:129], 0, s[22:23]
	s_mov_b32 m0, s36
	s_add_i32 s36, s98, 0x2000
	global_load_lds_dwordx4 v[236:237], off
	v_lshl_add_u64 v[236:237], v[128:129], 0, s[24:25]
	s_mov_b32 m0, s36
	s_nop 0
	global_load_lds_dwordx4 v[236:237], off
	s_waitcnt vmcnt(12)
	s_barrier
	s_waitcnt lgkmcnt(0)
	s_waitcnt lgkmcnt(0)
	v_mfma_f32_16x16x32_bf16 v[92:95], v[218:221], v[156:159], v[92:95]
	v_mfma_f32_16x16x32_bf16 v[88:91], v[226:229], v[156:159], v[88:91]
	v_mfma_f32_16x16x32_bf16 v[84:87], v[218:221], v[194:197], v[84:87]
	v_mfma_f32_16x16x32_bf16 v[80:83], v[226:229], v[194:197], v[80:83]
	v_mfma_f32_16x16x32_bf16 v[76:79], v[218:221], v[202:205], v[76:79]
	v_mfma_f32_16x16x32_bf16 v[72:75], v[226:229], v[202:205], v[72:75]
	v_mfma_f32_16x16x32_bf16 v[68:71], v[218:221], v[210:213], v[68:71]
	v_mfma_f32_16x16x32_bf16 v[64:67], v[226:229], v[210:213], v[64:67]
	v_mfma_f32_16x16x32_bf16 v[92:95], v[222:225], v[160:163], v[92:95]
	v_mfma_f32_16x16x32_bf16 v[88:91], v[230:233], v[160:163], v[88:91]
	v_mfma_f32_16x16x32_bf16 v[84:87], v[222:225], v[198:201], v[84:87]
	v_mfma_f32_16x16x32_bf16 v[80:83], v[230:233], v[198:201], v[80:83]
	v_mfma_f32_16x16x32_bf16 v[76:79], v[222:225], v[206:209], v[76:79]
	v_mfma_f32_16x16x32_bf16 v[72:75], v[230:233], v[206:209], v[72:75]
	v_mfma_f32_16x16x32_bf16 v[68:71], v[222:225], v[214:217], v[68:71]
	v_mfma_f32_16x16x32_bf16 v[64:67], v[230:233], v[214:217], v[64:67]
	s_barrier
	ds_read_b128 v[156:159], v193 offset:16384
	ds_read_b128 v[160:163], v193 offset:17408
	ds_read_b128 v[194:197], v192 offset:16384
	ds_read_b128 v[198:201], v192 offset:17408
	ds_read_b128 v[202:205], v191 offset:16384
	ds_read_b128 v[206:209], v191 offset:17408
	ds_read_b128 v[210:213], v190 offset:16384
	ds_read_b128 v[214:217], v190 offset:17408
	s_add_i32 s36, s98, 0x14000
	v_lshl_add_u64 v[236:237], v[234:235], 0, s[6:7]
	s_mov_b32 m0, s36
	s_add_i32 s36, s98, 0x16000
	global_load_lds_dwordx4 v[236:237], off
	v_lshl_add_u64 v[236:237], v[234:235], 0, s[8:9]
	s_mov_b32 m0, s36
	s_nop 0
	global_load_lds_dwordx4 v[236:237], off
	s_barrier
	s_waitcnt lgkmcnt(0)
	s_waitcnt lgkmcnt(0)
	v_mfma_f32_16x16x32_bf16 v[60:63], v[140:143], v[156:159], v[60:63]
	v_mfma_f32_16x16x32_bf16 v[56:59], v[148:151], v[156:159], v[56:59]
	v_mfma_f32_16x16x32_bf16 v[52:55], v[140:143], v[194:197], v[52:55]
	v_mfma_f32_16x16x32_bf16 v[48:51], v[148:151], v[194:197], v[48:51]
	v_mfma_f32_16x16x32_bf16 v[44:47], v[140:143], v[202:205], v[44:47]
	v_mfma_f32_16x16x32_bf16 v[40:43], v[148:151], v[202:205], v[40:43]
	v_mfma_f32_16x16x32_bf16 v[36:39], v[140:143], v[210:213], v[36:39]
	v_mfma_f32_16x16x32_bf16 v[32:35], v[148:151], v[210:213], v[32:35]
	v_mfma_f32_16x16x32_bf16 v[60:63], v[144:147], v[160:163], v[60:63]
	v_mfma_f32_16x16x32_bf16 v[56:59], v[152:155], v[160:163], v[56:59]
	v_mfma_f32_16x16x32_bf16 v[52:55], v[144:147], v[198:201], v[52:55]
	v_mfma_f32_16x16x32_bf16 v[48:51], v[152:155], v[198:201], v[48:51]
	v_mfma_f32_16x16x32_bf16 v[44:47], v[144:147], v[206:209], v[44:47]
	v_mfma_f32_16x16x32_bf16 v[40:43], v[152:155], v[206:209], v[40:43]
	v_mfma_f32_16x16x32_bf16 v[36:39], v[144:147], v[214:217], v[36:39]
	v_mfma_f32_16x16x32_bf16 v[32:35], v[152:155], v[214:217], v[32:35]
	s_barrier
	s_add_i32 s36, s98, 0x4000
	v_lshl_add_u64 v[142:143], v[128:129], 0, s[26:27]
	s_mov_b32 m0, s36
	s_add_i32 s36, s98, 0x6000
	global_load_lds_dwordx4 v[142:143], off
	s_mov_b32 m0, s36
	s_nop 0
	global_load_lds_dwordx4 v[128:129], off
	s_waitcnt vmcnt(12)
	s_barrier
	v_mfma_f32_16x16x32_bf16 v[28:31], v[218:221], v[156:159], v[28:31]
	v_mfma_f32_16x16x32_bf16 v[24:27], v[226:229], v[156:159], v[24:27]
	v_mfma_f32_16x16x32_bf16 v[20:23], v[218:221], v[194:197], v[20:23]
	v_mfma_f32_16x16x32_bf16 v[16:19], v[226:229], v[194:197], v[16:19]
	v_mfma_f32_16x16x32_bf16 v[12:15], v[218:221], v[202:205], v[12:15]
	v_mfma_f32_16x16x32_bf16 v[8:11], v[226:229], v[202:205], v[8:11]
	v_mfma_f32_16x16x32_bf16 v[4:7], v[218:221], v[210:213], v[4:7]
	v_mfma_f32_16x16x32_bf16 v[0:3], v[226:229], v[210:213], v[0:3]
	v_mfma_f32_16x16x32_bf16 v[28:31], v[222:225], v[160:163], v[28:31]
	v_mfma_f32_16x16x32_bf16 v[24:27], v[230:233], v[160:163], v[24:27]
	v_mfma_f32_16x16x32_bf16 v[20:23], v[222:225], v[198:201], v[20:23]
	v_mfma_f32_16x16x32_bf16 v[16:19], v[230:233], v[198:201], v[16:19]
	v_mfma_f32_16x16x32_bf16 v[12:15], v[222:225], v[206:209], v[12:15]
	v_mfma_f32_16x16x32_bf16 v[8:11], v[230:233], v[206:209], v[8:11]
	v_mfma_f32_16x16x32_bf16 v[4:7], v[222:225], v[214:217], v[4:7]
	v_mfma_f32_16x16x32_bf16 v[0:3], v[230:233], v[214:217], v[0:3]
	s_barrier
	ds_read_b128 v[140:143], v130
	ds_read_b128 v[144:147], v130 offset:1024
	ds_read_b128 v[148:151], v130 offset:2048
	ds_read_b128 v[152:155], v130 offset:3072
	ds_read_b128 v[156:159], v193 offset:32768
	ds_read_b128 v[160:163], v193 offset:33792
	ds_read_b128 v[194:197], v192 offset:32768
	ds_read_b128 v[198:201], v192 offset:33792
	ds_read_b128 v[202:205], v191 offset:32768
	ds_read_b128 v[206:209], v191 offset:33792
	ds_read_b128 v[210:213], v190 offset:32768
	ds_read_b128 v[214:217], v190 offset:33792
	s_waitcnt lgkmcnt(8)
	s_waitcnt vmcnt(10)
	s_barrier
	s_waitcnt lgkmcnt(0)
	s_waitcnt lgkmcnt(0)
	v_mfma_f32_16x16x32_bf16 v[124:127], v[140:143], v[156:159], v[124:127]
	v_mfma_f32_16x16x32_bf16 v[120:123], v[148:151], v[156:159], v[120:123]
	v_mfma_f32_16x16x32_bf16 v[116:119], v[140:143], v[194:197], v[116:119]
	v_mfma_f32_16x16x32_bf16 v[112:115], v[148:151], v[194:197], v[112:115]
	v_mfma_f32_16x16x32_bf16 v[108:111], v[140:143], v[202:205], v[108:111]
	v_mfma_f32_16x16x32_bf16 v[104:107], v[148:151], v[202:205], v[104:107]
	v_mfma_f32_16x16x32_bf16 v[100:103], v[140:143], v[210:213], v[100:103]
	v_mfma_f32_16x16x32_bf16 v[96:99], v[148:151], v[210:213], v[96:99]
	v_mfma_f32_16x16x32_bf16 v[124:127], v[144:147], v[160:163], v[124:127]
	v_mfma_f32_16x16x32_bf16 v[120:123], v[152:155], v[160:163], v[120:123]
	v_mfma_f32_16x16x32_bf16 v[116:119], v[144:147], v[198:201], v[116:119]
	v_mfma_f32_16x16x32_bf16 v[112:115], v[152:155], v[198:201], v[112:115]
	v_mfma_f32_16x16x32_bf16 v[108:111], v[144:147], v[206:209], v[108:111]
	v_mfma_f32_16x16x32_bf16 v[104:107], v[152:155], v[206:209], v[104:107]
	v_mfma_f32_16x16x32_bf16 v[100:103], v[144:147], v[214:217], v[100:103]
	v_mfma_f32_16x16x32_bf16 v[96:99], v[152:155], v[214:217], v[96:99]
	s_barrier
	s_add_i32 s36, s98, 0x18000
	v_lshl_add_u64 v[234:235], s[46:47], 0, v[164:165]
	s_mov_b32 m0, s36
	s_add_i32 s36, s98, 0x1a000
	ds_read_b128 v[218:221], v132
	ds_read_b128 v[222:225], v132 offset:1024
	ds_read_b128 v[226:229], v132 offset:2048
	ds_read_b128 v[230:233], v132 offset:3072
	global_load_lds_dwordx4 v[234:235], off
	v_lshl_add_u64 v[236:237], v[234:235], 0, s[2:3]
	s_mov_b32 m0, s36
	s_nop 0
	global_load_lds_dwordx4 v[236:237], off
	s_add_i32 s36, s98, 0x8000
	v_lshl_add_u64 v[236:237], v[128:129], 0, s[28:29]
	s_mov_b32 m0, s36
	s_add_i32 s36, s98, 0xa000
	global_load_lds_dwordx4 v[236:237], off
	v_lshl_add_u64 v[236:237], v[128:129], 0, s[30:31]
	s_mov_b32 m0, s36
	s_nop 0
	global_load_lds_dwordx4 v[236:237], off
	s_waitcnt vmcnt(12)
	s_barrier
	s_waitcnt lgkmcnt(0)
	s_waitcnt lgkmcnt(0)
	v_mfma_f32_16x16x32_bf16 v[92:95], v[218:221], v[156:159], v[92:95]
	v_mfma_f32_16x16x32_bf16 v[88:91], v[226:229], v[156:159], v[88:91]
	v_mfma_f32_16x16x32_bf16 v[84:87], v[218:221], v[194:197], v[84:87]
	v_mfma_f32_16x16x32_bf16 v[80:83], v[226:229], v[194:197], v[80:83]
	v_mfma_f32_16x16x32_bf16 v[76:79], v[218:221], v[202:205], v[76:79]
	v_mfma_f32_16x16x32_bf16 v[72:75], v[226:229], v[202:205], v[72:75]
	v_mfma_f32_16x16x32_bf16 v[68:71], v[218:221], v[210:213], v[68:71]
	v_mfma_f32_16x16x32_bf16 v[64:67], v[226:229], v[210:213], v[64:67]
	v_mfma_f32_16x16x32_bf16 v[92:95], v[222:225], v[160:163], v[92:95]
	v_mfma_f32_16x16x32_bf16 v[88:91], v[230:233], v[160:163], v[88:91]
	v_mfma_f32_16x16x32_bf16 v[84:87], v[222:225], v[198:201], v[84:87]
	v_mfma_f32_16x16x32_bf16 v[80:83], v[230:233], v[198:201], v[80:83]
	v_mfma_f32_16x16x32_bf16 v[76:79], v[222:225], v[206:209], v[76:79]
	v_mfma_f32_16x16x32_bf16 v[72:75], v[230:233], v[206:209], v[72:75]
	v_mfma_f32_16x16x32_bf16 v[68:71], v[222:225], v[214:217], v[68:71]
	v_mfma_f32_16x16x32_bf16 v[64:67], v[230:233], v[214:217], v[64:67]
	s_barrier
	ds_read_b128 v[156:159], v193 offset:49152
	ds_read_b128 v[160:163], v193 offset:50176
	ds_read_b128 v[194:197], v192 offset:49152
	ds_read_b128 v[198:201], v192 offset:50176
	ds_read_b128 v[202:205], v191 offset:49152
	ds_read_b128 v[206:209], v191 offset:50176
	ds_read_b128 v[210:213], v190 offset:49152
	ds_read_b128 v[214:217], v190 offset:50176
	s_add_i32 s36, s98, 0x1c000
	v_lshl_add_u64 v[236:237], v[234:235], 0, s[6:7]
	s_mov_b32 m0, s36
	s_add_i32 s36, s98, 0x1e000
	global_load_lds_dwordx4 v[236:237], off
	v_lshl_add_u64 v[236:237], v[234:235], 0, s[8:9]
	s_mov_b32 m0, s36
	s_nop 0
	global_load_lds_dwordx4 v[236:237], off
	s_barrier
	s_waitcnt lgkmcnt(0)
	s_waitcnt lgkmcnt(0)
	v_mfma_f32_16x16x32_bf16 v[60:63], v[140:143], v[156:159], v[60:63]
	v_mfma_f32_16x16x32_bf16 v[56:59], v[148:151], v[156:159], v[56:59]
	v_mfma_f32_16x16x32_bf16 v[52:55], v[140:143], v[194:197], v[52:55]
	v_mfma_f32_16x16x32_bf16 v[48:51], v[148:151], v[194:197], v[48:51]
	v_mfma_f32_16x16x32_bf16 v[44:47], v[140:143], v[202:205], v[44:47]
	v_mfma_f32_16x16x32_bf16 v[40:43], v[148:151], v[202:205], v[40:43]
	v_mfma_f32_16x16x32_bf16 v[36:39], v[140:143], v[210:213], v[36:39]
	v_mfma_f32_16x16x32_bf16 v[32:35], v[148:151], v[210:213], v[32:35]
	v_mfma_f32_16x16x32_bf16 v[60:63], v[144:147], v[160:163], v[60:63]
	v_mfma_f32_16x16x32_bf16 v[56:59], v[152:155], v[160:163], v[56:59]
	v_mfma_f32_16x16x32_bf16 v[52:55], v[144:147], v[198:201], v[52:55]
	v_mfma_f32_16x16x32_bf16 v[48:51], v[152:155], v[198:201], v[48:51]
	v_mfma_f32_16x16x32_bf16 v[44:47], v[144:147], v[206:209], v[44:47]
	v_mfma_f32_16x16x32_bf16 v[40:43], v[152:155], v[206:209], v[40:43]
	v_mfma_f32_16x16x32_bf16 v[36:39], v[144:147], v[214:217], v[36:39]
	v_mfma_f32_16x16x32_bf16 v[32:35], v[152:155], v[214:217], v[32:35]
	s_barrier
	v_lshl_add_u64 v[128:129], v[128:129], 0, s[34:35]
	s_add_i32 s36, s98, 0xc000
	v_lshl_add_u64 v[142:143], v[128:129], 0, s[18:19]
	s_mov_b32 m0, s36
	s_add_i32 s36, s98, 0xe000
	global_load_lds_dwordx4 v[142:143], off
	v_lshl_add_u64 v[142:143], v[128:129], 0, s[20:21]
	s_mov_b32 m0, s36
	s_nop 0
	global_load_lds_dwordx4 v[142:143], off
	s_waitcnt vmcnt(12)
	s_barrier
	v_mfma_f32_16x16x32_bf16 v[28:31], v[218:221], v[156:159], v[28:31]
	v_mfma_f32_16x16x32_bf16 v[24:27], v[226:229], v[156:159], v[24:27]
	v_mfma_f32_16x16x32_bf16 v[20:23], v[218:221], v[194:197], v[20:23]
	v_mfma_f32_16x16x32_bf16 v[16:19], v[226:229], v[194:197], v[16:19]
	v_mfma_f32_16x16x32_bf16 v[12:15], v[218:221], v[202:205], v[12:15]
	v_mfma_f32_16x16x32_bf16 v[8:11], v[226:229], v[202:205], v[8:11]
	v_mfma_f32_16x16x32_bf16 v[4:7], v[218:221], v[210:213], v[4:7]
	v_mfma_f32_16x16x32_bf16 v[0:3], v[226:229], v[210:213], v[0:3]
	v_mfma_f32_16x16x32_bf16 v[28:31], v[222:225], v[160:163], v[28:31]
	v_mfma_f32_16x16x32_bf16 v[24:27], v[230:233], v[160:163], v[24:27]
	v_mfma_f32_16x16x32_bf16 v[20:23], v[222:225], v[198:201], v[20:23]
	v_mfma_f32_16x16x32_bf16 v[16:19], v[230:233], v[198:201], v[16:19]
	v_mfma_f32_16x16x32_bf16 v[12:15], v[222:225], v[206:209], v[12:15]
	v_mfma_f32_16x16x32_bf16 v[8:11], v[230:233], v[206:209], v[8:11]
	v_mfma_f32_16x16x32_bf16 v[4:7], v[222:225], v[214:217], v[4:7]
	v_mfma_f32_16x16x32_bf16 v[0:3], v[230:233], v[214:217], v[0:3]
	s_add_i32 s14, s14, 2
	s_add_u32 s46, s46, s56
	s_addc_u32 s47, s47, s57
	s_add_u32 s58, s58, s56
	s_addc_u32 s59, s59, s57
	s_cmp_lt_u32 s14, 28
	s_barrier
	s_cbranch_scc1 .LBB0_521
	s_lshl_b32 s14, s60, 3
	s_or_b32 s80, s61, s14
	s_lshl_b32 s46, s80, 8
	v_lshlrev_b32_e32 v128, 3, v131
	v_lshlrev_b32_e32 v129, 5, v131
	s_or_b32 s14, s46, 0x80
	v_and_b32_e32 v128, 0x7fff0, v128
	v_and_b32_e32 v129, 32, v129
	s_lshl_b64 s[56:57], s[14:15], 13
	v_add_u32_e32 v129, v129, v134
	v_add_lshl_u32 v128, v133, v128, 13
	s_add_u32 s56, s40, s56
	v_lshl_add_u32 v164, v129, 1, v128
	s_addc_u32 s57, s41, s57
	v_lshl_add_u64 v[128:129], s[56:57], 0, v[164:165]
	v_readfirstlane_b32 s14, v137
	ds_read_b128 v[140:143], v138
	ds_read_b128 v[144:147], v138 offset:1024
	ds_read_b128 v[148:151], v138 offset:2048
	ds_read_b128 v[152:155], v138 offset:3072
	ds_read_b128 v[156:159], v193
	ds_read_b128 v[160:163], v193 offset:1024
	ds_read_b128 v[194:197], v192
	ds_read_b128 v[198:201], v192 offset:1024
	ds_read_b128 v[202:205], v191
	ds_read_b128 v[206:209], v191 offset:1024
	ds_read_b128 v[210:213], v190
	ds_read_b128 v[214:217], v190 offset:1024
	v_lshl_add_u64 v[138:139], v[128:129], 0, s[38:39]
	s_mov_b32 m0, s14
	v_readfirstlane_b32 s14, v136
	v_lshl_add_u64 v[128:129], v[128:129], 0, s[44:45]
	s_mov_b32 m0, s14
	s_mov_b32 s47, s15
	s_mul_i32 s99, s76, s84
	s_add_i32 s99, s99, s33
	s_cmpk_lt_u32 s99, 0x400
	s_cbranch_scc1 .Lxt12_has
	s_mov_b32 s99, 0
	s_branch .Lxt12_set

.LBB0_561:
	ds_read_b128 v[162:165], v161
	ds_read_b128 v[166:169], v161 offset:1024
	ds_read_b128 v[170:173], v161 offset:2048
	ds_read_b128 v[174:177], v161 offset:3072
	ds_read_b128 v[178:181], v152
	ds_read_b128 v[182:185], v152 offset:1024
	ds_read_b128 v[186:189], v151
	ds_read_b128 v[190:193], v151 offset:1024
	ds_read_b128 v[194:197], v150
	ds_read_b128 v[198:201], v150 offset:1024
	ds_read_b128 v[202:205], v149
	ds_read_b128 v[206:209], v149 offset:1024
	s_waitcnt lgkmcnt(8)
	s_waitcnt vmcnt(10)
	s_barrier
	s_waitcnt lgkmcnt(0)
	s_waitcnt lgkmcnt(0)
	v_mfma_f32_16x16x32_bf16 v[124:127], v[162:165], v[178:181], v[124:127]
	v_mfma_f32_16x16x32_bf16 v[120:123], v[170:173], v[178:181], v[120:123]
	v_mfma_f32_16x16x32_bf16 v[116:119], v[162:165], v[186:189], v[116:119]
	v_mfma_f32_16x16x32_bf16 v[112:115], v[170:173], v[186:189], v[112:115]
	v_mfma_f32_16x16x32_bf16 v[108:111], v[162:165], v[194:197], v[108:111]
	v_mfma_f32_16x16x32_bf16 v[104:107], v[170:173], v[194:197], v[104:107]
	v_mfma_f32_16x16x32_bf16 v[100:103], v[162:165], v[202:205], v[100:103]
	v_mfma_f32_16x16x32_bf16 v[96:99], v[170:173], v[202:205], v[96:99]
	v_mfma_f32_16x16x32_bf16 v[124:127], v[166:169], v[182:185], v[124:127]
	v_mfma_f32_16x16x32_bf16 v[120:123], v[174:177], v[182:185], v[120:123]
	v_mfma_f32_16x16x32_bf16 v[116:119], v[166:169], v[190:193], v[116:119]
	v_mfma_f32_16x16x32_bf16 v[112:115], v[174:177], v[190:193], v[112:115]
	v_mfma_f32_16x16x32_bf16 v[108:111], v[166:169], v[198:201], v[108:111]
	v_mfma_f32_16x16x32_bf16 v[104:107], v[174:177], v[198:201], v[104:107]
	v_mfma_f32_16x16x32_bf16 v[100:103], v[166:169], v[206:209], v[100:103]
	v_mfma_f32_16x16x32_bf16 v[96:99], v[174:177], v[206:209], v[96:99]
	s_barrier
	s_add_i32 s36, s98, 0x10000
	v_lshl_add_u64 v[226:227], v[130:131], 0, s[26:27]
	s_mov_b32 m0, s36
	s_add_i32 s36, s98, 0x12000
	ds_read_b128 v[210:213], v158
	ds_read_b128 v[214:217], v158 offset:1024
	ds_read_b128 v[218:221], v158 offset:2048
	ds_read_b128 v[222:225], v158 offset:3072
	global_load_lds_dwordx4 v[226:227], off
	v_lshl_add_u64 v[226:227], v[130:131], 0, s[28:29]
	s_mov_b32 m0, s36
	s_add_i32 s68, s68, 2
	global_load_lds_dwordx4 v[226:227], off
	s_mov_b32 s36, s98
	v_lshl_add_u64 v[226:227], v[132:133], 0, s[30:31]
	s_mov_b32 m0, s36
	s_add_i32 s36, s98, 0x2000
	global_load_lds_dwordx4 v[226:227], off
	v_lshl_add_u64 v[226:227], v[132:133], 0, s[34:35]
	s_mov_b32 m0, s36
	s_nop 0
	global_load_lds_dwordx4 v[226:227], off
	s_waitcnt vmcnt(12)
	s_barrier
	s_waitcnt lgkmcnt(0)
	s_waitcnt lgkmcnt(0)
	v_mfma_f32_16x16x32_bf16 v[92:95], v[210:213], v[178:181], v[92:95]
	v_mfma_f32_16x16x32_bf16 v[88:91], v[218:221], v[178:181], v[88:91]
	v_mfma_f32_16x16x32_bf16 v[84:87], v[210:213], v[186:189], v[84:87]
	v_mfma_f32_16x16x32_bf16 v[80:83], v[218:221], v[186:189], v[80:83]
	v_mfma_f32_16x16x32_bf16 v[76:79], v[210:213], v[194:197], v[76:79]
	v_mfma_f32_16x16x32_bf16 v[72:75], v[218:221], v[194:197], v[72:75]
	v_mfma_f32_16x16x32_bf16 v[68:71], v[210:213], v[202:205], v[68:71]
	v_mfma_f32_16x16x32_bf16 v[64:67], v[218:221], v[202:205], v[64:67]
	v_mfma_f32_16x16x32_bf16 v[92:95], v[214:217], v[182:185], v[92:95]
	v_mfma_f32_16x16x32_bf16 v[88:91], v[222:225], v[182:185], v[88:91]
	v_mfma_f32_16x16x32_bf16 v[84:87], v[214:217], v[190:193], v[84:87]
	v_mfma_f32_16x16x32_bf16 v[80:83], v[222:225], v[190:193], v[80:83]
	v_mfma_f32_16x16x32_bf16 v[76:79], v[214:217], v[198:201], v[76:79]
	v_mfma_f32_16x16x32_bf16 v[72:75], v[222:225], v[198:201], v[72:75]
	v_mfma_f32_16x16x32_bf16 v[68:71], v[214:217], v[206:209], v[68:71]
	v_mfma_f32_16x16x32_bf16 v[64:67], v[222:225], v[206:209], v[64:67]
	s_barrier
	ds_read_b128 v[178:181], v152 offset:16384
	ds_read_b128 v[182:185], v152 offset:17408
	ds_read_b128 v[186:189], v151 offset:16384
	ds_read_b128 v[190:193], v151 offset:17408
	ds_read_b128 v[194:197], v150 offset:16384
	ds_read_b128 v[198:201], v150 offset:17408
	ds_read_b128 v[202:205], v149 offset:16384
	ds_read_b128 v[206:209], v149 offset:17408
	s_add_i32 s36, s98, 0x14000
	v_lshl_add_u64 v[226:227], v[130:131], 0, s[38:39]
	s_mov_b32 m0, s36
	s_add_i32 s36, s98, 0x16000
	global_load_lds_dwordx4 v[226:227], off
	v_lshl_add_u64 v[226:227], v[130:131], 0, s[44:45]
	s_mov_b32 m0, s36
	s_nop 0
	global_load_lds_dwordx4 v[226:227], off
	s_barrier
	s_waitcnt lgkmcnt(0)
	s_waitcnt lgkmcnt(0)
	v_mfma_f32_16x16x32_bf16 v[60:63], v[162:165], v[178:181], v[60:63]
	v_mfma_f32_16x16x32_bf16 v[56:59], v[170:173], v[178:181], v[56:59]
	v_mfma_f32_16x16x32_bf16 v[52:55], v[162:165], v[186:189], v[52:55]
	v_mfma_f32_16x16x32_bf16 v[48:51], v[170:173], v[186:189], v[48:51]
	v_mfma_f32_16x16x32_bf16 v[44:47], v[162:165], v[194:197], v[44:47]
	v_mfma_f32_16x16x32_bf16 v[40:43], v[170:173], v[194:197], v[40:43]
	v_mfma_f32_16x16x32_bf16 v[36:39], v[162:165], v[202:205], v[36:39]
	v_mfma_f32_16x16x32_bf16 v[32:35], v[170:173], v[202:205], v[32:35]
	v_mfma_f32_16x16x32_bf16 v[60:63], v[166:169], v[182:185], v[60:63]
	v_mfma_f32_16x16x32_bf16 v[56:59], v[174:177], v[182:185], v[56:59]
	v_mfma_f32_16x16x32_bf16 v[52:55], v[166:169], v[190:193], v[52:55]
	v_mfma_f32_16x16x32_bf16 v[48:51], v[174:177], v[190:193], v[48:51]
	v_mfma_f32_16x16x32_bf16 v[44:47], v[166:169], v[198:201], v[44:47]
	v_mfma_f32_16x16x32_bf16 v[40:43], v[174:177], v[198:201], v[40:43]
	v_mfma_f32_16x16x32_bf16 v[36:39], v[166:169], v[206:209], v[36:39]
	v_mfma_f32_16x16x32_bf16 v[32:35], v[174:177], v[206:209], v[32:35]
	s_barrier
	s_add_i32 s36, s98, 0x4000
	v_lshl_add_u64 v[164:165], v[132:133], 0, s[46:47]
	s_mov_b32 m0, s36
	s_add_i32 s36, s98, 0x6000
	global_load_lds_dwordx4 v[164:165], off
	v_lshl_add_u64 v[164:165], v[132:133], 0, s[50:51]
	s_mov_b32 m0, s36
	s_nop 0
	global_load_lds_dwordx4 v[164:165], off
	s_waitcnt vmcnt(12)
	s_barrier
	v_mfma_f32_16x16x32_bf16 v[28:31], v[210:213], v[178:181], v[28:31]
	v_mfma_f32_16x16x32_bf16 v[24:27], v[218:221], v[178:181], v[24:27]
	v_mfma_f32_16x16x32_bf16 v[20:23], v[210:213], v[186:189], v[20:23]
	v_mfma_f32_16x16x32_bf16 v[16:19], v[218:221], v[186:189], v[16:19]
	v_mfma_f32_16x16x32_bf16 v[12:15], v[210:213], v[194:197], v[12:15]
	v_mfma_f32_16x16x32_bf16 v[8:11], v[218:221], v[194:197], v[8:11]
	v_mfma_f32_16x16x32_bf16 v[4:7], v[210:213], v[202:205], v[4:7]
	v_mfma_f32_16x16x32_bf16 v[0:3], v[218:221], v[202:205], v[0:3]
	v_mfma_f32_16x16x32_bf16 v[28:31], v[214:217], v[182:185], v[28:31]
	v_mfma_f32_16x16x32_bf16 v[24:27], v[222:225], v[182:185], v[24:27]
	v_mfma_f32_16x16x32_bf16 v[20:23], v[214:217], v[190:193], v[20:23]
	v_mfma_f32_16x16x32_bf16 v[16:19], v[222:225], v[190:193], v[16:19]
	v_mfma_f32_16x16x32_bf16 v[12:15], v[214:217], v[198:201], v[12:15]
	v_mfma_f32_16x16x32_bf16 v[8:11], v[222:225], v[198:201], v[8:11]
	v_mfma_f32_16x16x32_bf16 v[4:7], v[214:217], v[206:209], v[4:7]
	v_mfma_f32_16x16x32_bf16 v[0:3], v[222:225], v[206:209], v[0:3]
	s_barrier
	ds_read_b128 v[162:165], v154
	ds_read_b128 v[166:169], v154 offset:1024
	ds_read_b128 v[170:173], v154 offset:2048
	ds_read_b128 v[174:177], v154 offset:3072
	ds_read_b128 v[178:181], v152 offset:32768
	ds_read_b128 v[182:185], v152 offset:33792
	ds_read_b128 v[186:189], v151 offset:32768
	ds_read_b128 v[190:193], v151 offset:33792
	ds_read_b128 v[194:197], v150 offset:32768
	ds_read_b128 v[198:201], v150 offset:33792
	ds_read_b128 v[202:205], v149 offset:32768
	ds_read_b128 v[206:209], v149 offset:33792
	s_waitcnt lgkmcnt(8)
	s_waitcnt vmcnt(10)
	s_barrier
	s_waitcnt lgkmcnt(0)
	s_waitcnt lgkmcnt(0)
	v_mfma_f32_16x16x32_bf16 v[124:127], v[162:165], v[178:181], v[124:127]
	v_mfma_f32_16x16x32_bf16 v[120:123], v[170:173], v[178:181], v[120:123]
	v_mfma_f32_16x16x32_bf16 v[116:119], v[162:165], v[186:189], v[116:119]
	v_mfma_f32_16x16x32_bf16 v[112:115], v[170:173], v[186:189], v[112:115]
	v_mfma_f32_16x16x32_bf16 v[108:111], v[162:165], v[194:197], v[108:111]
	v_mfma_f32_16x16x32_bf16 v[104:107], v[170:173], v[194:197], v[104:107]
	v_mfma_f32_16x16x32_bf16 v[100:103], v[162:165], v[202:205], v[100:103]
	v_mfma_f32_16x16x32_bf16 v[96:99], v[170:173], v[202:205], v[96:99]
	v_mfma_f32_16x16x32_bf16 v[124:127], v[166:169], v[182:185], v[124:127]
	v_mfma_f32_16x16x32_bf16 v[120:123], v[174:177], v[182:185], v[120:123]
	v_mfma_f32_16x16x32_bf16 v[116:119], v[166:169], v[190:193], v[116:119]
	v_mfma_f32_16x16x32_bf16 v[112:115], v[174:177], v[190:193], v[112:115]
	v_mfma_f32_16x16x32_bf16 v[108:111], v[166:169], v[198:201], v[108:111]
	v_mfma_f32_16x16x32_bf16 v[104:107], v[174:177], v[198:201], v[104:107]
	v_mfma_f32_16x16x32_bf16 v[100:103], v[166:169], v[206:209], v[100:103]
	v_mfma_f32_16x16x32_bf16 v[96:99], v[174:177], v[206:209], v[96:99]
	s_barrier
	s_add_i32 s36, s98, 0x18000
	v_lshl_add_u64 v[226:227], v[130:131], 0, s[56:57]
	s_mov_b32 m0, s36
	s_add_i32 s36, s98, 0x1a000
	ds_read_b128 v[210:213], v153
	ds_read_b128 v[214:217], v153 offset:1024
	ds_read_b128 v[218:221], v153 offset:2048
	ds_read_b128 v[222:225], v153 offset:3072
	global_load_lds_dwordx4 v[226:227], off
	v_lshl_add_u64 v[226:227], v[130:131], 0, s[58:59]
	s_mov_b32 m0, s36
	s_nop 0
	global_load_lds_dwordx4 v[226:227], off
	s_add_i32 s36, s98, 0x8000
	v_lshl_add_u64 v[226:227], v[132:133], 0, s[60:61]
	s_mov_b32 m0, s36
	s_add_i32 s36, s98, 0xa000
	global_load_lds_dwordx4 v[226:227], off
	s_mov_b32 m0, s36
	s_nop 0
	global_load_lds_dwordx4 v[132:133], off
	s_waitcnt vmcnt(12)
	s_barrier
	s_waitcnt lgkmcnt(0)
	s_waitcnt lgkmcnt(0)
	v_mfma_f32_16x16x32_bf16 v[92:95], v[210:213], v[178:181], v[92:95]
	v_mfma_f32_16x16x32_bf16 v[88:91], v[218:221], v[178:181], v[88:91]
	v_mfma_f32_16x16x32_bf16 v[84:87], v[210:213], v[186:189], v[84:87]
	v_mfma_f32_16x16x32_bf16 v[80:83], v[218:221], v[186:189], v[80:83]
	v_mfma_f32_16x16x32_bf16 v[76:79], v[210:213], v[194:197], v[76:79]
	v_mfma_f32_16x16x32_bf16 v[72:75], v[218:221], v[194:197], v[72:75]
	v_mfma_f32_16x16x32_bf16 v[68:71], v[210:213], v[202:205], v[68:71]
	v_mfma_f32_16x16x32_bf16 v[64:67], v[218:221], v[202:205], v[64:67]
	v_mfma_f32_16x16x32_bf16 v[92:95], v[214:217], v[182:185], v[92:95]
	v_mfma_f32_16x16x32_bf16 v[88:91], v[222:225], v[182:185], v[88:91]
	v_mfma_f32_16x16x32_bf16 v[84:87], v[214:217], v[190:193], v[84:87]
	v_mfma_f32_16x16x32_bf16 v[80:83], v[222:225], v[190:193], v[80:83]
	v_mfma_f32_16x16x32_bf16 v[76:79], v[214:217], v[198:201], v[76:79]
	v_mfma_f32_16x16x32_bf16 v[72:75], v[222:225], v[198:201], v[72:75]
	v_mfma_f32_16x16x32_bf16 v[68:71], v[214:217], v[206:209], v[68:71]
	v_mfma_f32_16x16x32_bf16 v[64:67], v[222:225], v[206:209], v[64:67]
	s_barrier
	ds_read_b128 v[178:181], v152 offset:49152
	ds_read_b128 v[182:185], v152 offset:50176
	ds_read_b128 v[186:189], v151 offset:49152
	ds_read_b128 v[190:193], v151 offset:50176
	ds_read_b128 v[194:197], v150 offset:49152
	ds_read_b128 v[198:201], v150 offset:50176
	ds_read_b128 v[202:205], v149 offset:49152
	ds_read_b128 v[206:209], v149 offset:50176
	s_add_i32 s36, s98, 0x1c000
	v_lshl_add_u64 v[226:227], v[130:131], 0, s[60:61]
	s_mov_b32 m0, s36
	s_add_i32 s36, s98, 0x1e000
	global_load_lds_dwordx4 v[226:227], off
	s_mov_b32 m0, s36
	s_nop 0
	global_load_lds_dwordx4 v[130:131], off
	s_barrier
	s_waitcnt lgkmcnt(0)
	s_waitcnt lgkmcnt(0)
	v_mfma_f32_16x16x32_bf16 v[60:63], v[162:165], v[178:181], v[60:63]
	v_mfma_f32_16x16x32_bf16 v[56:59], v[170:173], v[178:181], v[56:59]
	v_mfma_f32_16x16x32_bf16 v[52:55], v[162:165], v[186:189], v[52:55]
	v_mfma_f32_16x16x32_bf16 v[48:51], v[170:173], v[186:189], v[48:51]
	v_mfma_f32_16x16x32_bf16 v[44:47], v[162:165], v[194:197], v[44:47]
	v_mfma_f32_16x16x32_bf16 v[40:43], v[170:173], v[194:197], v[40:43]
	v_mfma_f32_16x16x32_bf16 v[36:39], v[162:165], v[202:205], v[36:39]
	v_mfma_f32_16x16x32_bf16 v[32:35], v[170:173], v[202:205], v[32:35]
	v_mfma_f32_16x16x32_bf16 v[60:63], v[166:169], v[182:185], v[60:63]
	v_mfma_f32_16x16x32_bf16 v[56:59], v[174:177], v[182:185], v[56:59]
	v_mfma_f32_16x16x32_bf16 v[52:55], v[166:169], v[190:193], v[52:55]
	v_mfma_f32_16x16x32_bf16 v[48:51], v[174:177], v[190:193], v[48:51]
	v_mfma_f32_16x16x32_bf16 v[44:47], v[166:169], v[198:201], v[44:47]
	v_mfma_f32_16x16x32_bf16 v[40:43], v[174:177], v[198:201], v[40:43]
	v_mfma_f32_16x16x32_bf16 v[36:39], v[166:169], v[206:209], v[36:39]
	v_mfma_f32_16x16x32_bf16 v[32:35], v[174:177], v[206:209], v[32:35]
	s_barrier
	v_lshl_add_u64 v[132:133], v[132:133], 0, s[64:65]
	s_add_i32 s36, s98, 0xc000
	v_lshl_add_u64 v[164:165], v[132:133], 0, s[22:23]
	s_mov_b32 m0, s36
	s_add_i32 s36, s98, 0xe000
	global_load_lds_dwordx4 v[164:165], off
	v_lshl_add_u64 v[164:165], v[132:133], 0, s[24:25]
	s_mov_b32 m0, s36
	s_nop 0
	global_load_lds_dwordx4 v[164:165], off
	s_waitcnt vmcnt(12)
	s_barrier
	v_mfma_f32_16x16x32_bf16 v[28:31], v[210:213], v[178:181], v[28:31]
	v_mfma_f32_16x16x32_bf16 v[24:27], v[218:221], v[178:181], v[24:27]
	v_mfma_f32_16x16x32_bf16 v[20:23], v[210:213], v[186:189], v[20:23]
	v_mfma_f32_16x16x32_bf16 v[16:19], v[218:221], v[186:189], v[16:19]
	v_mfma_f32_16x16x32_bf16 v[12:15], v[210:213], v[194:197], v[12:15]
	v_mfma_f32_16x16x32_bf16 v[8:11], v[218:221], v[194:197], v[8:11]
	v_mfma_f32_16x16x32_bf16 v[4:7], v[210:213], v[202:205], v[4:7]
	v_mfma_f32_16x16x32_bf16 v[0:3], v[218:221], v[202:205], v[0:3]
	v_mfma_f32_16x16x32_bf16 v[28:31], v[214:217], v[182:185], v[28:31]
	v_mfma_f32_16x16x32_bf16 v[24:27], v[222:225], v[182:185], v[24:27]
	v_mfma_f32_16x16x32_bf16 v[20:23], v[214:217], v[190:193], v[20:23]
	v_mfma_f32_16x16x32_bf16 v[16:19], v[222:225], v[190:193], v[16:19]
	v_mfma_f32_16x16x32_bf16 v[12:15], v[214:217], v[198:201], v[12:15]
	v_mfma_f32_16x16x32_bf16 v[8:11], v[222:225], v[198:201], v[8:11]
	v_mfma_f32_16x16x32_bf16 v[4:7], v[214:217], v[206:209], v[4:7]
	v_mfma_f32_16x16x32_bf16 v[0:3], v[222:225], v[206:209], v[0:3]
	v_lshl_add_u64 v[130:131], v[130:131], 0, s[62:63]
	s_cmp_lt_u32 s68, s67
	s_barrier
	s_cbranch_scc1 .LBB0_561
	s_lshl_b32 s36, s86, 5
	s_lshl_b32 s37, s86, 8
	s_and_b32 s36, s36, 0x1800
	s_and_b32 s37, s37, 0x700
	s_or_b32 s96, s37, s36
	s_lshl_b32 s36, s96, 6
	s_add_u32 s36, s70, s36
	s_addc_u32 s37, s71, 0
	s_add_i32 s20, s20, -1
	s_lshl_b64 s[68:69], s[20:21], 20
	v_add_u32_e32 v128, v156, v157
	s_add_u32 s68, s36, s68
	v_or_b32_e32 v128, v128, v155
	s_addc_u32 s69, s37, s69
	v_lshl_add_u64 v[156:157], s[68:69], 0, v[128:129]
	v_readfirstlane_b32 s20, v160
	v_lshl_add_u64 v[206:207], v[156:157], 0, s[4:5]
	s_mov_b32 m0, s20
	v_readfirstlane_b32 s20, v159
	ds_read_b128 v[130:133], v161
	ds_read_b128 v[162:165], v161 offset:1024
	ds_read_b128 v[166:169], v161 offset:2048
	ds_read_b128 v[170:173], v161 offset:3072
	ds_read_b128 v[174:177], v152
	ds_read_b128 v[178:181], v152 offset:1024
	ds_read_b128 v[182:185], v151
	ds_read_b128 v[186:189], v151 offset:1024
	ds_read_b128 v[190:193], v150
	ds_read_b128 v[194:197], v150 offset:1024
	ds_read_b128 v[198:201], v149
	ds_read_b128 v[202:205], v149 offset:1024
	v_lshl_add_u64 v[156:157], v[156:157], 0, s[6:7]
	s_mov_b32 m0, s20
	s_nop 0
	s_waitcnt vmcnt(8)
	s_barrier
	s_waitcnt lgkmcnt(0)
	s_setprio 1
	s_waitcnt lgkmcnt(0)
	v_mfma_f32_16x16x32_bf16 v[124:127], v[130:133], v[174:177], v[124:127]
	v_mfma_f32_16x16x32_bf16 v[120:123], v[166:169], v[174:177], v[120:123]
	v_mfma_f32_16x16x32_bf16 v[116:119], v[130:133], v[182:185], v[116:119]
	v_mfma_f32_16x16x32_bf16 v[112:115], v[166:169], v[182:185], v[112:115]
	v_mfma_f32_16x16x32_bf16 v[108:111], v[130:133], v[190:193], v[108:111]
	v_mfma_f32_16x16x32_bf16 v[104:107], v[166:169], v[190:193], v[104:107]
	v_mfma_f32_16x16x32_bf16 v[100:103], v[130:133], v[198:201], v[100:103]
	v_mfma_f32_16x16x32_bf16 v[96:99], v[166:169], v[198:201], v[96:99]
	v_mfma_f32_16x16x32_bf16 v[124:127], v[162:165], v[178:181], v[124:127]
	v_mfma_f32_16x16x32_bf16 v[120:123], v[170:173], v[178:181], v[120:123]
	v_mfma_f32_16x16x32_bf16 v[116:119], v[162:165], v[186:189], v[116:119]
	v_mfma_f32_16x16x32_bf16 v[112:115], v[170:173], v[186:189], v[112:115]
	v_mfma_f32_16x16x32_bf16 v[108:111], v[162:165], v[194:197], v[108:111]
	v_mfma_f32_16x16x32_bf16 v[104:107], v[170:173], v[194:197], v[104:107]
	v_mfma_f32_16x16x32_bf16 v[100:103], v[162:165], v[202:205], v[100:103]
	v_mfma_f32_16x16x32_bf16 v[96:99], v[170:173], v[202:205], v[96:99]
	s_setprio 0
	s_barrier
	ds_read_b128 v[206:209], v158
	ds_read_b128 v[210:213], v158 offset:1024
	ds_read_b128 v[214:217], v158 offset:2048
	ds_read_b128 v[156:159], v158 offset:3072
	s_barrier
	s_waitcnt lgkmcnt(0)
	s_setprio 1
	s_waitcnt lgkmcnt(0)
	v_mfma_f32_16x16x32_bf16 v[92:95], v[206:209], v[174:177], v[92:95]
	v_mfma_f32_16x16x32_bf16 v[88:91], v[214:217], v[174:177], v[88:91]
	v_mfma_f32_16x16x32_bf16 v[84:87], v[206:209], v[182:185], v[84:87]
	v_mfma_f32_16x16x32_bf16 v[80:83], v[214:217], v[182:185], v[80:83]
	v_mfma_f32_16x16x32_bf16 v[76:79], v[206:209], v[190:193], v[76:79]
	v_mfma_f32_16x16x32_bf16 v[72:75], v[214:217], v[190:193], v[72:75]
	v_mfma_f32_16x16x32_bf16 v[68:71], v[206:209], v[198:201], v[68:71]
	v_mfma_f32_16x16x32_bf16 v[64:67], v[214:217], v[198:201], v[64:67]
	v_mfma_f32_16x16x32_bf16 v[174:177], v[210:213], v[178:181], v[92:95]
	v_mfma_f32_16x16x32_bf16 v[178:181], v[156:159], v[178:181], v[88:91]
	v_mfma_f32_16x16x32_bf16 v[182:185], v[210:213], v[186:189], v[84:87]
	v_mfma_f32_16x16x32_bf16 v[186:189], v[156:159], v[186:189], v[80:83]
	v_mfma_f32_16x16x32_bf16 v[190:193], v[210:213], v[194:197], v[76:79]
	v_mfma_f32_16x16x32_bf16 v[194:197], v[156:159], v[194:197], v[72:75]
	v_mfma_f32_16x16x32_bf16 v[198:201], v[210:213], v[202:205], v[68:71]
	v_mfma_f32_16x16x32_bf16 v[202:205], v[156:159], v[202:205], v[64:67]
	s_setprio 0
	s_barrier
	s_nop 0
	ds_read_b128 v[64:67], v152 offset:16384
	ds_read_b128 v[68:71], v152 offset:17408
	ds_read_b128 v[72:75], v151 offset:16384
	ds_read_b128 v[76:79], v151 offset:17408
	ds_read_b128 v[80:83], v150 offset:16384
	ds_read_b128 v[84:87], v150 offset:17408
	ds_read_b128 v[88:91], v149 offset:16384
	ds_read_b128 v[92:95], v149 offset:17408
	s_waitcnt vmcnt(4)
	s_barrier
	s_waitcnt lgkmcnt(0)
	s_setprio 1
	s_waitcnt lgkmcnt(0)
	v_mfma_f32_16x16x32_bf16 v[60:63], v[130:133], v[64:67], v[60:63]
	v_mfma_f32_16x16x32_bf16 v[56:59], v[166:169], v[64:67], v[56:59]
	v_mfma_f32_16x16x32_bf16 v[52:55], v[130:133], v[72:75], v[52:55]
	v_mfma_f32_16x16x32_bf16 v[48:51], v[166:169], v[72:75], v[48:51]
	v_mfma_f32_16x16x32_bf16 v[218:221], v[130:133], v[80:83], v[44:47]
	v_mfma_f32_16x16x32_bf16 v[222:225], v[166:169], v[80:83], v[40:43]
	v_mfma_f32_16x16x32_bf16 v[130:133], v[130:133], v[88:91], v[36:39]
	v_mfma_f32_16x16x32_bf16 v[166:169], v[166:169], v[88:91], v[32:35]
	v_mfma_f32_16x16x32_bf16 v[32:35], v[162:165], v[68:71], v[60:63]
	v_mfma_f32_16x16x32_bf16 v[36:39], v[170:173], v[68:71], v[56:59]
	v_mfma_f32_16x16x32_bf16 v[40:43], v[162:165], v[76:79], v[52:55]
	v_mfma_f32_16x16x32_bf16 v[44:47], v[170:173], v[76:79], v[48:51]
	v_mfma_f32_16x16x32_bf16 v[48:51], v[162:165], v[84:87], v[218:221]
	v_mfma_f32_16x16x32_bf16 v[52:55], v[170:173], v[84:87], v[222:225]
	v_mfma_f32_16x16x32_bf16 v[56:59], v[162:165], v[92:95], v[130:133]
	v_mfma_f32_16x16x32_bf16 v[60:63], v[170:173], v[92:95], v[166:169]
	s_setprio 0
	s_setprio 1
	v_mfma_f32_16x16x32_bf16 v[28:31], v[206:209], v[64:67], v[28:31]
	v_mfma_f32_16x16x32_bf16 v[24:27], v[214:217], v[64:67], v[24:27]
	v_mfma_f32_16x16x32_bf16 v[20:23], v[206:209], v[72:75], v[20:23]
	v_mfma_f32_16x16x32_bf16 v[64:67], v[214:217], v[72:75], v[16:19]
	v_mfma_f32_16x16x32_bf16 v[72:75], v[206:209], v[80:83], v[12:15]
	v_mfma_f32_16x16x32_bf16 v[8:11], v[214:217], v[80:83], v[8:11]
	v_mfma_f32_16x16x32_bf16 v[80:83], v[206:209], v[88:91], v[4:7]
	v_mfma_f32_16x16x32_bf16 v[0:3], v[214:217], v[88:91], v[0:3]
	v_mfma_f32_16x16x32_bf16 v[4:7], v[210:213], v[68:71], v[28:31]
	v_mfma_f32_16x16x32_bf16 v[12:15], v[156:159], v[68:71], v[24:27]
	v_mfma_f32_16x16x32_bf16 v[16:19], v[210:213], v[76:79], v[20:23]
	v_mfma_f32_16x16x32_bf16 v[20:23], v[156:159], v[76:79], v[64:67]
	v_mfma_f32_16x16x32_bf16 v[24:27], v[210:213], v[84:87], v[72:75]
	v_mfma_f32_16x16x32_bf16 v[28:31], v[156:159], v[84:87], v[8:11]
	v_mfma_f32_16x16x32_bf16 v[64:67], v[210:213], v[92:95], v[80:83]
	v_mfma_f32_16x16x32_bf16 v[68:71], v[156:159], v[92:95], v[0:3]
	s_setprio 0
	s_barrier
	ds_read_b128 v[8:11], v154
	ds_read_b128 v[0:3], v154 offset:1024
	ds_read_b128 v[76:79], v154 offset:2048
	ds_read_b128 v[72:75], v154 offset:3072
	ds_read_b128 v[130:133], v152 offset:32768
	ds_read_b128 v[154:157], v152 offset:33792
	ds_read_b128 v[158:161], v151 offset:32768
	ds_read_b128 v[162:165], v151 offset:33792
	ds_read_b128 v[166:169], v150 offset:32768
	ds_read_b128 v[170:173], v150 offset:33792
	ds_read_b128 v[206:209], v149 offset:32768
	ds_read_b128 v[210:213], v149 offset:33792
	s_waitcnt vmcnt(2)
	s_barrier
	s_waitcnt lgkmcnt(0)
	s_setprio 1
	s_waitcnt lgkmcnt(0)
	v_mfma_f32_16x16x32_bf16 v[80:83], v[8:11], v[130:133], v[124:127]
	v_mfma_f32_16x16x32_bf16 v[84:87], v[76:79], v[130:133], v[120:123]
	v_mfma_f32_16x16x32_bf16 v[88:91], v[8:11], v[158:161], v[116:119]
	v_mfma_f32_16x16x32_bf16 v[92:95], v[76:79], v[158:161], v[112:115]
	v_mfma_f32_16x16x32_bf16 v[108:111], v[8:11], v[166:169], v[108:111]
	v_mfma_f32_16x16x32_bf16 v[104:107], v[76:79], v[166:169], v[104:107]
	v_mfma_f32_16x16x32_bf16 v[100:103], v[8:11], v[206:209], v[100:103]
	v_mfma_f32_16x16x32_bf16 v[96:99], v[76:79], v[206:209], v[96:99]
	v_mfma_f32_16x16x32_bf16 v[112:115], v[0:3], v[154:157], v[80:83]
	v_mfma_f32_16x16x32_bf16 v[116:119], v[72:75], v[154:157], v[84:87]
	v_mfma_f32_16x16x32_bf16 v[120:123], v[0:3], v[162:165], v[88:91]
	v_mfma_f32_16x16x32_bf16 v[124:127], v[72:75], v[162:165], v[92:95]
	v_mfma_f32_16x16x32_bf16 v[108:111], v[0:3], v[170:173], v[108:111]
	v_mfma_f32_16x16x32_bf16 v[104:107], v[72:75], v[170:173], v[104:107]
	v_mfma_f32_16x16x32_bf16 v[100:103], v[0:3], v[210:213], v[100:103]
	v_mfma_f32_16x16x32_bf16 v[96:99], v[72:75], v[210:213], v[96:99]
	s_setprio 0
	s_barrier
	ds_read_b128 v[88:91], v153
	ds_read_b128 v[80:83], v153 offset:1024
	ds_read_b128 v[92:95], v153 offset:2048
	ds_read_b128 v[84:87], v153 offset:3072
	s_waitcnt vmcnt(0)
	s_barrier
	s_waitcnt lgkmcnt(0)
	s_setprio 1
	s_waitcnt lgkmcnt(0)
	v_mfma_f32_16x16x32_bf16 v[174:177], v[88:91], v[130:133], v[174:177]
	v_mfma_f32_16x16x32_bf16 v[130:133], v[92:95], v[130:133], v[178:181]
	v_mfma_f32_16x16x32_bf16 v[178:181], v[88:91], v[158:161], v[182:185]
	v_mfma_f32_16x16x32_bf16 v[158:161], v[92:95], v[158:161], v[186:189]
	v_mfma_f32_16x16x32_bf16 v[182:185], v[88:91], v[166:169], v[190:193]
	v_mfma_f32_16x16x32_bf16 v[166:169], v[92:95], v[166:169], v[194:197]
	v_mfma_f32_16x16x32_bf16 v[186:189], v[88:91], v[206:209], v[198:201]
	v_mfma_f32_16x16x32_bf16 v[190:193], v[92:95], v[206:209], v[202:205]
	v_mfma_f32_16x16x32_bf16 v[174:177], v[80:83], v[154:157], v[174:177]
	v_mfma_f32_16x16x32_bf16 v[130:133], v[84:87], v[154:157], v[130:133]
	v_mfma_f32_16x16x32_bf16 v[154:157], v[80:83], v[162:165], v[178:181]
	v_mfma_f32_16x16x32_bf16 v[158:161], v[84:87], v[162:165], v[158:161]
	v_mfma_f32_16x16x32_bf16 v[162:165], v[80:83], v[170:173], v[182:185]
	v_mfma_f32_16x16x32_bf16 v[166:169], v[84:87], v[170:173], v[166:169]
	v_mfma_f32_16x16x32_bf16 v[170:173], v[80:83], v[210:213], v[186:189]
	v_mfma_f32_16x16x32_bf16 v[178:181], v[84:87], v[210:213], v[190:193]
	s_setprio 0
	s_barrier
	v_mbcnt_lo_u32_b32 v128, -1, 0
	v_mbcnt_hi_u32_b32 v128, -1, v128
	v_cvt_pk_bf16_f32 v112, v112, v113
	v_cvt_pk_bf16_f32 v113, v114, v115
	v_cvt_pk_bf16_f32 v114, v116, v117
	v_cvt_pk_bf16_f32 v115, v118, v119
	s_lshl_b32 s89, s66, 9
	v_add_u32_e32 v153, s74, v128
	v_ashrrev_i32_e32 v182, 6, v153
	v_and_b32_e32 v183, 15, v128
	v_and_b32_e32 v184, 48, v128
	v_mul_lo_u32 v185, v182, s79
	v_bfe_u32 v186, v128, 3, 3
	v_lshlrev_b32_e32 v128, 4, v128
	v_add_u32_e32 v185, 0x20000, v185
	v_lshrrev_b32_e32 v153, 2, v153
	v_and_b32_e32 v128, 0x70, v128
	v_mul_u32_u24_e32 v183, 0x90, v183
	v_and_b32_e32 v153, 64, v153
	v_add3_u32 v183, v185, v183, v184
	v_or_b32_e32 v184, v185, v128
	v_or3_b32 v153, s96, v153, v186
	v_mad_u32_u24 v184, v186, s81, v184
	ds_write_b128 v183, v[112:115]
	v_cvt_pk_bf16_f32 v112, v174, v175
	v_cvt_pk_bf16_f32 v113, v176, v177
	v_cvt_pk_bf16_f32 v114, v130, v131
	v_cvt_pk_bf16_f32 v115, v132, v133
	ds_write_b128 v183, v[112:115] offset:64
	v_lshlrev_b32_e32 v182, 7, v182
	ds_read_b128 v[112:115], v184
	v_lshlrev_b32_e32 v116, 12, v153
	v_and_or_b32 v116, v182, s82, v116
	v_or3_b32 v128, v116, s89, v128
	ds_read_b128 v[116:119], v184 offset:1152
	v_lshl_add_u64 v[130:131], s[0:1], 0, v[128:129]
	s_mov_b32 s20, 0x8000
	s_waitcnt lgkmcnt(0)
	global_store_dwordx4 v128, v[112:115], s[0:1]
	v_cvt_pk_bf16_f32 v108, v108, v109
	v_cvt_pk_bf16_f32 v109, v110, v111
	v_cvt_pk_bf16_f32 v110, v104, v105
	v_cvt_pk_bf16_f32 v111, v106, v107
	v_cvt_pk_bf16_f32 v104, v162, v163
	s_nop 1
	v_add_co_u32_e32 v112, vcc, s20, v130
	v_cvt_pk_bf16_f32 v114, v124, v125
	v_cvt_pk_bf16_f32 v115, v126, v127
	v_cvt_pk_bf16_f32 v105, v164, v165
	v_cvt_pk_bf16_f32 v106, v166, v167
	s_nop 1
	v_addc_co_u32_e32 v113, vcc, 0, v131, vcc
	global_store_dwordx4 v[112:113], v[116:119], off
	v_cvt_pk_bf16_f32 v112, v120, v121
	v_cvt_pk_bf16_f32 v113, v122, v123
	ds_write_b128 v183, v[112:115]
	v_cvt_pk_bf16_f32 v112, v154, v155
	v_cvt_pk_bf16_f32 v113, v156, v157
	v_cvt_pk_bf16_f32 v114, v158, v159
	v_cvt_pk_bf16_f32 v115, v160, v161
	ds_write_b128 v183, v[112:115] offset:64
	ds_read_b128 v[112:115], v184
	ds_read_b128 v[116:119], v184 offset:1152
	v_add_co_u32_e32 v120, vcc, s76, v130
	ds_write_b128 v183, v[108:111]
	v_cvt_pk_bf16_f32 v107, v168, v169
	ds_write_b128 v183, v[104:107] offset:64
	v_addc_co_u32_e32 v121, vcc, 0, v131, vcc
	ds_read_b128 v[104:107], v184
	ds_read_b128 v[108:111], v184 offset:1152
	s_waitcnt lgkmcnt(0)
	global_store_dwordx4 v[120:121], v[112:115], off
	v_cvt_pk_bf16_f32 v100, v100, v101
	v_cvt_pk_bf16_f32 v101, v102, v103
	v_cvt_pk_bf16_f32 v102, v96, v97
	v_cvt_pk_bf16_f32 v103, v98, v99
	ds_write_b128 v183, v[100:103]
	s_nop 0
	v_add_co_u32_e32 v112, vcc, s77, v130
	v_cvt_pk_bf16_f32 v96, v170, v171
	v_cvt_pk_bf16_f32 v97, v172, v173
	v_cvt_pk_bf16_f32 v98, v178, v179
	v_cvt_pk_bf16_f32 v99, v180, v181
	s_nop 1
	v_addc_co_u32_e32 v113, vcc, 0, v131, vcc
	global_store_dwordx4 v[112:113], v[116:119], off
	v_add_co_u32_e32 v112, vcc, s80, v130
	ds_write_b128 v183, v[96:99] offset:64
	s_nop 0
	v_addc_co_u32_e32 v113, vcc, 0, v131, vcc
	ds_read_b128 v[96:99], v184
	ds_read_b128 v[100:103], v184 offset:1152
	global_store_dwordx4 v[112:113], v[104:107], off
	s_nop 1
	v_add_co_u32_e32 v104, vcc, s83, v130
	s_nop 1
	v_addc_co_u32_e32 v105, vcc, 0, v131, vcc
	global_store_dwordx4 v[104:105], v[108:111], off
	v_add_co_u32_e32 v104, vcc, s85, v130
	s_nop 1
	v_addc_co_u32_e32 v105, vcc, 0, v131, vcc
	s_waitcnt lgkmcnt(0)
	global_store_dwordx4 v[104:105], v[96:99], off
	s_nop 1
	v_add_co_u32_e32 v96, vcc, s87, v130
	s_nop 1
	v_addc_co_u32_e32 v97, vcc, 0, v131, vcc
	global_store_dwordx4 v[96:97], v[100:103], off
	ds_read_b128 v[96:99], v152 offset:49152
	ds_read_b128 v[100:103], v152 offset:50176
	ds_read_b128 v[104:107], v151 offset:49152
	ds_read_b128 v[108:111], v151 offset:50176
	ds_read_b128 v[112:115], v150 offset:49152
	ds_read_b128 v[116:119], v150 offset:50176
	ds_read_b128 v[120:123], v149 offset:49152
	ds_read_b128 v[124:127], v149 offset:50176
	s_barrier
	s_waitcnt lgkmcnt(0)
	s_setprio 1
	s_waitcnt lgkmcnt(0)
	v_mfma_f32_16x16x32_bf16 v[32:35], v[8:11], v[96:99], v[32:35]
	v_mfma_f32_16x16x32_bf16 v[36:39], v[76:79], v[96:99], v[36:39]
	v_mfma_f32_16x16x32_bf16 v[40:43], v[8:11], v[104:107], v[40:43]
	v_mfma_f32_16x16x32_bf16 v[130:133], v[76:79], v[104:107], v[44:47]
	v_mfma_f32_16x16x32_bf16 v[150:153], v[8:11], v[112:115], v[48:51]
	v_mfma_f32_16x16x32_bf16 v[52:55], v[76:79], v[112:115], v[52:55]
	v_mfma_f32_16x16x32_bf16 v[8:11], v[8:11], v[120:123], v[56:59]
	v_mfma_f32_16x16x32_bf16 v[60:63], v[76:79], v[120:123], v[60:63]
	v_mfma_f32_16x16x32_bf16 v[56:59], v[0:3], v[100:103], v[32:35]
	v_mfma_f32_16x16x32_bf16 v[48:51], v[72:75], v[100:103], v[36:39]
	v_mfma_f32_16x16x32_bf16 v[44:47], v[0:3], v[108:111], v[40:43]
	v_mfma_f32_16x16x32_bf16 v[40:43], v[72:75], v[108:111], v[130:133]
	v_mfma_f32_16x16x32_bf16 v[36:39], v[0:3], v[116:119], v[150:153]
	v_mfma_f32_16x16x32_bf16 v[32:35], v[72:75], v[116:119], v[52:55]
	v_mfma_f32_16x16x32_bf16 v[8:11], v[0:3], v[124:127], v[8:11]
	v_mfma_f32_16x16x32_bf16 v[0:3], v[72:75], v[124:127], v[60:63]
	s_setprio 0
	s_setprio 1
	v_mfma_f32_16x16x32_bf16 v[4:7], v[88:91], v[96:99], v[4:7]
	v_mfma_f32_16x16x32_bf16 v[12:15], v[92:95], v[96:99], v[12:15]
	v_mfma_f32_16x16x32_bf16 v[16:19], v[88:91], v[104:107], v[16:19]
	v_mfma_f32_16x16x32_bf16 v[20:23], v[92:95], v[104:107], v[20:23]
	v_mfma_f32_16x16x32_bf16 v[72:75], v[88:91], v[112:115], v[24:27]
	v_mfma_f32_16x16x32_bf16 v[76:79], v[92:95], v[112:115], v[28:31]
	v_mfma_f32_16x16x32_bf16 v[64:67], v[88:91], v[120:123], v[64:67]
	v_mfma_f32_16x16x32_bf16 v[68:71], v[92:95], v[120:123], v[68:71]
	v_mfma_f32_16x16x32_bf16 v[60:63], v[80:83], v[100:103], v[4:7]
	v_mfma_f32_16x16x32_bf16 v[52:55], v[84:87], v[100:103], v[12:15]
	v_mfma_f32_16x16x32_bf16 v[28:31], v[80:83], v[108:111], v[16:19]
	v_mfma_f32_16x16x32_bf16 v[24:27], v[84:87], v[108:111], v[20:23]
	v_mfma_f32_16x16x32_bf16 v[20:23], v[80:83], v[116:119], v[72:75]
	v_mfma_f32_16x16x32_bf16 v[16:19], v[84:87], v[116:119], v[76:79]
	v_mfma_f32_16x16x32_bf16 v[12:15], v[80:83], v[124:127], v[64:67]
	v_mfma_f32_16x16x32_bf16 v[4:7], v[84:87], v[124:127], v[68:71]
	s_setprio 0
	v_cmp_gt_u32_e32 vcc, s88, v135
	s_barrier
	s_and_saveexec_b64 s[66:67], vcc
	s_cbranch_execz .LBB0_564
	s_barrier
